# GEMM MFMA blocks: s_setprio 1 raised before the barrier and the redundant lgkmcnt(0) after it removed, so the first MFMA issues right at release (on top of the 2-DMA move)
# speedup vs baseline: 1.0145x; 1.0145x over previous
; #define PG8_STAGE(bufoff, gbase, voff) do { _Pragma("unroll") for (int _i = 0; _i < 2; ++_i) \
;         __builtin_amdgcn_global_load_lds((const unsigned*)((const char*)(gbase) + (voff)[_i]), (PG8_LAS unsigned*)(lds + (bufoff) + ldsw + _i * 8192), 16, 0, 0); } while (0)
; #define PG8_LDA(dst, b, h) do { _Pragma("unroll") for (int m = 0; m < 4; ++m) _Pragma("unroll") for (int k = 0; k < 2; ++k) dst[m][k] = *(const PG8_LAS bf16x8*)(lds + PG8_SA(b, h) + aoff + m * 2048 + k * 1024); } while (0)
; #define PG8_LDB(dst, b, h) do { _Pragma("unroll") for (int n = 0; n < 2; ++n) _Pragma("unroll") for (int k = 0; k < 2; ++k) dst[n][k] = *(const PG8_LAS bf16x8*)(lds + PG8_SB(b, h) + boff + n * 2048 + k * 1024); } while (0)
; #define PG8_MMA(ai, bj, At, Bt) do { __builtin_amdgcn_s_setprio(1); _Pragma("unroll") for (int m = 0; m < 4; ++m) _Pragma("unroll") for (int n = 0; n < 2; ++n) _Pragma("unroll") for (int k = 0; k < 2; ++k) \
;         acc[ai][bj][m][n] = __builtin_amdgcn_mfma_f32_16x16x32_bf16(Bt[n][k], At[m][k], acc[ai][bj][m][n], 0, 0, 0); __builtin_amdgcn_s_setprio(0); } while (0)
; #define PG8_WAIT_V(n) asm volatile("s_waitcnt vmcnt(" #n ")" ::: "memory")
; #define PG8_BAR __builtin_amdgcn_s_barrier()
; template <class Epi, class Sched, bool ALIGN_EPI = false, bool SP2 = false>
; __device__ __forceinline__ void gemm_phase(PG8_LAS unsigned char* lds, const Gemm g, const Sched& S, const Epi& E) {
;     ...
;         for (int t = 0; t < nt; t += 2) {
;             const bool last = (t == nt - 2);
;             const char* a1 = cA + (size_t)(t + 1) * kstep;
;             const char* a2 = last ? nA : cA + (size_t)(t + 2) * kstep; const char* b2 = last ? nB : cB + (size_t)(t + 2) * kstep;
;             const char* a3 = a2 + kstep; const char* b3 = b2 + kstep;
;             if (last && has_next) S.a_ready(nxt);
;             if constexpr (SP2) {
;             PG8_LDB(B0, 0, 0); PG8_LDB(B1, 0, 1); PG8_SCHED; PG8_LDA(At, 0, 0); PG8_STAGE(PG8_SA(1, 1), a1 + hstep, voffA);
;             PG8_WAIT_V(8); PG8_WAIT_L(0); PG8_BAR; PG8_MMA(0, 0, At, B0); PG8_MMA(0, 1, At, B1); PG8_BAR; PG8_SCHED;
;             PG8_LDA(At, 0, 1); PG8_STAGE(PG8_SB(0, 0), b2, voffB); PG8_STAGE(PG8_SB(0, 1), b2 + hstep, voffB); PG8_STAGE(PG8_SA(0, 0), a2, voffA);
;             PG8_WAIT_V(8); PG8_WAIT_L(0); PG8_BAR; PG8_MMA(1, 0, At, B0); PG8_MMA(1, 1, At, B1); PG8_BAR; PG8_SCHED;
.LBB0_192:
	ds_read_b128 v[152:155], v149
	ds_read_b128 v[156:159], v149 offset:1024
	ds_read_b128 v[160:163], v149 offset:2048
	ds_read_b128 v[164:167], v149 offset:3072
	ds_read_b128 v[168:171], v150
	ds_read_b128 v[172:175], v150 offset:1024
	ds_read_b128 v[176:179], v150 offset:2048
	ds_read_b128 v[182:185], v150 offset:3072
	s_add_u32 s44, s42, 0xfffc0080
	s_addc_u32 s45, s43, -1
	s_cmp_eq_u32 s92, 12
	s_cselect_b32 s47, s23, s45
	s_cselect_b32 s46, s88, s44
	s_cselect_b32 s45, s21, s91
	s_cselect_b32 s44, s89, s90
	v_lshl_add_u64 v[144:145], s[42:43], 0, v[136:137]
	s_add_i32 m0, s41, 0xc000
	ds_read_b128 v[186:189], v151
	ds_read_b128 v[192:195], v151 offset:1024
	ds_read_b128 v[196:199], v151 offset:2048
	ds_read_b128 v[200:203], v151 offset:3072
	ds_read_b128 v[204:207], v151 offset:4096
	ds_read_b128 v[208:211], v151 offset:5120
	ds_read_b128 v[212:215], v151 offset:6144
	ds_read_b128 v[216:219], v151 offset:7168
	global_load_lds_dwordx4 v[144:145], off
	v_lshl_add_u64 v[144:145], s[42:43], 0, v[138:139]
	s_add_i32 m0, s41, 0xe000
	s_nop 0
	global_load_lds_dwordx4 v[144:145], off
	s_waitcnt vmcnt(8)
	s_waitcnt lgkmcnt(0)
	s_setprio 1
	s_barrier
	v_mfma_f32_16x16x32_bf16 v[124:127], v[152:155], v[186:189], v[124:127]
	v_mfma_f32_16x16x32_bf16 v[116:119], v[160:163], v[186:189], v[116:119]
	v_mfma_f32_16x16x32_bf16 v[108:111], v[152:155], v[196:199], v[108:111]
	v_mfma_f32_16x16x32_bf16 v[100:103], v[160:163], v[196:199], v[100:103]
	v_mfma_f32_16x16x32_bf16 v[92:95], v[152:155], v[204:207], v[92:95]
	v_mfma_f32_16x16x32_bf16 v[84:87], v[160:163], v[204:207], v[84:87]
	v_mfma_f32_16x16x32_bf16 v[76:79], v[152:155], v[212:215], v[76:79]
	v_mfma_f32_16x16x32_bf16 v[68:71], v[160:163], v[212:215], v[68:71]
	v_mfma_f32_16x16x32_bf16 v[124:127], v[156:159], v[192:195], v[124:127]
	v_mfma_f32_16x16x32_bf16 v[116:119], v[164:167], v[192:195], v[116:119]
	v_mfma_f32_16x16x32_bf16 v[108:111], v[156:159], v[200:203], v[108:111]
	v_mfma_f32_16x16x32_bf16 v[100:103], v[164:167], v[200:203], v[100:103]
	v_mfma_f32_16x16x32_bf16 v[92:95], v[156:159], v[208:211], v[92:95]
	v_mfma_f32_16x16x32_bf16 v[84:87], v[164:167], v[208:211], v[84:87]
	v_mfma_f32_16x16x32_bf16 v[76:79], v[156:159], v[216:219], v[76:79]
	v_mfma_f32_16x16x32_bf16 v[68:71], v[164:167], v[216:219], v[68:71]
	s_setprio 0
	s_setprio 1
	v_mfma_f32_16x16x32_bf16 v[120:123], v[168:171], v[186:189], v[120:123]
	v_mfma_f32_16x16x32_bf16 v[112:115], v[176:179], v[186:189], v[112:115]
	v_mfma_f32_16x16x32_bf16 v[104:107], v[168:171], v[196:199], v[104:107]
	v_mfma_f32_16x16x32_bf16 v[96:99], v[176:179], v[196:199], v[96:99]
	v_mfma_f32_16x16x32_bf16 v[88:91], v[168:171], v[204:207], v[88:91]
	v_mfma_f32_16x16x32_bf16 v[80:83], v[176:179], v[204:207], v[80:83]
	v_mfma_f32_16x16x32_bf16 v[72:75], v[168:171], v[212:215], v[72:75]
	v_mfma_f32_16x16x32_bf16 v[64:67], v[176:179], v[212:215], v[64:67]
	v_mfma_f32_16x16x32_bf16 v[120:123], v[172:175], v[192:195], v[120:123]
	v_mfma_f32_16x16x32_bf16 v[112:115], v[182:185], v[192:195], v[112:115]
	v_mfma_f32_16x16x32_bf16 v[104:107], v[172:175], v[200:203], v[104:107]
	v_mfma_f32_16x16x32_bf16 v[96:99], v[182:185], v[200:203], v[96:99]
	v_mfma_f32_16x16x32_bf16 v[88:91], v[172:175], v[208:211], v[88:91]
	v_mfma_f32_16x16x32_bf16 v[80:83], v[182:185], v[208:211], v[80:83]
	v_mfma_f32_16x16x32_bf16 v[72:75], v[172:175], v[216:219], v[72:75]
	v_mfma_f32_16x16x32_bf16 v[64:67], v[182:185], v[216:219], v[64:67]
	s_setprio 0
	s_barrier
	s_add_i32 s93, s84, s48
	v_lshl_add_u64 v[144:145], s[44:45], 0, v[132:133]
	s_mov_b32 m0, s93
	ds_read_b128 v[186:189], v151 offset:16384
	ds_read_b128 v[192:195], v151 offset:17408
	ds_read_b128 v[196:199], v151 offset:18432
	ds_read_b128 v[200:203], v151 offset:19456
	ds_read_b128 v[204:207], v151 offset:20480
	ds_read_b128 v[208:211], v151 offset:21504
	ds_read_b128 v[212:215], v151 offset:22528
	ds_read_b128 v[216:219], v151 offset:23552
	global_load_lds_dwordx4 v[144:145], off
	s_add_i32 m0, s93, 0x2000
	s_add_u32 s94, s44, 0x40000
	v_lshl_add_u64 v[220:221], s[44:45], 0, v[128:129]
	s_addc_u32 s95, s45, 0
	s_add_i32 s93, s85, s48
	global_load_lds_dwordx4 v[220:221], off
	v_lshl_add_u64 v[222:223], s[94:95], 0, v[132:133]
	s_mov_b32 m0, s93
	v_lshl_add_u64 v[224:225], s[46:47], 0, v[130:131]
	global_load_lds_dwordx4 v[222:223], off
	v_lshl_add_u64 v[222:223], s[94:95], 0, v[128:129]
	s_add_i32 m0, s93, 0x2000
	s_nop 0
	global_load_lds_dwordx4 v[222:223], off
	s_waitcnt vmcnt(6)
	s_waitcnt lgkmcnt(0)
	s_setprio 1
	s_barrier
; #define PG8_STAGE(bufoff, gbase, voff) do { _Pragma("unroll") for (int _i = 0; _i < 2; ++_i) \
;         __builtin_amdgcn_global_load_lds((const unsigned*)((const char*)(gbase) + (voff)[_i]), (PG8_LAS unsigned*)(lds + (bufoff) + ldsw + _i * 8192), 16, 0, 0); } while (0)
; #define PG8_LDA(dst, b, h) do { _Pragma("unroll") for (int m = 0; m < 4; ++m) _Pragma("unroll") for (int k = 0; k < 2; ++k) dst[m][k] = *(const PG8_LAS bf16x8*)(lds + PG8_SA(b, h) + aoff + m * 2048 + k * 1024); } while (0)
; #define PG8_LDB(dst, b, h) do { _Pragma("unroll") for (int n = 0; n < 2; ++n) _Pragma("unroll") for (int k = 0; k < 2; ++k) dst[n][k] = *(const PG8_LAS bf16x8*)(lds + PG8_SB(b, h) + boff + n * 2048 + k * 1024); } while (0)
; #define PG8_MMA(ai, bj, At, Bt) do { __builtin_amdgcn_s_setprio(1); _Pragma("unroll") for (int m = 0; m < 4; ++m) _Pragma("unroll") for (int n = 0; n < 2; ++n) _Pragma("unroll") for (int k = 0; k < 2; ++k) \
;         acc[ai][bj][m][n] = __builtin_amdgcn_mfma_f32_16x16x32_bf16(Bt[n][k], At[m][k], acc[ai][bj][m][n], 0, 0, 0); __builtin_amdgcn_s_setprio(0); } while (0)
; #define PG8_WAIT_V(n) asm volatile("s_waitcnt vmcnt(" #n ")" ::: "memory")
; #define PG8_WAIT_L(n) asm volatile("s_waitcnt lgkmcnt(" #n ")" ::: "memory")
; #define PG8_BAR __builtin_amdgcn_s_barrier()
; #define PG8_SCHED __builtin_amdgcn_sched_barrier(0)
; template <class Epi, class Sched, bool ALIGN_EPI = false, bool SP2 = false>
; __device__ __forceinline__ void gemm_phase(PG8_LAS unsigned char* lds, const Gemm g, const Sched& S, const Epi& E) {
;     ...
;             PG8_WAIT_V(8); PG8_WAIT_L(0); PG8_BAR; PG8_MMA(0, 0, At, B0); PG8_MMA(0, 1, At, B1); PG8_BAR; PG8_SCHED;
;             PG8_LDA(At, 0, 1); PG8_STAGE(PG8_SB(0, 0), b2, voffB); PG8_STAGE(PG8_SB(0, 1), b2 + hstep, voffB); PG8_STAGE(PG8_SA(0, 0), a2, voffA);
;             PG8_WAIT_V(8); PG8_WAIT_L(0); PG8_BAR; PG8_MMA(1, 0, At, B0); PG8_MMA(1, 1, At, B1); PG8_BAR; PG8_SCHED;
;             PG8_LDB(B0, 1, 0); PG8_LDB(B1, 1, 1); PG8_SCHED; PG8_LDA(At, 1, 0); PG8_STAGE(PG8_SA(0, 1), a2 + hstep, voffA);
;             PG8_WAIT_V(8); PG8_WAIT_L(0); PG8_BAR; PG8_MMA(0, 0, At, B0); PG8_MMA(0, 1, At, B1); PG8_BAR; PG8_SCHED;
	v_mfma_f32_16x16x32_bf16 v[60:63], v[152:155], v[186:189], v[60:63]
	v_mfma_f32_16x16x32_bf16 v[52:55], v[160:163], v[186:189], v[52:55]
	v_mfma_f32_16x16x32_bf16 v[44:47], v[152:155], v[196:199], v[44:47]
	v_mfma_f32_16x16x32_bf16 v[36:39], v[160:163], v[196:199], v[36:39]
	v_mfma_f32_16x16x32_bf16 v[28:31], v[152:155], v[204:207], v[28:31]
	v_mfma_f32_16x16x32_bf16 v[20:23], v[160:163], v[204:207], v[20:23]
	v_lshl_add_u64 v[222:223], s[46:47], 0, v[134:135]
	s_mov_b32 m0, s41
	s_nop 0
	global_load_lds_dwordx4 v[222:223], off
	v_mfma_f32_16x16x32_bf16 v[12:15], v[152:155], v[212:215], v[12:15]
	v_mfma_f32_16x16x32_bf16 v[4:7], v[160:163], v[212:215], v[4:7]
	v_mfma_f32_16x16x32_bf16 v[60:63], v[156:159], v[192:195], v[60:63]
	v_mfma_f32_16x16x32_bf16 v[52:55], v[164:167], v[192:195], v[52:55]
	v_mfma_f32_16x16x32_bf16 v[44:47], v[156:159], v[200:203], v[44:47]
	v_mfma_f32_16x16x32_bf16 v[36:39], v[164:167], v[200:203], v[36:39]
	v_mfma_f32_16x16x32_bf16 v[28:31], v[156:159], v[208:211], v[28:31]
	v_mfma_f32_16x16x32_bf16 v[20:23], v[164:167], v[208:211], v[20:23]
	v_mfma_f32_16x16x32_bf16 v[12:15], v[156:159], v[216:219], v[12:15]
	v_mfma_f32_16x16x32_bf16 v[4:7], v[164:167], v[216:219], v[4:7]
	s_setprio 0
	s_setprio 1
	v_mfma_f32_16x16x32_bf16 v[56:59], v[168:171], v[186:189], v[56:59]
	v_mfma_f32_16x16x32_bf16 v[48:51], v[176:179], v[186:189], v[48:51]
	v_mfma_f32_16x16x32_bf16 v[40:43], v[168:171], v[196:199], v[40:43]
	v_mfma_f32_16x16x32_bf16 v[32:35], v[176:179], v[196:199], v[32:35]
	v_mfma_f32_16x16x32_bf16 v[24:27], v[168:171], v[204:207], v[24:27]
	v_mfma_f32_16x16x32_bf16 v[16:19], v[176:179], v[204:207], v[16:19]
	s_mov_b32 m0, s61
	s_nop 0
	global_load_lds_dwordx4 v[224:225], off
	v_mfma_f32_16x16x32_bf16 v[8:11], v[168:171], v[212:215], v[8:11]
	v_mfma_f32_16x16x32_bf16 v[0:3], v[176:179], v[212:215], v[0:3]
	v_mfma_f32_16x16x32_bf16 v[56:59], v[172:175], v[192:195], v[56:59]
	v_mfma_f32_16x16x32_bf16 v[48:51], v[182:185], v[192:195], v[48:51]
	v_mfma_f32_16x16x32_bf16 v[40:43], v[172:175], v[200:203], v[40:43]
	v_mfma_f32_16x16x32_bf16 v[32:35], v[182:185], v[200:203], v[32:35]
	v_mfma_f32_16x16x32_bf16 v[24:27], v[172:175], v[208:211], v[24:27]
	v_mfma_f32_16x16x32_bf16 v[16:19], v[182:185], v[208:211], v[16:19]
	v_mfma_f32_16x16x32_bf16 v[8:11], v[172:175], v[216:219], v[8:11]
	v_mfma_f32_16x16x32_bf16 v[0:3], v[182:185], v[216:219], v[0:3]
	s_setprio 0
	s_barrier
	s_add_i32 s93, 0, 0x18000
	s_add_i32 s94, 0, 0x1c000
	v_add_u32_e32 v164, s93, v147
	v_add_u32_e32 v181, s94, v147
	ds_read_b128 v[152:155], v164
	ds_read_b128 v[156:159], v164 offset:1024
	ds_read_b128 v[160:163], v164 offset:2048
	ds_read_b128 v[164:167], v164 offset:3072
	ds_read_b128 v[168:171], v181
	ds_read_b128 v[172:175], v181 offset:1024
	ds_read_b128 v[176:179], v181 offset:2048
	ds_read_b128 v[182:185], v181 offset:3072
	s_add_u32 s46, s46, 0x40000
	s_addc_u32 s47, s47, 0
	s_mov_b32 m0, s78
	v_lshl_add_u64 v[226:227], s[46:47], 0, v[134:135]
	ds_read_b128 v[186:189], v151 offset:32768
	ds_read_b128 v[192:195], v151 offset:33792
	ds_read_b128 v[196:199], v151 offset:34816
	ds_read_b128 v[200:203], v151 offset:35840
	ds_read_b128 v[204:207], v151 offset:36864
	ds_read_b128 v[208:211], v151 offset:37888
	ds_read_b128 v[212:215], v151 offset:38912
	ds_read_b128 v[216:219], v151 offset:39936
	global_load_lds_dwordx4 v[226:227], off
	v_lshl_add_u64 v[226:227], s[46:47], 0, v[130:131]
	s_mov_b32 m0, s79
	s_nop 0
	global_load_lds_dwordx4 v[226:227], off
	s_waitcnt vmcnt(8)
	s_waitcnt lgkmcnt(0)
	s_setprio 1
	s_barrier
	v_mfma_f32_16x16x32_bf16 v[124:127], v[152:155], v[186:189], v[124:127]
	v_mfma_f32_16x16x32_bf16 v[116:119], v[160:163], v[186:189], v[116:119]
	v_mfma_f32_16x16x32_bf16 v[108:111], v[152:155], v[196:199], v[108:111]
	v_mfma_f32_16x16x32_bf16 v[100:103], v[160:163], v[196:199], v[100:103]
	v_mfma_f32_16x16x32_bf16 v[92:95], v[152:155], v[204:207], v[92:95]
	v_mfma_f32_16x16x32_bf16 v[84:87], v[160:163], v[204:207], v[84:87]
	v_mfma_f32_16x16x32_bf16 v[76:79], v[152:155], v[212:215], v[76:79]
	v_mfma_f32_16x16x32_bf16 v[68:71], v[160:163], v[212:215], v[68:71]
	v_mfma_f32_16x16x32_bf16 v[124:127], v[156:159], v[192:195], v[124:127]
	v_mfma_f32_16x16x32_bf16 v[116:119], v[164:167], v[192:195], v[116:119]
	v_mfma_f32_16x16x32_bf16 v[108:111], v[156:159], v[200:203], v[108:111]
	v_mfma_f32_16x16x32_bf16 v[100:103], v[164:167], v[200:203], v[100:103]
	v_mfma_f32_16x16x32_bf16 v[92:95], v[156:159], v[208:211], v[92:95]
	v_mfma_f32_16x16x32_bf16 v[84:87], v[164:167], v[208:211], v[84:87]
	v_mfma_f32_16x16x32_bf16 v[76:79], v[156:159], v[216:219], v[76:79]
	v_mfma_f32_16x16x32_bf16 v[68:71], v[164:167], v[216:219], v[68:71]
	s_setprio 0
	s_setprio 1
	v_mfma_f32_16x16x32_bf16 v[120:123], v[168:171], v[186:189], v[120:123]
	v_mfma_f32_16x16x32_bf16 v[112:115], v[176:179], v[186:189], v[112:115]
	v_mfma_f32_16x16x32_bf16 v[104:107], v[168:171], v[196:199], v[104:107]
	v_mfma_f32_16x16x32_bf16 v[96:99], v[176:179], v[196:199], v[96:99]
	v_mfma_f32_16x16x32_bf16 v[88:91], v[168:171], v[204:207], v[88:91]
	v_mfma_f32_16x16x32_bf16 v[80:83], v[176:179], v[204:207], v[80:83]
	v_mfma_f32_16x16x32_bf16 v[72:75], v[168:171], v[212:215], v[72:75]
	v_mfma_f32_16x16x32_bf16 v[64:67], v[176:179], v[212:215], v[64:67]
	v_mfma_f32_16x16x32_bf16 v[120:123], v[172:175], v[192:195], v[120:123]
	v_mfma_f32_16x16x32_bf16 v[112:115], v[182:185], v[192:195], v[112:115]
	v_mfma_f32_16x16x32_bf16 v[104:107], v[172:175], v[200:203], v[104:107]
	v_mfma_f32_16x16x32_bf16 v[96:99], v[182:185], v[200:203], v[96:99]
	v_mfma_f32_16x16x32_bf16 v[88:91], v[172:175], v[208:211], v[88:91]
	v_mfma_f32_16x16x32_bf16 v[80:83], v[182:185], v[208:211], v[80:83]
	v_mfma_f32_16x16x32_bf16 v[72:75], v[172:175], v[216:219], v[72:75]
	v_mfma_f32_16x16x32_bf16 v[64:67], v[182:185], v[216:219], v[64:67]
	s_setprio 0
	s_barrier
; #define PG8_STAGE(bufoff, gbase, voff) do { _Pragma("unroll") for (int _i = 0; _i < 2; ++_i) \
;         __builtin_amdgcn_global_load_lds((const unsigned*)((const char*)(gbase) + (voff)[_i]), (PG8_LAS unsigned*)(lds + (bufoff) + ldsw + _i * 8192), 16, 0, 0); } while (0)
; #define PG8_LDA(dst, b, h) do { _Pragma("unroll") for (int m = 0; m < 4; ++m) _Pragma("unroll") for (int k = 0; k < 2; ++k) dst[m][k] = *(const PG8_LAS bf16x8*)(lds + PG8_SA(b, h) + aoff + m * 2048 + k * 1024); } while (0)
; #define PG8_MMA(ai, bj, At, Bt) do { __builtin_amdgcn_s_setprio(1); _Pragma("unroll") for (int m = 0; m < 4; ++m) _Pragma("unroll") for (int n = 0; n < 2; ++n) _Pragma("unroll") for (int k = 0; k < 2; ++k) \
;         acc[ai][bj][m][n] = __builtin_amdgcn_mfma_f32_16x16x32_bf16(Bt[n][k], At[m][k], acc[ai][bj][m][n], 0, 0, 0); __builtin_amdgcn_s_setprio(0); } while (0)
; #define PG8_WAIT_V(n) asm volatile("s_waitcnt vmcnt(" #n ")" ::: "memory")
; #define PG8_WAIT_L(n) asm volatile("s_waitcnt lgkmcnt(" #n ")" ::: "memory")
; #define PG8_BAR __builtin_amdgcn_s_barrier()
; #define PG8_SCHED __builtin_amdgcn_sched_barrier(0)
; template <class Epi, class Sched, bool ALIGN_EPI = false, bool SP2 = false>
; __device__ __forceinline__ void gemm_phase(PG8_LAS unsigned char* lds, const Gemm g, const Sched& S, const Epi& E) {
;     ...
;             PG8_WAIT_V(8); PG8_WAIT_L(0); PG8_BAR; PG8_MMA(0, 0, At, B0); PG8_MMA(0, 1, At, B1); PG8_BAR; PG8_SCHED;
;             PG8_LDA(At, 1, 1); PG8_STAGE(PG8_SB(1, 0), b3, voffB); PG8_STAGE(PG8_SB(1, 1), b3 + hstep, voffB); PG8_STAGE(PG8_SA(1, 0), a3, voffA);
;             PG8_WAIT_V(8); PG8_WAIT_L(0); PG8_BAR; PG8_MMA(1, 0, At, B0); PG8_MMA(1, 1, At, B1); PG8_BAR; PG8_SCHED;
;     ...
;         }
;         if constexpr (ALIGN_EPI) { if (wr == 0) PG8_BAR; }
	s_add_i32 s46, s93, s48
	v_lshl_add_u64 v[144:145], v[144:145], 0, s[6:7]
	s_mov_b32 m0, s46
	ds_read_b128 v[186:189], v151 offset:49152
	ds_read_b128 v[192:195], v151 offset:50176
	ds_read_b128 v[196:199], v151 offset:51200
	ds_read_b128 v[200:203], v151 offset:52224
	ds_read_b128 v[204:207], v151 offset:53248
	ds_read_b128 v[208:211], v151 offset:54272
	ds_read_b128 v[212:215], v151 offset:55296
	ds_read_b128 v[216:219], v151 offset:56320
	global_load_lds_dwordx4 v[144:145], off
	s_add_i32 m0, s46, 0x2000
	s_add_u32 s44, s44, 0x40080
	v_lshl_add_u64 v[144:145], v[220:221], 0, s[6:7]
	s_addc_u32 s45, s45, 0
	s_add_i32 s46, s94, s48
	global_load_lds_dwordx4 v[144:145], off
	v_lshl_add_u64 v[144:145], s[44:45], 0, v[132:133]
	s_mov_b32 m0, s46
	s_nop 0
	global_load_lds_dwordx4 v[144:145], off
	v_lshl_add_u64 v[144:145], s[44:45], 0, v[128:129]
	s_add_i32 m0, s46, 0x2000
	s_nop 0
	global_load_lds_dwordx4 v[144:145], off
	s_waitcnt vmcnt(6)
	s_waitcnt lgkmcnt(0)
	s_setprio 1
	s_barrier
	v_mfma_f32_16x16x32_bf16 v[60:63], v[152:155], v[186:189], v[60:63]
	v_mfma_f32_16x16x32_bf16 v[52:55], v[160:163], v[186:189], v[52:55]
	v_mfma_f32_16x16x32_bf16 v[44:47], v[152:155], v[196:199], v[44:47]
	v_mfma_f32_16x16x32_bf16 v[36:39], v[160:163], v[196:199], v[36:39]
	v_mfma_f32_16x16x32_bf16 v[28:31], v[152:155], v[204:207], v[28:31]
	v_mfma_f32_16x16x32_bf16 v[20:23], v[160:163], v[204:207], v[20:23]
	v_lshl_add_u64 v[144:145], v[222:223], 0, s[6:7]
	s_mov_b32 m0, s81
	s_nop 0
	global_load_lds_dwordx4 v[144:145], off
	v_mfma_f32_16x16x32_bf16 v[12:15], v[152:155], v[212:215], v[12:15]
	v_mfma_f32_16x16x32_bf16 v[4:7], v[160:163], v[212:215], v[4:7]
	v_mfma_f32_16x16x32_bf16 v[60:63], v[156:159], v[192:195], v[60:63]
	v_mfma_f32_16x16x32_bf16 v[52:55], v[164:167], v[192:195], v[52:55]
	v_mfma_f32_16x16x32_bf16 v[44:47], v[156:159], v[200:203], v[44:47]
	v_mfma_f32_16x16x32_bf16 v[36:39], v[164:167], v[200:203], v[36:39]
	v_mfma_f32_16x16x32_bf16 v[28:31], v[156:159], v[208:211], v[28:31]
	v_mfma_f32_16x16x32_bf16 v[20:23], v[164:167], v[208:211], v[20:23]
	v_mfma_f32_16x16x32_bf16 v[12:15], v[156:159], v[216:219], v[12:15]
	v_mfma_f32_16x16x32_bf16 v[4:7], v[164:167], v[216:219], v[4:7]
	s_setprio 0
	s_setprio 1
	v_mfma_f32_16x16x32_bf16 v[56:59], v[168:171], v[186:189], v[56:59]
	v_mfma_f32_16x16x32_bf16 v[48:51], v[176:179], v[186:189], v[48:51]
	v_mfma_f32_16x16x32_bf16 v[40:43], v[168:171], v[196:199], v[40:43]
	v_mfma_f32_16x16x32_bf16 v[32:35], v[176:179], v[196:199], v[32:35]
	v_mfma_f32_16x16x32_bf16 v[24:27], v[168:171], v[204:207], v[24:27]
	v_mfma_f32_16x16x32_bf16 v[16:19], v[176:179], v[204:207], v[16:19]
	v_lshl_add_u64 v[144:145], v[224:225], 0, s[6:7]
	s_mov_b32 m0, s82
	s_nop 0
	global_load_lds_dwordx4 v[144:145], off
	v_mfma_f32_16x16x32_bf16 v[8:11], v[168:171], v[212:215], v[8:11]
	v_mfma_f32_16x16x32_bf16 v[0:3], v[176:179], v[212:215], v[0:3]
	v_mfma_f32_16x16x32_bf16 v[56:59], v[172:175], v[192:195], v[56:59]
	v_mfma_f32_16x16x32_bf16 v[48:51], v[182:185], v[192:195], v[48:51]
	v_mfma_f32_16x16x32_bf16 v[40:43], v[172:175], v[200:203], v[40:43]
	v_mfma_f32_16x16x32_bf16 v[32:35], v[182:185], v[200:203], v[32:35]
	v_mfma_f32_16x16x32_bf16 v[24:27], v[172:175], v[208:211], v[24:27]
	v_mfma_f32_16x16x32_bf16 v[16:19], v[182:185], v[208:211], v[16:19]
	v_mfma_f32_16x16x32_bf16 v[8:11], v[172:175], v[216:219], v[8:11]
	v_mfma_f32_16x16x32_bf16 v[0:3], v[182:185], v[216:219], v[0:3]
	s_setprio 0
	s_barrier
	s_add_i32 s92, s92, 2
	s_add_u32 s42, s42, 0x100
	s_addc_u32 s43, s43, 0
	s_add_u32 s90, s90, 0x100
	s_addc_u32 s91, s91, 0
	s_cmp_gt_u32 s92, 13
	s_cbranch_scc0 .LBB0_192
	s_and_b64 vcc, exec, s[18:19]
	s_cbranch_vccz .LBB0_195
	s_barrier

; #define PG8_STAGE(bufoff, gbase, voff) do { _Pragma("unroll") for (int _i = 0; _i < 2; ++_i) \
;         __builtin_amdgcn_global_load_lds((const unsigned*)((const char*)(gbase) + (voff)[_i]), (PG8_LAS unsigned*)(lds + (bufoff) + ldsw + _i * 8192), 16, 0, 0); } while (0)
; #define PG8_LDA(dst, b, h) do { _Pragma("unroll") for (int m = 0; m < 4; ++m) _Pragma("unroll") for (int k = 0; k < 2; ++k) dst[m][k] = *(const PG8_LAS bf16x8*)(lds + PG8_SA(b, h) + aoff + m * 2048 + k * 1024); } while (0)
; #define PG8_LDB(dst, b, h) do { _Pragma("unroll") for (int n = 0; n < 2; ++n) _Pragma("unroll") for (int k = 0; k < 2; ++k) dst[n][k] = *(const PG8_LAS bf16x8*)(lds + PG8_SB(b, h) + boff + n * 2048 + k * 1024); } while (0)
; #define PG8_MMA(ai, bj, At, Bt) do { __builtin_amdgcn_s_setprio(1); _Pragma("unroll") for (int m = 0; m < 4; ++m) _Pragma("unroll") for (int n = 0; n < 2; ++n) _Pragma("unroll") for (int k = 0; k < 2; ++k) \
;         acc[ai][bj][m][n] = __builtin_amdgcn_mfma_f32_16x16x32_bf16(Bt[n][k], At[m][k], acc[ai][bj][m][n], 0, 0, 0); __builtin_amdgcn_s_setprio(0); } while (0)
; #define PG8_WAIT_V(n) asm volatile("s_waitcnt vmcnt(" #n ")" ::: "memory")
; #define PG8_BAR __builtin_amdgcn_s_barrier()
; template <class Epi, class Sched, bool ALIGN_EPI = false, bool SP2 = false>
; __device__ __forceinline__ void gemm_phase(PG8_LAS unsigned char* lds, const Gemm g, const Sched& S, const Epi& E) {
;     ...
;         for (int t = 0; t < nt; t += 2) {
;             const bool last = (t == nt - 2);
;             const char* a1 = cA + (size_t)(t + 1) * kstep;
;             const char* a2 = last ? nA : cA + (size_t)(t + 2) * kstep; const char* b2 = last ? nB : cB + (size_t)(t + 2) * kstep;
;             const char* a3 = a2 + kstep; const char* b3 = b2 + kstep;
;             if (last && has_next) S.a_ready(nxt);
;             if constexpr (SP2) {
;             PG8_LDB(B0, 0, 0); PG8_LDB(B1, 0, 1); PG8_SCHED; PG8_LDA(At, 0, 0); PG8_STAGE(PG8_SA(1, 1), a1 + hstep, voffA);
;             PG8_WAIT_V(8); PG8_WAIT_L(0); PG8_BAR; PG8_MMA(0, 0, At, B0); PG8_MMA(0, 1, At, B1); PG8_BAR; PG8_SCHED;
;             PG8_LDA(At, 0, 1); PG8_STAGE(PG8_SB(0, 0), b2, voffB); PG8_STAGE(PG8_SB(0, 1), b2 + hstep, voffB); PG8_STAGE(PG8_SA(0, 0), a2, voffA);
;             PG8_WAIT_V(8); PG8_WAIT_L(0); PG8_BAR; PG8_MMA(1, 0, At, B0); PG8_MMA(1, 1, At, B1); PG8_BAR; PG8_SCHED;
.LBB0_266:
	ds_read_b128 v[128:131], v171
	ds_read_b128 v[132:135], v171 offset:1024
	ds_read_b128 v[136:139], v171 offset:2048
	ds_read_b128 v[140:143], v171 offset:3072
	ds_read_b128 v[160:163], v172
	ds_read_b128 v[164:167], v172 offset:1024
	ds_read_b128 v[176:179], v172 offset:2048
	ds_read_b128 v[182:185], v172 offset:3072
	s_add_u32 s22, s20, 0xfff50080
	s_addc_u32 s23, s21, -1
	s_cmp_eq_u32 s86, 40
	s_cselect_b32 s25, s1, s23
	s_cselect_b32 s24, s0, s22
	s_cselect_b32 s23, s7, s85
	s_cselect_b32 s22, s6, s84
	v_lshl_add_u64 v[220:221], s[20:21], 0, v[152:153]
	s_add_i32 m0, s40, 0xc000
	ds_read_b128 v[186:189], v173
	ds_read_b128 v[192:195], v173 offset:1024
	ds_read_b128 v[196:199], v173 offset:2048
	ds_read_b128 v[200:203], v173 offset:3072
	ds_read_b128 v[204:207], v173 offset:4096
	ds_read_b128 v[208:211], v173 offset:5120
	ds_read_b128 v[212:215], v173 offset:6144
	ds_read_b128 v[216:219], v173 offset:7168
	global_load_lds_dwordx4 v[220:221], off
	v_lshl_add_u64 v[220:221], s[20:21], 0, v[154:155]
	s_add_i32 m0, s40, 0xe000
	s_nop 0
	global_load_lds_dwordx4 v[220:221], off
	s_waitcnt vmcnt(8)
	s_waitcnt lgkmcnt(0)
	s_setprio 1
	s_barrier
	v_mfma_f32_16x16x32_bf16 v[124:127], v[128:131], v[186:189], v[124:127]
	v_mfma_f32_16x16x32_bf16 v[120:123], v[136:139], v[186:189], v[120:123]
	v_mfma_f32_16x16x32_bf16 v[108:111], v[128:131], v[196:199], v[108:111]
	v_mfma_f32_16x16x32_bf16 v[104:107], v[136:139], v[196:199], v[104:107]
	v_mfma_f32_16x16x32_bf16 v[92:95], v[128:131], v[204:207], v[92:95]
	v_mfma_f32_16x16x32_bf16 v[88:91], v[136:139], v[204:207], v[88:91]
	v_mfma_f32_16x16x32_bf16 v[76:79], v[128:131], v[212:215], v[76:79]
	v_mfma_f32_16x16x32_bf16 v[72:75], v[136:139], v[212:215], v[72:75]
	v_mfma_f32_16x16x32_bf16 v[124:127], v[132:135], v[192:195], v[124:127]
	v_mfma_f32_16x16x32_bf16 v[120:123], v[140:143], v[192:195], v[120:123]
	v_mfma_f32_16x16x32_bf16 v[108:111], v[132:135], v[200:203], v[108:111]
	v_mfma_f32_16x16x32_bf16 v[104:107], v[140:143], v[200:203], v[104:107]
	v_mfma_f32_16x16x32_bf16 v[92:95], v[132:135], v[208:211], v[92:95]
	v_mfma_f32_16x16x32_bf16 v[88:91], v[140:143], v[208:211], v[88:91]
	v_mfma_f32_16x16x32_bf16 v[76:79], v[132:135], v[216:219], v[76:79]
	v_mfma_f32_16x16x32_bf16 v[72:75], v[140:143], v[216:219], v[72:75]
	s_setprio 0
	s_setprio 1
	v_mfma_f32_16x16x32_bf16 v[116:119], v[160:163], v[186:189], v[116:119]
	v_mfma_f32_16x16x32_bf16 v[112:115], v[176:179], v[186:189], v[112:115]
	v_mfma_f32_16x16x32_bf16 v[100:103], v[160:163], v[196:199], v[100:103]
	v_mfma_f32_16x16x32_bf16 v[96:99], v[176:179], v[196:199], v[96:99]
	v_mfma_f32_16x16x32_bf16 v[84:87], v[160:163], v[204:207], v[84:87]
	v_mfma_f32_16x16x32_bf16 v[80:83], v[176:179], v[204:207], v[80:83]
	v_mfma_f32_16x16x32_bf16 v[68:71], v[160:163], v[212:215], v[68:71]
	v_mfma_f32_16x16x32_bf16 v[64:67], v[176:179], v[212:215], v[64:67]
	v_mfma_f32_16x16x32_bf16 v[116:119], v[164:167], v[192:195], v[116:119]
	v_mfma_f32_16x16x32_bf16 v[112:115], v[182:185], v[192:195], v[112:115]
	v_mfma_f32_16x16x32_bf16 v[100:103], v[164:167], v[200:203], v[100:103]
	v_mfma_f32_16x16x32_bf16 v[96:99], v[182:185], v[200:203], v[96:99]
	v_mfma_f32_16x16x32_bf16 v[84:87], v[164:167], v[208:211], v[84:87]
	v_mfma_f32_16x16x32_bf16 v[80:83], v[182:185], v[208:211], v[80:83]
	v_mfma_f32_16x16x32_bf16 v[68:71], v[164:167], v[216:219], v[68:71]
	v_mfma_f32_16x16x32_bf16 v[64:67], v[182:185], v[216:219], v[64:67]
	s_setprio 0
	s_barrier
	s_add_i32 s87, s78, s27
	v_lshl_add_u64 v[220:221], s[22:23], 0, v[146:147]
	s_mov_b32 m0, s87
	ds_read_b128 v[186:189], v173 offset:16384
	ds_read_b128 v[192:195], v173 offset:17408
	ds_read_b128 v[196:199], v173 offset:18432
	ds_read_b128 v[200:203], v173 offset:19456
	ds_read_b128 v[204:207], v173 offset:20480
	ds_read_b128 v[208:211], v173 offset:21504
	ds_read_b128 v[212:215], v173 offset:22528
	ds_read_b128 v[216:219], v173 offset:23552
	global_load_lds_dwordx4 v[220:221], off
	s_add_i32 m0, s87, 0x2000
	s_add_u32 s88, s22, 0xb0000
	v_lshl_add_u64 v[222:223], s[22:23], 0, v[150:151]
	s_addc_u32 s89, s23, 0
	s_add_i32 s87, s79, s27
	global_load_lds_dwordx4 v[222:223], off
	v_lshl_add_u64 v[224:225], s[88:89], 0, v[146:147]
	s_mov_b32 m0, s87
	v_lshl_add_u64 v[226:227], s[24:25], 0, v[148:149]
	global_load_lds_dwordx4 v[224:225], off
	v_lshl_add_u64 v[224:225], s[88:89], 0, v[150:151]
	s_add_i32 m0, s87, 0x2000
	s_nop 0
	global_load_lds_dwordx4 v[224:225], off
	s_waitcnt vmcnt(6)
	s_waitcnt lgkmcnt(0)
	s_setprio 1
	s_barrier
; #define PG8_STAGE(bufoff, gbase, voff) do { _Pragma("unroll") for (int _i = 0; _i < 2; ++_i) \
;         __builtin_amdgcn_global_load_lds((const unsigned*)((const char*)(gbase) + (voff)[_i]), (PG8_LAS unsigned*)(lds + (bufoff) + ldsw + _i * 8192), 16, 0, 0); } while (0)
; #define PG8_LDA(dst, b, h) do { _Pragma("unroll") for (int m = 0; m < 4; ++m) _Pragma("unroll") for (int k = 0; k < 2; ++k) dst[m][k] = *(const PG8_LAS bf16x8*)(lds + PG8_SA(b, h) + aoff + m * 2048 + k * 1024); } while (0)
; #define PG8_LDB(dst, b, h) do { _Pragma("unroll") for (int n = 0; n < 2; ++n) _Pragma("unroll") for (int k = 0; k < 2; ++k) dst[n][k] = *(const PG8_LAS bf16x8*)(lds + PG8_SB(b, h) + boff + n * 2048 + k * 1024); } while (0)
; #define PG8_MMA(ai, bj, At, Bt) do { __builtin_amdgcn_s_setprio(1); _Pragma("unroll") for (int m = 0; m < 4; ++m) _Pragma("unroll") for (int n = 0; n < 2; ++n) _Pragma("unroll") for (int k = 0; k < 2; ++k) \
;         acc[ai][bj][m][n] = __builtin_amdgcn_mfma_f32_16x16x32_bf16(Bt[n][k], At[m][k], acc[ai][bj][m][n], 0, 0, 0); __builtin_amdgcn_s_setprio(0); } while (0)
; #define PG8_WAIT_V(n) asm volatile("s_waitcnt vmcnt(" #n ")" ::: "memory")
; #define PG8_WAIT_L(n) asm volatile("s_waitcnt lgkmcnt(" #n ")" ::: "memory")
; #define PG8_BAR __builtin_amdgcn_s_barrier()
; #define PG8_SCHED __builtin_amdgcn_sched_barrier(0)
; template <class Epi, class Sched, bool ALIGN_EPI = false, bool SP2 = false>
; __device__ __forceinline__ void gemm_phase(PG8_LAS unsigned char* lds, const Gemm g, const Sched& S, const Epi& E) {
;     ...
;             PG8_WAIT_V(8); PG8_WAIT_L(0); PG8_BAR; PG8_MMA(0, 0, At, B0); PG8_MMA(0, 1, At, B1); PG8_BAR; PG8_SCHED;
;             PG8_LDA(At, 0, 1); PG8_STAGE(PG8_SB(0, 0), b2, voffB); PG8_STAGE(PG8_SB(0, 1), b2 + hstep, voffB); PG8_STAGE(PG8_SA(0, 0), a2, voffA);
;             PG8_WAIT_V(8); PG8_WAIT_L(0); PG8_BAR; PG8_MMA(1, 0, At, B0); PG8_MMA(1, 1, At, B1); PG8_BAR; PG8_SCHED;
;             PG8_LDB(B0, 1, 0); PG8_LDB(B1, 1, 1); PG8_SCHED; PG8_LDA(At, 1, 0); PG8_STAGE(PG8_SA(0, 1), a2 + hstep, voffA);
;             PG8_WAIT_V(8); PG8_WAIT_L(0); PG8_BAR; PG8_MMA(0, 0, At, B0); PG8_MMA(0, 1, At, B1); PG8_BAR; PG8_SCHED;
	v_mfma_f32_16x16x32_bf16 v[60:63], v[128:131], v[186:189], v[60:63]
	v_mfma_f32_16x16x32_bf16 v[56:59], v[136:139], v[186:189], v[56:59]
	v_mfma_f32_16x16x32_bf16 v[44:47], v[128:131], v[196:199], v[44:47]
	v_mfma_f32_16x16x32_bf16 v[40:43], v[136:139], v[196:199], v[40:43]
	v_mfma_f32_16x16x32_bf16 v[28:31], v[128:131], v[204:207], v[28:31]
	v_mfma_f32_16x16x32_bf16 v[24:27], v[136:139], v[204:207], v[24:27]
	v_lshl_add_u64 v[224:225], s[24:25], 0, v[144:145]
	s_mov_b32 m0, s40
	s_nop 0
	global_load_lds_dwordx4 v[224:225], off
	v_mfma_f32_16x16x32_bf16 v[12:15], v[128:131], v[212:215], v[12:15]
	v_mfma_f32_16x16x32_bf16 v[8:11], v[136:139], v[212:215], v[8:11]
	v_mfma_f32_16x16x32_bf16 v[60:63], v[132:135], v[192:195], v[60:63]
	v_mfma_f32_16x16x32_bf16 v[56:59], v[140:143], v[192:195], v[56:59]
	v_mfma_f32_16x16x32_bf16 v[44:47], v[132:135], v[200:203], v[44:47]
	v_mfma_f32_16x16x32_bf16 v[40:43], v[140:143], v[200:203], v[40:43]
	v_mfma_f32_16x16x32_bf16 v[28:31], v[132:135], v[208:211], v[28:31]
	v_mfma_f32_16x16x32_bf16 v[24:27], v[140:143], v[208:211], v[24:27]
	v_mfma_f32_16x16x32_bf16 v[12:15], v[132:135], v[216:219], v[12:15]
	v_mfma_f32_16x16x32_bf16 v[8:11], v[140:143], v[216:219], v[8:11]
	s_setprio 0
	s_setprio 1
	v_mfma_f32_16x16x32_bf16 v[52:55], v[160:163], v[186:189], v[52:55]
	v_mfma_f32_16x16x32_bf16 v[48:51], v[176:179], v[186:189], v[48:51]
	v_mfma_f32_16x16x32_bf16 v[36:39], v[160:163], v[196:199], v[36:39]
	v_mfma_f32_16x16x32_bf16 v[32:35], v[176:179], v[196:199], v[32:35]
	v_mfma_f32_16x16x32_bf16 v[20:23], v[160:163], v[204:207], v[20:23]
	v_mfma_f32_16x16x32_bf16 v[16:19], v[176:179], v[204:207], v[16:19]
	s_mov_b32 m0, s41
	s_nop 0
	global_load_lds_dwordx4 v[226:227], off
	v_mfma_f32_16x16x32_bf16 v[4:7], v[160:163], v[212:215], v[4:7]
	v_mfma_f32_16x16x32_bf16 v[0:3], v[176:179], v[212:215], v[0:3]
	v_mfma_f32_16x16x32_bf16 v[52:55], v[164:167], v[192:195], v[52:55]
	v_mfma_f32_16x16x32_bf16 v[48:51], v[182:185], v[192:195], v[48:51]
	v_mfma_f32_16x16x32_bf16 v[36:39], v[164:167], v[200:203], v[36:39]
	v_mfma_f32_16x16x32_bf16 v[32:35], v[182:185], v[200:203], v[32:35]
	v_mfma_f32_16x16x32_bf16 v[20:23], v[164:167], v[208:211], v[20:23]
	v_mfma_f32_16x16x32_bf16 v[16:19], v[182:185], v[208:211], v[16:19]
	v_mfma_f32_16x16x32_bf16 v[4:7], v[164:167], v[216:219], v[4:7]
	v_mfma_f32_16x16x32_bf16 v[0:3], v[182:185], v[216:219], v[0:3]
	s_setprio 0
	s_barrier
	s_add_i32 s87, 0, 0x18000
	s_add_i32 s88, 0, 0x1c000
	v_add_u32_e32 v140, s87, v169
	v_add_u32_e32 v175, s88, v169
	ds_read_b128 v[128:131], v140
	ds_read_b128 v[132:135], v140 offset:1024
	ds_read_b128 v[136:139], v140 offset:2048
	ds_read_b128 v[140:143], v140 offset:3072
	ds_read_b128 v[160:163], v175
	ds_read_b128 v[164:167], v175 offset:1024
	ds_read_b128 v[176:179], v175 offset:2048
	ds_read_b128 v[182:185], v175 offset:3072
	s_add_u32 s24, s24, 0xb0000
	s_addc_u32 s25, s25, 0
	s_mov_b32 m0, s42
	v_lshl_add_u64 v[228:229], s[24:25], 0, v[144:145]
	ds_read_b128 v[186:189], v173 offset:32768
	ds_read_b128 v[192:195], v173 offset:33792
	ds_read_b128 v[196:199], v173 offset:34816
	ds_read_b128 v[200:203], v173 offset:35840
	ds_read_b128 v[204:207], v173 offset:36864
	ds_read_b128 v[208:211], v173 offset:37888
	ds_read_b128 v[212:215], v173 offset:38912
	ds_read_b128 v[216:219], v173 offset:39936
	global_load_lds_dwordx4 v[228:229], off
	v_lshl_add_u64 v[228:229], s[24:25], 0, v[148:149]
	s_mov_b32 m0, s43
	s_nop 0
	global_load_lds_dwordx4 v[228:229], off
	s_waitcnt vmcnt(8)
	s_waitcnt lgkmcnt(0)
	s_setprio 1
	s_barrier
	v_mfma_f32_16x16x32_bf16 v[124:127], v[128:131], v[186:189], v[124:127]
	v_mfma_f32_16x16x32_bf16 v[120:123], v[136:139], v[186:189], v[120:123]
	v_mfma_f32_16x16x32_bf16 v[108:111], v[128:131], v[196:199], v[108:111]
	v_mfma_f32_16x16x32_bf16 v[104:107], v[136:139], v[196:199], v[104:107]
	v_mfma_f32_16x16x32_bf16 v[92:95], v[128:131], v[204:207], v[92:95]
	v_mfma_f32_16x16x32_bf16 v[88:91], v[136:139], v[204:207], v[88:91]
	v_mfma_f32_16x16x32_bf16 v[76:79], v[128:131], v[212:215], v[76:79]
	v_mfma_f32_16x16x32_bf16 v[72:75], v[136:139], v[212:215], v[72:75]
	v_mfma_f32_16x16x32_bf16 v[124:127], v[132:135], v[192:195], v[124:127]
	v_mfma_f32_16x16x32_bf16 v[120:123], v[140:143], v[192:195], v[120:123]
	v_mfma_f32_16x16x32_bf16 v[108:111], v[132:135], v[200:203], v[108:111]
	v_mfma_f32_16x16x32_bf16 v[104:107], v[140:143], v[200:203], v[104:107]
	v_mfma_f32_16x16x32_bf16 v[92:95], v[132:135], v[208:211], v[92:95]
	v_mfma_f32_16x16x32_bf16 v[88:91], v[140:143], v[208:211], v[88:91]
	v_mfma_f32_16x16x32_bf16 v[76:79], v[132:135], v[216:219], v[76:79]
	v_mfma_f32_16x16x32_bf16 v[72:75], v[140:143], v[216:219], v[72:75]
	s_setprio 0
	s_setprio 1
	v_mfma_f32_16x16x32_bf16 v[116:119], v[160:163], v[186:189], v[116:119]
	v_mfma_f32_16x16x32_bf16 v[112:115], v[176:179], v[186:189], v[112:115]
	v_mfma_f32_16x16x32_bf16 v[100:103], v[160:163], v[196:199], v[100:103]
	v_mfma_f32_16x16x32_bf16 v[96:99], v[176:179], v[196:199], v[96:99]
	v_mfma_f32_16x16x32_bf16 v[84:87], v[160:163], v[204:207], v[84:87]
	v_mfma_f32_16x16x32_bf16 v[80:83], v[176:179], v[204:207], v[80:83]
	v_mfma_f32_16x16x32_bf16 v[68:71], v[160:163], v[212:215], v[68:71]
	v_mfma_f32_16x16x32_bf16 v[64:67], v[176:179], v[212:215], v[64:67]
	v_mfma_f32_16x16x32_bf16 v[116:119], v[164:167], v[192:195], v[116:119]
	v_mfma_f32_16x16x32_bf16 v[112:115], v[182:185], v[192:195], v[112:115]
	v_mfma_f32_16x16x32_bf16 v[100:103], v[164:167], v[200:203], v[100:103]
	v_mfma_f32_16x16x32_bf16 v[96:99], v[182:185], v[200:203], v[96:99]
	v_mfma_f32_16x16x32_bf16 v[84:87], v[164:167], v[208:211], v[84:87]
	v_mfma_f32_16x16x32_bf16 v[80:83], v[182:185], v[208:211], v[80:83]
	v_mfma_f32_16x16x32_bf16 v[68:71], v[164:167], v[216:219], v[68:71]
	v_mfma_f32_16x16x32_bf16 v[64:67], v[182:185], v[216:219], v[64:67]
	s_setprio 0
	s_barrier
; #define PG8_STAGE(bufoff, gbase, voff) do { _Pragma("unroll") for (int _i = 0; _i < 2; ++_i) \
;         __builtin_amdgcn_global_load_lds((const unsigned*)((const char*)(gbase) + (voff)[_i]), (PG8_LAS unsigned*)(lds + (bufoff) + ldsw + _i * 8192), 16, 0, 0); } while (0)
; #define PG8_LDA(dst, b, h) do { _Pragma("unroll") for (int m = 0; m < 4; ++m) _Pragma("unroll") for (int k = 0; k < 2; ++k) dst[m][k] = *(const PG8_LAS bf16x8*)(lds + PG8_SA(b, h) + aoff + m * 2048 + k * 1024); } while (0)
; #define PG8_MMA(ai, bj, At, Bt) do { __builtin_amdgcn_s_setprio(1); _Pragma("unroll") for (int m = 0; m < 4; ++m) _Pragma("unroll") for (int n = 0; n < 2; ++n) _Pragma("unroll") for (int k = 0; k < 2; ++k) \
;         acc[ai][bj][m][n] = __builtin_amdgcn_mfma_f32_16x16x32_bf16(Bt[n][k], At[m][k], acc[ai][bj][m][n], 0, 0, 0); __builtin_amdgcn_s_setprio(0); } while (0)
; #define PG8_WAIT_V(n) asm volatile("s_waitcnt vmcnt(" #n ")" ::: "memory")
; #define PG8_WAIT_L(n) asm volatile("s_waitcnt lgkmcnt(" #n ")" ::: "memory")
; #define PG8_BAR __builtin_amdgcn_s_barrier()
; #define PG8_SCHED __builtin_amdgcn_sched_barrier(0)
; template <class Epi, class Sched, bool ALIGN_EPI = false, bool SP2 = false>
; __device__ __forceinline__ void gemm_phase(PG8_LAS unsigned char* lds, const Gemm g, const Sched& S, const Epi& E) {
;     ...
;             PG8_WAIT_V(8); PG8_WAIT_L(0); PG8_BAR; PG8_MMA(0, 0, At, B0); PG8_MMA(0, 1, At, B1); PG8_BAR; PG8_SCHED;
;             PG8_LDA(At, 1, 1); PG8_STAGE(PG8_SB(1, 0), b3, voffB); PG8_STAGE(PG8_SB(1, 1), b3 + hstep, voffB); PG8_STAGE(PG8_SA(1, 0), a3, voffA);
;             PG8_WAIT_V(8); PG8_WAIT_L(0); PG8_BAR; PG8_MMA(1, 0, At, B0); PG8_MMA(1, 1, At, B1); PG8_BAR; PG8_SCHED;
	s_add_i32 s24, s87, s27
	v_lshl_add_u64 v[220:221], v[220:221], 0, s[18:19]
	s_mov_b32 m0, s24
	ds_read_b128 v[186:189], v173 offset:49152
	ds_read_b128 v[192:195], v173 offset:50176
	ds_read_b128 v[196:199], v173 offset:51200
	ds_read_b128 v[200:203], v173 offset:52224
	ds_read_b128 v[204:207], v173 offset:53248
	ds_read_b128 v[208:211], v173 offset:54272
	ds_read_b128 v[212:215], v173 offset:55296
	ds_read_b128 v[216:219], v173 offset:56320
	global_load_lds_dwordx4 v[220:221], off
	s_add_i32 m0, s24, 0x2000
	s_add_u32 s22, s22, 0xb0080
	v_lshl_add_u64 v[220:221], v[222:223], 0, s[18:19]
	s_addc_u32 s23, s23, 0
	s_add_i32 s24, s88, s27
	global_load_lds_dwordx4 v[220:221], off
	v_lshl_add_u64 v[220:221], s[22:23], 0, v[146:147]
	s_mov_b32 m0, s24
	s_nop 0
	global_load_lds_dwordx4 v[220:221], off
	v_lshl_add_u64 v[220:221], s[22:23], 0, v[150:151]
	s_add_i32 m0, s24, 0x2000
	s_nop 0
	global_load_lds_dwordx4 v[220:221], off
	s_waitcnt vmcnt(6)
	s_waitcnt lgkmcnt(0)
	s_setprio 1
	s_barrier
	v_mfma_f32_16x16x32_bf16 v[60:63], v[128:131], v[186:189], v[60:63]
	v_mfma_f32_16x16x32_bf16 v[56:59], v[136:139], v[186:189], v[56:59]
	v_mfma_f32_16x16x32_bf16 v[44:47], v[128:131], v[196:199], v[44:47]
	v_mfma_f32_16x16x32_bf16 v[40:43], v[136:139], v[196:199], v[40:43]
	v_mfma_f32_16x16x32_bf16 v[28:31], v[128:131], v[204:207], v[28:31]
	v_mfma_f32_16x16x32_bf16 v[24:27], v[136:139], v[204:207], v[24:27]
	v_lshl_add_u64 v[220:221], v[224:225], 0, s[18:19]
	s_mov_b32 m0, s45
	s_nop 0
	global_load_lds_dwordx4 v[220:221], off
	v_mfma_f32_16x16x32_bf16 v[12:15], v[128:131], v[212:215], v[12:15]
	v_mfma_f32_16x16x32_bf16 v[8:11], v[136:139], v[212:215], v[8:11]
	v_mfma_f32_16x16x32_bf16 v[60:63], v[132:135], v[192:195], v[60:63]
	v_mfma_f32_16x16x32_bf16 v[56:59], v[140:143], v[192:195], v[56:59]
	v_mfma_f32_16x16x32_bf16 v[44:47], v[132:135], v[200:203], v[44:47]
	v_mfma_f32_16x16x32_bf16 v[40:43], v[140:143], v[200:203], v[40:43]
	v_mfma_f32_16x16x32_bf16 v[28:31], v[132:135], v[208:211], v[28:31]
	v_mfma_f32_16x16x32_bf16 v[24:27], v[140:143], v[208:211], v[24:27]
	v_mfma_f32_16x16x32_bf16 v[12:15], v[132:135], v[216:219], v[12:15]
	v_mfma_f32_16x16x32_bf16 v[8:11], v[140:143], v[216:219], v[8:11]
	s_setprio 0
	s_setprio 1
	v_mfma_f32_16x16x32_bf16 v[52:55], v[160:163], v[186:189], v[52:55]
	v_mfma_f32_16x16x32_bf16 v[48:51], v[176:179], v[186:189], v[48:51]
	v_mfma_f32_16x16x32_bf16 v[36:39], v[160:163], v[196:199], v[36:39]
	v_mfma_f32_16x16x32_bf16 v[32:35], v[176:179], v[196:199], v[32:35]
	v_mfma_f32_16x16x32_bf16 v[20:23], v[160:163], v[204:207], v[20:23]
	v_mfma_f32_16x16x32_bf16 v[16:19], v[176:179], v[204:207], v[16:19]
	v_lshl_add_u64 v[220:221], v[226:227], 0, s[18:19]
	s_mov_b32 m0, s46
	s_nop 0
	global_load_lds_dwordx4 v[220:221], off
	v_mfma_f32_16x16x32_bf16 v[4:7], v[160:163], v[212:215], v[4:7]
	v_mfma_f32_16x16x32_bf16 v[0:3], v[176:179], v[212:215], v[0:3]
	v_mfma_f32_16x16x32_bf16 v[52:55], v[164:167], v[192:195], v[52:55]
	v_mfma_f32_16x16x32_bf16 v[48:51], v[182:185], v[192:195], v[48:51]
	v_mfma_f32_16x16x32_bf16 v[36:39], v[164:167], v[200:203], v[36:39]
	v_mfma_f32_16x16x32_bf16 v[32:35], v[182:185], v[200:203], v[32:35]
	v_mfma_f32_16x16x32_bf16 v[20:23], v[164:167], v[208:211], v[20:23]
	v_mfma_f32_16x16x32_bf16 v[16:19], v[182:185], v[208:211], v[16:19]
	v_mfma_f32_16x16x32_bf16 v[4:7], v[164:167], v[216:219], v[4:7]
	v_mfma_f32_16x16x32_bf16 v[0:3], v[182:185], v[216:219], v[0:3]
	s_setprio 0
	s_barrier
	s_add_i32 s86, s86, 2
	s_add_u32 s20, s20, 0x100
	s_addc_u32 s21, s21, 0
	s_add_u32 s84, s84, 0x100
	s_addc_u32 s85, s85, 0
	s_cmp_gt_u32 s86, 41
	s_cbranch_scc0 .LBB0_266
; __device__ __forceinline__ u32x2 pack4(f32x4 v) { u32x2 w; w.x = cvt_pk_bf16(v[0], v[1]); w.y = cvt_pk_bf16(v[2], v[3]); return w; }
;     __device__ __forceinline__ void operator()(const f32x4 (&acc)[2][2][4][2], const Unit& u, int wr, int wc, int fr, int fq) const {
;         const int row0 = u.pm * BM + wr * 64 + fr, col0 = u.pn * BM + wc * 32 + 8 * fq;
;         const float* base = (u.pm * BM < split) ? base0 : base1; bf16_t* const xn = (bf16_t*)(ws + WS_XN); float* const ssq = (float*)(ws + WS_SSQ);
; #pragma unroll
;         for (int ai = 0; ai < 2; ++ai)
; #pragma unroll
;         for (int mh = 0; mh < 4; mh += 2) {
;             f32x4 pre[4][2][2];
; #pragma unroll
;             for (int m = mh; m < mh + 2; ++m)
; #pragma unroll
;                 for (int bj = 0; bj < 2; ++bj)
; #pragma unroll
;                     for (int n = 0; n < 2; ++n) pre[m][bj][n] = *(const f32x4*)(base + (size_t)(row0 + ai * HALF + m * 16) * 1024 + col0 + bj * HALF + n * 4);
;             asm volatile("" ::: "memory");
; #pragma unroll
;             for (int m = mh; m < mh + 2; ++m) { const int row = row0 + ai * HALF + m * 16; const size_t off = (size_t)row * 1024 + col0; float ss = 0.f;
; #pragma unroll
;                 for (int bj = 0; bj < 2; ++bj) { u32x4e w;
; #pragma unroll
;                     for (int n = 0; n < 2; ++n) { const f32x4 o = pre[m][bj][n] + acc[ai][bj][m][n] * s;
;                         *(f32x4*)(out + off + bj * HALF + n * 4) = o;
;                         if (NORMOUT) { const u32x2 p = pack4(o); w[2 * n] = p.x; w[2 * n + 1] = p.y; ss += (o[0] * o[0] + o[1] * o[1]) + (o[2] * o[2] + o[3] * o[3]); } }
;                     if (NORMOUT) *(u32x4e*)(xn + off + bj * HALF) = w; }
;                 if (NORMOUT) { ss += __shfl_xor(ss, 16); ss += __shfl_xor(ss, 32); if (fq == 0) ssq[(size_t)row * 16 + u.pn * 4 + wc] = ss; } }
	s_cmpk_lt_i32 s83, 0x80
	v_lshl_add_u32 v162, s83, 8, v168
	v_lshl_or_b32 v160, s82, 8, v170
	s_cselect_b32 s20, s37, s39
	s_cselect_b32 s21, s36, s38
	v_mov_b32_e32 v128, s21
	v_mov_b32_e32 v129, s20
	v_ashrrev_i32_e32 v161, 31, v160
	v_ashrrev_i32_e32 v163, 31, v162
	v_lshl_add_u64 v[164:165], v[160:161], 2, v[128:129]
	v_lshlrev_b64 v[128:129], 12, v[162:163]
	v_lshl_add_u64 v[128:129], v[164:165], 0, v[128:129]
	global_load_dwordx4 v[182:185], v[128:129], off
	global_load_dwordx4 v[186:189], v[128:129], off offset:16
	global_load_dwordx4 v[192:195], v[128:129], off offset:512
	global_load_dwordx4 v[196:199], v[128:129], off offset:528
	v_or_b32_e32 v166, 16, v162
	v_ashrrev_i32_e32 v167, 31, v166
	v_lshlrev_b64 v[128:129], 12, v[166:167]
	v_lshl_add_u64 v[132:133], v[164:165], 0, v[128:129]
	global_load_dwordx4 v[136:139], v[132:133], off offset:16
	global_load_dwordx4 v[140:143], v[132:133], off
	global_load_dwordx4 v[128:131], v[132:133], off offset:528
	s_nop 0
	global_load_dwordx4 v[132:135], v[132:133], off offset:512
	v_and_b32_e32 v176, 64, v174
	v_xor_b32_e32 v175, 16, v174
	v_add_u32_e32 v176, 64, v176
	v_lshlrev_b64 v[178:179], 10, v[162:163]
	v_xor_b32_e32 v177, 32, v174
	v_cmp_lt_i32_e32 vcc, v175, v176
	v_lshl_add_u64 v[178:179], v[178:179], 0, v[160:161]
	v_lshl_add_u64 v[200:201], v[178:179], 1, s[64:65]
	v_cndmask_b32_e32 v175, v174, v175, vcc
	v_cmp_lt_i32_e32 vcc, v177, v176
	v_lshl_add_u64 v[178:179], v[178:179], 2, s[56:57]
	v_lshlrev_b32_e32 v176, 2, v175
	v_cndmask_b32_e32 v177, v174, v177, vcc
	v_lshlrev_b32_e32 v175, 2, v177
	s_lshl_b32 s20, s82, 2
	s_ashr_i32 s21, s20, 31
	s_lshl_b64 s[20:21], s[20:21], 2
	s_add_u32 s20, s49, s20
	s_addc_u32 s21, s60, s21
	s_waitcnt vmcnt(0)
	v_pk_fma_f32 v[126:127], v[126:127], 0.5, v[184:185] op_sel_hi:[1,0,1]
	v_pk_fma_f32 v[124:125], v[124:125], 0.5, v[182:183] op_sel_hi:[1,0,1]
	v_pk_fma_f32 v[122:123], v[122:123], 0.5, v[188:189] op_sel_hi:[1,0,1]
	v_pk_fma_f32 v[120:121], v[120:121], 0.5, v[186:187] op_sel_hi:[1,0,1]
	v_pk_fma_f32 v[118:119], v[118:119], 0.5, v[194:195] op_sel_hi:[1,0,1]
	v_pk_fma_f32 v[116:117], v[116:117], 0.5, v[192:193] op_sel_hi:[1,0,1]
	v_pk_fma_f32 v[184:185], v[114:115], 0.5, v[198:199] op_sel_hi:[1,0,1]
	v_pk_fma_f32 v[182:183], v[112:113], 0.5, v[196:197] op_sel_hi:[1,0,1]
	global_store_dwordx4 v[178:179], v[124:127], off
	v_cvt_pk_bf16_f32 v112, v124, v125
	v_cvt_pk_bf16_f32 v113, v126, v127
	v_mul_f32_e32 v125, v125, v125
	v_mul_f32_e32 v127, v127, v127
	global_store_dwordx4 v[178:179], v[120:123], off offset:16
	v_cvt_pk_bf16_f32 v114, v120, v121
	v_cvt_pk_bf16_f32 v115, v122, v123
	v_mul_f32_e32 v121, v121, v121
	v_mul_f32_e32 v123, v123, v123
	v_mul_f32_e32 v177, v117, v117
	v_mul_f32_e32 v181, v119, v119
	v_fmac_f32_e32 v125, v124, v124
	v_fmac_f32_e32 v127, v126, v126
	v_fmac_f32_e32 v121, v120, v120
	v_fmac_f32_e32 v123, v122, v122
	v_mul_f32_e32 v186, v183, v183
	v_mul_f32_e32 v187, v185, v185
	v_fmac_f32_e32 v177, v116, v116
	v_fmac_f32_e32 v181, v118, v118
	v_add_f32_e32 v120, v125, v127
	v_add_f32_e32 v121, v121, v123
	v_fmac_f32_e32 v186, v182, v182
	v_fmac_f32_e32 v187, v184, v184
	v_add_f32_e32 v122, v177, v181
	v_add_f32_e32 v120, v120, v121
	v_add_f32_e32 v120, v122, v120
	v_add_f32_e32 v121, v186, v187
	v_add_f32_e32 v120, v121, v120
	ds_bpermute_b32 v121, v176, v120
	global_store_dwordx4 v[200:201], v[112:115], off
	global_store_dwordx4 v[178:179], v[116:119], off offset:512
	global_store_dwordx4 v[178:179], v[182:185], off offset:528
	v_cvt_pk_bf16_f32 v114, v116, v117
	v_cvt_pk_bf16_f32 v115, v118, v119
	s_waitcnt lgkmcnt(0)
	v_add_f32_e32 v112, v120, v121
	ds_bpermute_b32 v113, v175, v112
	v_cvt_pk_bf16_f32 v116, v182, v183
	v_cvt_pk_bf16_f32 v117, v184, v185
	global_store_dwordx4 v[200:201], v[114:117], off offset:256
	s_and_saveexec_b64 s[22:23], s[2:3]
	s_cbranch_execz .LBB0_269
	v_lshlrev_b64 v[114:115], 6, v[162:163]
	v_lshl_add_u64 v[114:115], s[20:21], 0, v[114:115]
	s_waitcnt lgkmcnt(0)
	v_add_f32_e32 v112, v112, v113
	global_store_dword v[114:115], v112, off

; #define PG8_STAGE(bufoff, gbase, voff) do { _Pragma("unroll") for (int _i = 0; _i < 2; ++_i) \
;         __builtin_amdgcn_global_load_lds((const unsigned*)((const char*)(gbase) + (voff)[_i]), (PG8_LAS unsigned*)(lds + (bufoff) + ldsw + _i * 8192), 16, 0, 0); } while (0)
; #define PG8_LDA(dst, b, h) do { _Pragma("unroll") for (int m = 0; m < 4; ++m) _Pragma("unroll") for (int k = 0; k < 2; ++k) dst[m][k] = *(const PG8_LAS bf16x8*)(lds + PG8_SA(b, h) + aoff + m * 2048 + k * 1024); } while (0)
; #define PG8_LDB(dst, b, h) do { _Pragma("unroll") for (int n = 0; n < 2; ++n) _Pragma("unroll") for (int k = 0; k < 2; ++k) dst[n][k] = *(const PG8_LAS bf16x8*)(lds + PG8_SB(b, h) + boff + n * 2048 + k * 1024); } while (0)
; #define PG8_MMA(ai, bj, At, Bt) do { __builtin_amdgcn_s_setprio(1); _Pragma("unroll") for (int m = 0; m < 4; ++m) _Pragma("unroll") for (int n = 0; n < 2; ++n) _Pragma("unroll") for (int k = 0; k < 2; ++k) \
;         acc[ai][bj][m][n] = __builtin_amdgcn_mfma_f32_16x16x32_bf16(Bt[n][k], At[m][k], acc[ai][bj][m][n], 0, 0, 0); __builtin_amdgcn_s_setprio(0); } while (0)
; #define PG8_WAIT_V(n) asm volatile("s_waitcnt vmcnt(" #n ")" ::: "memory")
; #define PG8_BAR __builtin_amdgcn_s_barrier()
; template <class Epi, class Sched, bool ALIGN_EPI = false, bool SP2 = false>
; __device__ __forceinline__ void gemm_phase(PG8_LAS unsigned char* lds, const Gemm g, const Sched& S, const Epi& E) {
;     ...
;         for (int t = 0; t < nt; t += 2) {
;             const bool last = (t == nt - 2);
;             const char* a1 = cA + (size_t)(t + 1) * kstep;
;             const char* a2 = last ? nA : cA + (size_t)(t + 2) * kstep; const char* b2 = last ? nB : cB + (size_t)(t + 2) * kstep;
;             const char* a3 = a2 + kstep; const char* b3 = b2 + kstep;
;             if (last && has_next) S.a_ready(nxt);
;             if constexpr (SP2) {
;             PG8_LDB(B0, 0, 0); PG8_LDB(B1, 0, 1); PG8_SCHED; PG8_LDA(At, 0, 0); PG8_STAGE(PG8_SA(1, 1), a1 + hstep, voffA);
;             PG8_WAIT_V(8); PG8_WAIT_L(0); PG8_BAR; PG8_MMA(0, 0, At, B0); PG8_MMA(0, 1, At, B1); PG8_BAR; PG8_SCHED;
;             PG8_LDA(At, 0, 1); PG8_STAGE(PG8_SB(0, 0), b2, voffB); PG8_STAGE(PG8_SB(0, 1), b2 + hstep, voffB); PG8_STAGE(PG8_SA(0, 0), a2, voffA);
;             PG8_WAIT_V(8); PG8_WAIT_L(0); PG8_BAR; PG8_MMA(1, 0, At, B0); PG8_MMA(1, 1, At, B1); PG8_BAR; PG8_SCHED;
.LBB0_348:
	ds_read_b128 v[128:131], v186
	ds_read_b128 v[132:135], v186 offset:1024
	ds_read_b128 v[136:139], v186 offset:2048
	ds_read_b128 v[164:167], v186 offset:3072
	ds_read_b128 v[168:171], v187
	ds_read_b128 v[172:175], v187 offset:1024
	ds_read_b128 v[176:179], v187 offset:2048
	ds_read_b128 v[196:199], v187 offset:3072
	s_add_u32 s48, s6, 0xfffc0080
	s_addc_u32 s49, s7, -1
	s_cmp_eq_u32 s79, 12
	s_cselect_b32 s75, s1, s49
	s_cselect_b32 s74, s43, s48
	s_cselect_b32 s49, s41, s78
	s_cselect_b32 s48, s76, s77
	v_lshl_add_u64 v[228:229], s[6:7], 0, v[156:157]
	s_add_i32 m0, s83, 0xc000
	ds_read_b128 v[200:203], v188
	ds_read_b128 v[204:207], v188 offset:1024
	ds_read_b128 v[208:211], v188 offset:2048
	ds_read_b128 v[212:215], v188 offset:3072
	ds_read_b128 v[216:219], v188 offset:4096
	ds_read_b128 v[220:223], v188 offset:5120
	ds_read_b128 v[224:227], v188 offset:6144
	ds_read_b128 v[232:235], v188 offset:7168
	global_load_lds_dwordx4 v[228:229], off
	v_lshl_add_u64 v[228:229], s[6:7], 0, v[158:159]
	s_add_i32 m0, s83, 0xe000
	s_nop 0
	global_load_lds_dwordx4 v[228:229], off
	s_waitcnt vmcnt(8)
	s_waitcnt lgkmcnt(0)
	s_setprio 1
	s_barrier
	v_mfma_f32_16x16x32_bf16 v[124:127], v[128:131], v[200:203], v[124:127]
	v_mfma_f32_16x16x32_bf16 v[120:123], v[136:139], v[200:203], v[120:123]
	v_mfma_f32_16x16x32_bf16 v[108:111], v[128:131], v[208:211], v[108:111]
	v_mfma_f32_16x16x32_bf16 v[104:107], v[136:139], v[208:211], v[104:107]
	v_mfma_f32_16x16x32_bf16 v[92:95], v[128:131], v[216:219], v[92:95]
	v_mfma_f32_16x16x32_bf16 v[88:91], v[136:139], v[216:219], v[88:91]
	v_mfma_f32_16x16x32_bf16 v[76:79], v[128:131], v[224:227], v[76:79]
	v_mfma_f32_16x16x32_bf16 v[72:75], v[136:139], v[224:227], v[72:75]
	v_mfma_f32_16x16x32_bf16 v[124:127], v[132:135], v[204:207], v[124:127]
	v_mfma_f32_16x16x32_bf16 v[120:123], v[164:167], v[204:207], v[120:123]
	v_mfma_f32_16x16x32_bf16 v[108:111], v[132:135], v[212:215], v[108:111]
	v_mfma_f32_16x16x32_bf16 v[104:107], v[164:167], v[212:215], v[104:107]
	v_mfma_f32_16x16x32_bf16 v[92:95], v[132:135], v[220:223], v[92:95]
	v_mfma_f32_16x16x32_bf16 v[88:91], v[164:167], v[220:223], v[88:91]
	v_mfma_f32_16x16x32_bf16 v[76:79], v[132:135], v[232:235], v[76:79]
	v_mfma_f32_16x16x32_bf16 v[72:75], v[164:167], v[232:235], v[72:75]
	s_setprio 0
	s_setprio 1
	v_mfma_f32_16x16x32_bf16 v[116:119], v[168:171], v[200:203], v[116:119]
	v_mfma_f32_16x16x32_bf16 v[112:115], v[176:179], v[200:203], v[112:115]
	v_mfma_f32_16x16x32_bf16 v[100:103], v[168:171], v[208:211], v[100:103]
	v_mfma_f32_16x16x32_bf16 v[96:99], v[176:179], v[208:211], v[96:99]
	v_mfma_f32_16x16x32_bf16 v[84:87], v[168:171], v[216:219], v[84:87]
	v_mfma_f32_16x16x32_bf16 v[80:83], v[176:179], v[216:219], v[80:83]
	v_mfma_f32_16x16x32_bf16 v[68:71], v[168:171], v[224:227], v[68:71]
	v_mfma_f32_16x16x32_bf16 v[64:67], v[176:179], v[224:227], v[64:67]
	v_mfma_f32_16x16x32_bf16 v[116:119], v[172:175], v[204:207], v[116:119]
	v_mfma_f32_16x16x32_bf16 v[112:115], v[196:199], v[204:207], v[112:115]
	v_mfma_f32_16x16x32_bf16 v[100:103], v[172:175], v[212:215], v[100:103]
	v_mfma_f32_16x16x32_bf16 v[96:99], v[196:199], v[212:215], v[96:99]
	v_mfma_f32_16x16x32_bf16 v[84:87], v[172:175], v[220:223], v[84:87]
	v_mfma_f32_16x16x32_bf16 v[80:83], v[196:199], v[220:223], v[80:83]
	v_mfma_f32_16x16x32_bf16 v[68:71], v[172:175], v[232:235], v[68:71]
	v_mfma_f32_16x16x32_bf16 v[64:67], v[196:199], v[232:235], v[64:67]
	s_setprio 0
	s_barrier
	s_add_i32 vcc_lo, s97, s80
	v_lshl_add_u64 v[228:229], s[48:49], 0, v[144:145]
	s_mov_b32 m0, vcc_lo
	ds_read_b128 v[200:203], v188 offset:16384
	ds_read_b128 v[204:207], v188 offset:17408
	ds_read_b128 v[208:211], v188 offset:18432
	ds_read_b128 v[212:215], v188 offset:19456
	ds_read_b128 v[216:219], v188 offset:20480
	ds_read_b128 v[220:223], v188 offset:21504
	ds_read_b128 v[224:227], v188 offset:22528
	ds_read_b128 v[232:235], v188 offset:23552
	global_load_lds_dwordx4 v[228:229], off
	s_add_i32 m0, vcc_lo, 0x2000
	s_add_u32 vcc_lo, s48, 0x40000
	v_lshl_add_u64 v[236:237], s[48:49], 0, v[140:141]
	s_addc_u32 vcc_hi, s49, 0
	s_add_i32 s94, s60, s80
	global_load_lds_dwordx4 v[236:237], off
	v_lshl_add_u64 v[238:239], vcc, 0, v[144:145]
	s_mov_b32 m0, s94
	v_lshl_add_u64 v[240:241], s[74:75], 0, v[142:143]
	global_load_lds_dwordx4 v[238:239], off
	v_lshl_add_u64 v[238:239], vcc, 0, v[140:141]
	s_add_i32 m0, s94, 0x2000
	s_nop 0
	global_load_lds_dwordx4 v[238:239], off
	s_waitcnt vmcnt(6)
	s_waitcnt lgkmcnt(0)
	s_setprio 1
	s_barrier
; #define PG8_STAGE(bufoff, gbase, voff) do { _Pragma("unroll") for (int _i = 0; _i < 2; ++_i) \
;         __builtin_amdgcn_global_load_lds((const unsigned*)((const char*)(gbase) + (voff)[_i]), (PG8_LAS unsigned*)(lds + (bufoff) + ldsw + _i * 8192), 16, 0, 0); } while (0)
; #define PG8_LDA(dst, b, h) do { _Pragma("unroll") for (int m = 0; m < 4; ++m) _Pragma("unroll") for (int k = 0; k < 2; ++k) dst[m][k] = *(const PG8_LAS bf16x8*)(lds + PG8_SA(b, h) + aoff + m * 2048 + k * 1024); } while (0)
; #define PG8_LDB(dst, b, h) do { _Pragma("unroll") for (int n = 0; n < 2; ++n) _Pragma("unroll") for (int k = 0; k < 2; ++k) dst[n][k] = *(const PG8_LAS bf16x8*)(lds + PG8_SB(b, h) + boff + n * 2048 + k * 1024); } while (0)
; #define PG8_MMA(ai, bj, At, Bt) do { __builtin_amdgcn_s_setprio(1); _Pragma("unroll") for (int m = 0; m < 4; ++m) _Pragma("unroll") for (int n = 0; n < 2; ++n) _Pragma("unroll") for (int k = 0; k < 2; ++k) \
;         acc[ai][bj][m][n] = __builtin_amdgcn_mfma_f32_16x16x32_bf16(Bt[n][k], At[m][k], acc[ai][bj][m][n], 0, 0, 0); __builtin_amdgcn_s_setprio(0); } while (0)
; #define PG8_WAIT_V(n) asm volatile("s_waitcnt vmcnt(" #n ")" ::: "memory")
; #define PG8_WAIT_L(n) asm volatile("s_waitcnt lgkmcnt(" #n ")" ::: "memory")
; #define PG8_BAR __builtin_amdgcn_s_barrier()
; #define PG8_SCHED __builtin_amdgcn_sched_barrier(0)
; template <class Epi, class Sched, bool ALIGN_EPI = false, bool SP2 = false>
; __device__ __forceinline__ void gemm_phase(PG8_LAS unsigned char* lds, const Gemm g, const Sched& S, const Epi& E) {
;     ...
;             PG8_WAIT_V(8); PG8_WAIT_L(0); PG8_BAR; PG8_MMA(0, 0, At, B0); PG8_MMA(0, 1, At, B1); PG8_BAR; PG8_SCHED;
;             PG8_LDA(At, 0, 1); PG8_STAGE(PG8_SB(0, 0), b2, voffB); PG8_STAGE(PG8_SB(0, 1), b2 + hstep, voffB); PG8_STAGE(PG8_SA(0, 0), a2, voffA);
;             PG8_WAIT_V(8); PG8_WAIT_L(0); PG8_BAR; PG8_MMA(1, 0, At, B0); PG8_MMA(1, 1, At, B1); PG8_BAR; PG8_SCHED;
;             PG8_LDB(B0, 1, 0); PG8_LDB(B1, 1, 1); PG8_SCHED; PG8_LDA(At, 1, 0); PG8_STAGE(PG8_SA(0, 1), a2 + hstep, voffA);
;             PG8_WAIT_V(8); PG8_WAIT_L(0); PG8_BAR; PG8_MMA(0, 0, At, B0); PG8_MMA(0, 1, At, B1); PG8_BAR; PG8_SCHED;
	v_mfma_f32_16x16x32_bf16 v[60:63], v[128:131], v[200:203], v[60:63]
	v_mfma_f32_16x16x32_bf16 v[56:59], v[136:139], v[200:203], v[56:59]
	v_mfma_f32_16x16x32_bf16 v[44:47], v[128:131], v[208:211], v[44:47]
	v_mfma_f32_16x16x32_bf16 v[40:43], v[136:139], v[208:211], v[40:43]
	v_mfma_f32_16x16x32_bf16 v[28:31], v[128:131], v[216:219], v[28:31]
	v_mfma_f32_16x16x32_bf16 v[24:27], v[136:139], v[216:219], v[24:27]
	v_lshl_add_u64 v[238:239], s[74:75], 0, v[146:147]
	s_mov_b32 m0, s83
	s_nop 0
	global_load_lds_dwordx4 v[238:239], off
	v_mfma_f32_16x16x32_bf16 v[12:15], v[128:131], v[224:227], v[12:15]
	v_mfma_f32_16x16x32_bf16 v[8:11], v[136:139], v[224:227], v[8:11]
	v_mfma_f32_16x16x32_bf16 v[60:63], v[132:135], v[204:207], v[60:63]
	v_mfma_f32_16x16x32_bf16 v[56:59], v[164:167], v[204:207], v[56:59]
	v_mfma_f32_16x16x32_bf16 v[44:47], v[132:135], v[212:215], v[44:47]
	v_mfma_f32_16x16x32_bf16 v[40:43], v[164:167], v[212:215], v[40:43]
	v_mfma_f32_16x16x32_bf16 v[28:31], v[132:135], v[220:223], v[28:31]
	v_mfma_f32_16x16x32_bf16 v[24:27], v[164:167], v[220:223], v[24:27]
	v_mfma_f32_16x16x32_bf16 v[12:15], v[132:135], v[232:235], v[12:15]
	v_mfma_f32_16x16x32_bf16 v[8:11], v[164:167], v[232:235], v[8:11]
	s_setprio 0
	s_setprio 1
	v_mfma_f32_16x16x32_bf16 v[52:55], v[168:171], v[200:203], v[52:55]
	v_mfma_f32_16x16x32_bf16 v[48:51], v[176:179], v[200:203], v[48:51]
	v_mfma_f32_16x16x32_bf16 v[36:39], v[168:171], v[208:211], v[36:39]
	v_mfma_f32_16x16x32_bf16 v[32:35], v[176:179], v[208:211], v[32:35]
	v_mfma_f32_16x16x32_bf16 v[20:23], v[168:171], v[216:219], v[20:23]
	v_mfma_f32_16x16x32_bf16 v[16:19], v[176:179], v[216:219], v[16:19]
	s_mov_b32 m0, s84
	s_nop 0
	global_load_lds_dwordx4 v[240:241], off
	v_mfma_f32_16x16x32_bf16 v[4:7], v[168:171], v[224:227], v[4:7]
	v_mfma_f32_16x16x32_bf16 v[0:3], v[176:179], v[224:227], v[0:3]
	v_mfma_f32_16x16x32_bf16 v[52:55], v[172:175], v[204:207], v[52:55]
	v_mfma_f32_16x16x32_bf16 v[48:51], v[196:199], v[204:207], v[48:51]
	v_mfma_f32_16x16x32_bf16 v[36:39], v[172:175], v[212:215], v[36:39]
	v_mfma_f32_16x16x32_bf16 v[32:35], v[196:199], v[212:215], v[32:35]
	v_mfma_f32_16x16x32_bf16 v[20:23], v[172:175], v[220:223], v[20:23]
	v_mfma_f32_16x16x32_bf16 v[16:19], v[196:199], v[220:223], v[16:19]
	v_mfma_f32_16x16x32_bf16 v[4:7], v[172:175], v[232:235], v[4:7]
	v_mfma_f32_16x16x32_bf16 v[0:3], v[196:199], v[232:235], v[0:3]
	s_setprio 0
	s_barrier
	s_add_i32 s94, 0, 0x18000
	v_add_u32_e32 v148, s94, v181
	s_add_i32 vcc_lo, 0, 0x1c000
	ds_read_b128 v[128:131], v148
	ds_read_b128 v[132:135], v148 offset:1024
	ds_read_b128 v[136:139], v148 offset:2048
	ds_read_b128 v[164:167], v148 offset:3072
	v_add_u32_e32 v148, vcc_lo, v181
	ds_read_b128 v[168:171], v148
	ds_read_b128 v[172:175], v148 offset:1024
	ds_read_b128 v[176:179], v148 offset:2048
	ds_read_b128 v[196:199], v148 offset:3072
	s_add_u32 s74, s74, 0x40000
	s_addc_u32 s75, s75, 0
	s_mov_b32 m0, s85
	v_lshl_add_u64 v[242:243], s[74:75], 0, v[146:147]
	ds_read_b128 v[200:203], v188 offset:32768
	ds_read_b128 v[204:207], v188 offset:33792
	ds_read_b128 v[208:211], v188 offset:34816
	ds_read_b128 v[212:215], v188 offset:35840
	ds_read_b128 v[216:219], v188 offset:36864
	ds_read_b128 v[220:223], v188 offset:37888
	ds_read_b128 v[224:227], v188 offset:38912
	ds_read_b128 v[232:235], v188 offset:39936
	global_load_lds_dwordx4 v[242:243], off
	v_lshl_add_u64 v[242:243], s[74:75], 0, v[142:143]
	s_mov_b32 m0, s86
	s_nop 0
	global_load_lds_dwordx4 v[242:243], off
	s_waitcnt vmcnt(8)
	s_waitcnt lgkmcnt(0)
	s_setprio 1
	s_barrier
	v_mfma_f32_16x16x32_bf16 v[124:127], v[128:131], v[200:203], v[124:127]
	v_mfma_f32_16x16x32_bf16 v[120:123], v[136:139], v[200:203], v[120:123]
	v_mfma_f32_16x16x32_bf16 v[108:111], v[128:131], v[208:211], v[108:111]
	v_mfma_f32_16x16x32_bf16 v[104:107], v[136:139], v[208:211], v[104:107]
	v_mfma_f32_16x16x32_bf16 v[92:95], v[128:131], v[216:219], v[92:95]
	v_mfma_f32_16x16x32_bf16 v[88:91], v[136:139], v[216:219], v[88:91]
	v_mfma_f32_16x16x32_bf16 v[76:79], v[128:131], v[224:227], v[76:79]
	v_mfma_f32_16x16x32_bf16 v[72:75], v[136:139], v[224:227], v[72:75]
	v_mfma_f32_16x16x32_bf16 v[124:127], v[132:135], v[204:207], v[124:127]
	v_mfma_f32_16x16x32_bf16 v[120:123], v[164:167], v[204:207], v[120:123]
	v_mfma_f32_16x16x32_bf16 v[108:111], v[132:135], v[212:215], v[108:111]
	v_mfma_f32_16x16x32_bf16 v[104:107], v[164:167], v[212:215], v[104:107]
	v_mfma_f32_16x16x32_bf16 v[92:95], v[132:135], v[220:223], v[92:95]
	v_mfma_f32_16x16x32_bf16 v[88:91], v[164:167], v[220:223], v[88:91]
	v_mfma_f32_16x16x32_bf16 v[76:79], v[132:135], v[232:235], v[76:79]
	v_mfma_f32_16x16x32_bf16 v[72:75], v[164:167], v[232:235], v[72:75]
	s_setprio 0
	s_setprio 1
	v_mfma_f32_16x16x32_bf16 v[116:119], v[168:171], v[200:203], v[116:119]
	v_mfma_f32_16x16x32_bf16 v[112:115], v[176:179], v[200:203], v[112:115]
	v_mfma_f32_16x16x32_bf16 v[100:103], v[168:171], v[208:211], v[100:103]
	v_mfma_f32_16x16x32_bf16 v[96:99], v[176:179], v[208:211], v[96:99]
	v_mfma_f32_16x16x32_bf16 v[84:87], v[168:171], v[216:219], v[84:87]
	v_mfma_f32_16x16x32_bf16 v[80:83], v[176:179], v[216:219], v[80:83]
	v_mfma_f32_16x16x32_bf16 v[68:71], v[168:171], v[224:227], v[68:71]
	v_mfma_f32_16x16x32_bf16 v[64:67], v[176:179], v[224:227], v[64:67]
	v_mfma_f32_16x16x32_bf16 v[116:119], v[172:175], v[204:207], v[116:119]
	v_mfma_f32_16x16x32_bf16 v[112:115], v[196:199], v[204:207], v[112:115]
	v_mfma_f32_16x16x32_bf16 v[100:103], v[172:175], v[212:215], v[100:103]
	v_mfma_f32_16x16x32_bf16 v[96:99], v[196:199], v[212:215], v[96:99]
	v_mfma_f32_16x16x32_bf16 v[84:87], v[172:175], v[220:223], v[84:87]
	v_mfma_f32_16x16x32_bf16 v[80:83], v[196:199], v[220:223], v[80:83]
	v_mfma_f32_16x16x32_bf16 v[68:71], v[172:175], v[232:235], v[68:71]
	v_mfma_f32_16x16x32_bf16 v[64:67], v[196:199], v[232:235], v[64:67]
	s_setprio 0
	s_barrier
; #define PG8_STAGE(bufoff, gbase, voff) do { _Pragma("unroll") for (int _i = 0; _i < 2; ++_i) \
;         __builtin_amdgcn_global_load_lds((const unsigned*)((const char*)(gbase) + (voff)[_i]), (PG8_LAS unsigned*)(lds + (bufoff) + ldsw + _i * 8192), 16, 0, 0); } while (0)
; #define PG8_LDA(dst, b, h) do { _Pragma("unroll") for (int m = 0; m < 4; ++m) _Pragma("unroll") for (int k = 0; k < 2; ++k) dst[m][k] = *(const PG8_LAS bf16x8*)(lds + PG8_SA(b, h) + aoff + m * 2048 + k * 1024); } while (0)
; #define PG8_MMA(ai, bj, At, Bt) do { __builtin_amdgcn_s_setprio(1); _Pragma("unroll") for (int m = 0; m < 4; ++m) _Pragma("unroll") for (int n = 0; n < 2; ++n) _Pragma("unroll") for (int k = 0; k < 2; ++k) \
;         acc[ai][bj][m][n] = __builtin_amdgcn_mfma_f32_16x16x32_bf16(Bt[n][k], At[m][k], acc[ai][bj][m][n], 0, 0, 0); __builtin_amdgcn_s_setprio(0); } while (0)
; #define PG8_WAIT_V(n) asm volatile("s_waitcnt vmcnt(" #n ")" ::: "memory")
; #define PG8_WAIT_L(n) asm volatile("s_waitcnt lgkmcnt(" #n ")" ::: "memory")
; #define PG8_BAR __builtin_amdgcn_s_barrier()
; #define PG8_SCHED __builtin_amdgcn_sched_barrier(0)
; template <class Epi, class Sched, bool ALIGN_EPI = false, bool SP2 = false>
; __device__ __forceinline__ void gemm_phase(PG8_LAS unsigned char* lds, const Gemm g, const Sched& S, const Epi& E) {
;     ...
;             PG8_WAIT_V(8); PG8_WAIT_L(0); PG8_BAR; PG8_MMA(0, 0, At, B0); PG8_MMA(0, 1, At, B1); PG8_BAR; PG8_SCHED;
;             PG8_LDA(At, 1, 1); PG8_STAGE(PG8_SB(1, 0), b3, voffB); PG8_STAGE(PG8_SB(1, 1), b3 + hstep, voffB); PG8_STAGE(PG8_SA(1, 0), a3, voffA);
;             PG8_WAIT_V(8); PG8_WAIT_L(0); PG8_BAR; PG8_MMA(1, 0, At, B0); PG8_MMA(1, 1, At, B1); PG8_BAR; PG8_SCHED;
;     ...
;         }
;         if constexpr (ALIGN_EPI) { if (wr == 0) PG8_BAR; }
	s_add_i32 s74, s94, s80
	v_lshl_add_u64 v[228:229], v[228:229], 0, s[22:23]
	s_mov_b32 m0, s74
	ds_read_b128 v[200:203], v188 offset:49152
	ds_read_b128 v[204:207], v188 offset:50176
	ds_read_b128 v[208:211], v188 offset:51200
	ds_read_b128 v[212:215], v188 offset:52224
	ds_read_b128 v[216:219], v188 offset:53248
	ds_read_b128 v[220:223], v188 offset:54272
	ds_read_b128 v[224:227], v188 offset:55296
	ds_read_b128 v[232:235], v188 offset:56320
	global_load_lds_dwordx4 v[228:229], off
	s_add_i32 m0, s74, 0x2000
	s_add_u32 s48, s48, 0x40080
	v_lshl_add_u64 v[228:229], v[236:237], 0, s[22:23]
	s_addc_u32 s49, s49, 0
	s_add_i32 s74, vcc_lo, s80
	global_load_lds_dwordx4 v[228:229], off
	v_lshl_add_u64 v[228:229], s[48:49], 0, v[144:145]
	s_mov_b32 m0, s74
	s_nop 0
	global_load_lds_dwordx4 v[228:229], off
	v_lshl_add_u64 v[228:229], s[48:49], 0, v[140:141]
	s_add_i32 m0, s74, 0x2000
	s_nop 0
	global_load_lds_dwordx4 v[228:229], off
	s_waitcnt vmcnt(6)
	s_waitcnt lgkmcnt(0)
	s_setprio 1
	s_barrier
	v_mfma_f32_16x16x32_bf16 v[60:63], v[128:131], v[200:203], v[60:63]
	v_mfma_f32_16x16x32_bf16 v[56:59], v[136:139], v[200:203], v[56:59]
	v_mfma_f32_16x16x32_bf16 v[44:47], v[128:131], v[208:211], v[44:47]
	v_mfma_f32_16x16x32_bf16 v[40:43], v[136:139], v[208:211], v[40:43]
	v_mfma_f32_16x16x32_bf16 v[28:31], v[128:131], v[216:219], v[28:31]
	v_mfma_f32_16x16x32_bf16 v[24:27], v[136:139], v[216:219], v[24:27]
	v_lshl_add_u64 v[228:229], v[238:239], 0, s[22:23]
	s_mov_b32 m0, s89
	s_nop 0
	global_load_lds_dwordx4 v[228:229], off
	v_mfma_f32_16x16x32_bf16 v[12:15], v[128:131], v[224:227], v[12:15]
	v_mfma_f32_16x16x32_bf16 v[8:11], v[136:139], v[224:227], v[8:11]
	v_mfma_f32_16x16x32_bf16 v[60:63], v[132:135], v[204:207], v[60:63]
	v_mfma_f32_16x16x32_bf16 v[56:59], v[164:167], v[204:207], v[56:59]
	v_mfma_f32_16x16x32_bf16 v[44:47], v[132:135], v[212:215], v[44:47]
	v_mfma_f32_16x16x32_bf16 v[40:43], v[164:167], v[212:215], v[40:43]
	v_mfma_f32_16x16x32_bf16 v[28:31], v[132:135], v[220:223], v[28:31]
	v_mfma_f32_16x16x32_bf16 v[24:27], v[164:167], v[220:223], v[24:27]
	v_mfma_f32_16x16x32_bf16 v[12:15], v[132:135], v[232:235], v[12:15]
	v_mfma_f32_16x16x32_bf16 v[8:11], v[164:167], v[232:235], v[8:11]
	s_setprio 0
	s_setprio 1
	v_mfma_f32_16x16x32_bf16 v[52:55], v[168:171], v[200:203], v[52:55]
	v_mfma_f32_16x16x32_bf16 v[48:51], v[176:179], v[200:203], v[48:51]
	v_mfma_f32_16x16x32_bf16 v[36:39], v[168:171], v[208:211], v[36:39]
	v_mfma_f32_16x16x32_bf16 v[32:35], v[176:179], v[208:211], v[32:35]
	v_mfma_f32_16x16x32_bf16 v[20:23], v[168:171], v[216:219], v[20:23]
	v_mfma_f32_16x16x32_bf16 v[16:19], v[176:179], v[216:219], v[16:19]
	v_lshl_add_u64 v[228:229], v[240:241], 0, s[22:23]
	s_mov_b32 m0, s90
	s_nop 0
	global_load_lds_dwordx4 v[228:229], off
	v_mfma_f32_16x16x32_bf16 v[4:7], v[168:171], v[224:227], v[4:7]
	v_mfma_f32_16x16x32_bf16 v[0:3], v[176:179], v[224:227], v[0:3]
	v_mfma_f32_16x16x32_bf16 v[52:55], v[172:175], v[204:207], v[52:55]
	v_mfma_f32_16x16x32_bf16 v[48:51], v[196:199], v[204:207], v[48:51]
	v_mfma_f32_16x16x32_bf16 v[36:39], v[172:175], v[212:215], v[36:39]
	v_mfma_f32_16x16x32_bf16 v[32:35], v[196:199], v[212:215], v[32:35]
	v_mfma_f32_16x16x32_bf16 v[20:23], v[172:175], v[220:223], v[20:23]
	v_mfma_f32_16x16x32_bf16 v[16:19], v[196:199], v[220:223], v[16:19]
	v_mfma_f32_16x16x32_bf16 v[4:7], v[172:175], v[232:235], v[4:7]
	v_mfma_f32_16x16x32_bf16 v[0:3], v[196:199], v[232:235], v[0:3]
	s_setprio 0
	s_barrier
	s_add_i32 s79, s79, 2
	s_add_u32 s6, s6, 0x100
	s_addc_u32 s7, s7, 0
	s_add_u32 s77, s77, 0x100
	s_addc_u32 s78, s78, 0
	s_cmp_gt_u32 s79, 13
	s_cbranch_scc0 .LBB0_348
	s_and_b64 vcc, exec, s[24:25]
	s_cbranch_vccz .LBB0_351
	s_barrier

; #define PG8_STAGE(bufoff, gbase, voff) do { _Pragma("unroll") for (int _i = 0; _i < 2; ++_i) \
;         __builtin_amdgcn_global_load_lds((const unsigned*)((const char*)(gbase) + (voff)[_i]), (PG8_LAS unsigned*)(lds + (bufoff) + ldsw + _i * 8192), 16, 0, 0); } while (0)
; #define PG8_LDA(dst, b, h) do { _Pragma("unroll") for (int m = 0; m < 4; ++m) _Pragma("unroll") for (int k = 0; k < 2; ++k) dst[m][k] = *(const PG8_LAS bf16x8*)(lds + PG8_SA(b, h) + aoff + m * 2048 + k * 1024); } while (0)
; #define PG8_LDB(dst, b, h) do { _Pragma("unroll") for (int n = 0; n < 2; ++n) _Pragma("unroll") for (int k = 0; k < 2; ++k) dst[n][k] = *(const PG8_LAS bf16x8*)(lds + PG8_SB(b, h) + boff + n * 2048 + k * 1024); } while (0)
; #define PG8_MMA(ai, bj, At, Bt) do { __builtin_amdgcn_s_setprio(1); _Pragma("unroll") for (int m = 0; m < 4; ++m) _Pragma("unroll") for (int n = 0; n < 2; ++n) _Pragma("unroll") for (int k = 0; k < 2; ++k) \
;         acc[ai][bj][m][n] = __builtin_amdgcn_mfma_f32_16x16x32_bf16(Bt[n][k], At[m][k], acc[ai][bj][m][n], 0, 0, 0); __builtin_amdgcn_s_setprio(0); } while (0)
; #define PG8_WAIT_V(n) asm volatile("s_waitcnt vmcnt(" #n ")" ::: "memory")
; #define PG8_BAR __builtin_amdgcn_s_barrier()
; template <class Epi, class Sched, bool ALIGN_EPI = false, bool SP2 = false>
; __device__ __forceinline__ void gemm_phase(PG8_LAS unsigned char* lds, const Gemm g, const Sched& S, const Epi& E) {
;     ...
;         for (int t = 0; t < nt; t += 2) {
;             const bool last = (t == nt - 2);
;             const char* a1 = cA + (size_t)(t + 1) * kstep;
;             const char* a2 = last ? nA : cA + (size_t)(t + 2) * kstep; const char* b2 = last ? nB : cB + (size_t)(t + 2) * kstep;
;             const char* a3 = a2 + kstep; const char* b3 = b2 + kstep;
;             if (last && has_next) S.a_ready(nxt);
;             if constexpr (SP2) {
;             PG8_LDB(B0, 0, 0); PG8_LDB(B1, 0, 1); PG8_SCHED; PG8_LDA(At, 0, 0); PG8_STAGE(PG8_SA(1, 1), a1 + hstep, voffA);
;             PG8_WAIT_V(8); PG8_WAIT_L(0); PG8_BAR; PG8_MMA(0, 0, At, B0); PG8_MMA(0, 1, At, B1); PG8_BAR; PG8_SCHED;
;             PG8_LDA(At, 0, 1); PG8_STAGE(PG8_SB(0, 0), b2, voffB); PG8_STAGE(PG8_SB(0, 1), b2 + hstep, voffB); PG8_STAGE(PG8_SA(0, 0), a2, voffA);
;             PG8_WAIT_V(8); PG8_WAIT_L(0); PG8_BAR; PG8_MMA(1, 0, At, B0); PG8_MMA(1, 1, At, B1); PG8_BAR; PG8_SCHED;
.LBB0_735:
	ds_read_b128 v[144:147], v159
	ds_read_b128 v[162:165], v159 offset:1024
	ds_read_b128 v[166:169], v159 offset:2048
	ds_read_b128 v[170:173], v159 offset:3072
	ds_read_b128 v[174:177], v160
	ds_read_b128 v[178:181], v160 offset:1024
	ds_read_b128 v[182:185], v160 offset:2048
	ds_read_b128 v[186:189], v160 offset:3072
	s_add_u32 s44, s42, 0xfffe0080
	s_addc_u32 s45, s43, -1
	s_cmp_eq_u32 s86, 4
	s_cselect_b32 s47, s27, s45
	s_cselect_b32 s46, s82, s44
	s_cselect_b32 s45, s25, s85
	s_cselect_b32 s44, s83, s84
	v_lshl_add_u64 v[222:223], s[42:43], 0, v[136:137]
	s_add_i32 m0, s41, 0xc000
	ds_read_b128 v[190:193], v161
	ds_read_b128 v[194:197], v161 offset:1024
	ds_read_b128 v[198:201], v161 offset:2048
	ds_read_b128 v[202:205], v161 offset:3072
	ds_read_b128 v[206:209], v161 offset:4096
	ds_read_b128 v[210:213], v161 offset:5120
	ds_read_b128 v[214:217], v161 offset:6144
	ds_read_b128 v[218:221], v161 offset:7168
	global_load_lds_dwordx4 v[222:223], off
	v_lshl_add_u64 v[222:223], s[42:43], 0, v[138:139]
	s_add_i32 m0, s41, 0xe000
	s_nop 0
	global_load_lds_dwordx4 v[222:223], off
	s_waitcnt vmcnt(8)
	s_waitcnt lgkmcnt(0)
	s_setprio 1
	s_barrier
	v_mfma_f32_16x16x32_bf16 v[124:127], v[144:147], v[190:193], v[124:127]
	v_mfma_f32_16x16x32_bf16 v[120:123], v[166:169], v[190:193], v[120:123]
	v_mfma_f32_16x16x32_bf16 v[112:115], v[144:147], v[198:201], v[112:115]
	v_mfma_f32_16x16x32_bf16 v[104:107], v[166:169], v[198:201], v[104:107]
	v_mfma_f32_16x16x32_bf16 v[92:95], v[144:147], v[206:209], v[92:95]
	v_mfma_f32_16x16x32_bf16 v[88:91], v[166:169], v[206:209], v[88:91]
	v_mfma_f32_16x16x32_bf16 v[84:87], v[144:147], v[214:217], v[84:87]
	v_mfma_f32_16x16x32_bf16 v[80:83], v[166:169], v[214:217], v[80:83]
	v_mfma_f32_16x16x32_bf16 v[124:127], v[162:165], v[194:197], v[124:127]
	v_mfma_f32_16x16x32_bf16 v[120:123], v[170:173], v[194:197], v[120:123]
	v_mfma_f32_16x16x32_bf16 v[112:115], v[162:165], v[202:205], v[112:115]
	v_mfma_f32_16x16x32_bf16 v[104:107], v[170:173], v[202:205], v[104:107]
	v_mfma_f32_16x16x32_bf16 v[92:95], v[162:165], v[210:213], v[92:95]
	v_mfma_f32_16x16x32_bf16 v[88:91], v[170:173], v[210:213], v[88:91]
	v_mfma_f32_16x16x32_bf16 v[84:87], v[162:165], v[218:221], v[84:87]
	v_mfma_f32_16x16x32_bf16 v[80:83], v[170:173], v[218:221], v[80:83]
	s_setprio 0
	s_setprio 1
	v_mfma_f32_16x16x32_bf16 v[116:119], v[174:177], v[190:193], v[116:119]
	v_mfma_f32_16x16x32_bf16 v[108:111], v[182:185], v[190:193], v[108:111]
	v_mfma_f32_16x16x32_bf16 v[100:103], v[174:177], v[198:201], v[100:103]
	v_mfma_f32_16x16x32_bf16 v[96:99], v[182:185], v[198:201], v[96:99]
	v_mfma_f32_16x16x32_bf16 v[76:79], v[174:177], v[206:209], v[76:79]
	v_mfma_f32_16x16x32_bf16 v[72:75], v[182:185], v[206:209], v[72:75]
	v_mfma_f32_16x16x32_bf16 v[68:71], v[174:177], v[214:217], v[68:71]
	v_mfma_f32_16x16x32_bf16 v[64:67], v[182:185], v[214:217], v[64:67]
	v_mfma_f32_16x16x32_bf16 v[116:119], v[178:181], v[194:197], v[116:119]
	v_mfma_f32_16x16x32_bf16 v[108:111], v[186:189], v[194:197], v[108:111]
	v_mfma_f32_16x16x32_bf16 v[100:103], v[178:181], v[202:205], v[100:103]
	v_mfma_f32_16x16x32_bf16 v[96:99], v[186:189], v[202:205], v[96:99]
	v_mfma_f32_16x16x32_bf16 v[76:79], v[178:181], v[210:213], v[76:79]
	v_mfma_f32_16x16x32_bf16 v[72:75], v[186:189], v[210:213], v[72:75]
	v_mfma_f32_16x16x32_bf16 v[68:71], v[178:181], v[218:221], v[68:71]
	v_mfma_f32_16x16x32_bf16 v[64:67], v[186:189], v[218:221], v[64:67]
	s_setprio 0
	s_barrier
	s_add_i32 s87, s75, s49
	v_lshl_add_u64 v[222:223], s[44:45], 0, v[130:131]
	s_mov_b32 m0, s87
	ds_read_b128 v[190:193], v161 offset:16384
	ds_read_b128 v[194:197], v161 offset:17408
	ds_read_b128 v[198:201], v161 offset:18432
	ds_read_b128 v[202:205], v161 offset:19456
	ds_read_b128 v[206:209], v161 offset:20480
	ds_read_b128 v[210:213], v161 offset:21504
	ds_read_b128 v[214:217], v161 offset:22528
	ds_read_b128 v[218:221], v161 offset:23552
	global_load_lds_dwordx4 v[222:223], off
	s_add_i32 m0, s87, 0x2000
	s_add_u32 s88, s44, 0x20000
	v_lshl_add_u64 v[224:225], s[44:45], 0, v[134:135]
	s_addc_u32 s89, s45, 0
	s_add_i32 s87, s76, s49
	global_load_lds_dwordx4 v[224:225], off
	v_lshl_add_u64 v[226:227], s[88:89], 0, v[130:131]
	s_mov_b32 m0, s87
	v_lshl_add_u64 v[228:229], s[46:47], 0, v[132:133]
	global_load_lds_dwordx4 v[226:227], off
	v_lshl_add_u64 v[226:227], s[88:89], 0, v[134:135]
	s_add_i32 m0, s87, 0x2000
	s_nop 0
	global_load_lds_dwordx4 v[226:227], off
	s_waitcnt vmcnt(6)
	s_waitcnt lgkmcnt(0)
	s_setprio 1
	s_barrier
; #define PG8_STAGE(bufoff, gbase, voff) do { _Pragma("unroll") for (int _i = 0; _i < 2; ++_i) \
;         __builtin_amdgcn_global_load_lds((const unsigned*)((const char*)(gbase) + (voff)[_i]), (PG8_LAS unsigned*)(lds + (bufoff) + ldsw + _i * 8192), 16, 0, 0); } while (0)
; #define PG8_LDA(dst, b, h) do { _Pragma("unroll") for (int m = 0; m < 4; ++m) _Pragma("unroll") for (int k = 0; k < 2; ++k) dst[m][k] = *(const PG8_LAS bf16x8*)(lds + PG8_SA(b, h) + aoff + m * 2048 + k * 1024); } while (0)
; #define PG8_LDB(dst, b, h) do { _Pragma("unroll") for (int n = 0; n < 2; ++n) _Pragma("unroll") for (int k = 0; k < 2; ++k) dst[n][k] = *(const PG8_LAS bf16x8*)(lds + PG8_SB(b, h) + boff + n * 2048 + k * 1024); } while (0)
; #define PG8_MMA(ai, bj, At, Bt) do { __builtin_amdgcn_s_setprio(1); _Pragma("unroll") for (int m = 0; m < 4; ++m) _Pragma("unroll") for (int n = 0; n < 2; ++n) _Pragma("unroll") for (int k = 0; k < 2; ++k) \
;         acc[ai][bj][m][n] = __builtin_amdgcn_mfma_f32_16x16x32_bf16(Bt[n][k], At[m][k], acc[ai][bj][m][n], 0, 0, 0); __builtin_amdgcn_s_setprio(0); } while (0)
; #define PG8_WAIT_V(n) asm volatile("s_waitcnt vmcnt(" #n ")" ::: "memory")
; #define PG8_WAIT_L(n) asm volatile("s_waitcnt lgkmcnt(" #n ")" ::: "memory")
; #define PG8_BAR __builtin_amdgcn_s_barrier()
; #define PG8_SCHED __builtin_amdgcn_sched_barrier(0)
; template <class Epi, class Sched, bool ALIGN_EPI = false, bool SP2 = false>
; __device__ __forceinline__ void gemm_phase(PG8_LAS unsigned char* lds, const Gemm g, const Sched& S, const Epi& E) {
;     ...
;             PG8_WAIT_V(8); PG8_WAIT_L(0); PG8_BAR; PG8_MMA(0, 0, At, B0); PG8_MMA(0, 1, At, B1); PG8_BAR; PG8_SCHED;
;             PG8_LDA(At, 0, 1); PG8_STAGE(PG8_SB(0, 0), b2, voffB); PG8_STAGE(PG8_SB(0, 1), b2 + hstep, voffB); PG8_STAGE(PG8_SA(0, 0), a2, voffA);
;             PG8_WAIT_V(8); PG8_WAIT_L(0); PG8_BAR; PG8_MMA(1, 0, At, B0); PG8_MMA(1, 1, At, B1); PG8_BAR; PG8_SCHED;
;             PG8_LDB(B0, 1, 0); PG8_LDB(B1, 1, 1); PG8_SCHED; PG8_LDA(At, 1, 0); PG8_STAGE(PG8_SA(0, 1), a2 + hstep, voffA);
;             PG8_WAIT_V(8); PG8_WAIT_L(0); PG8_BAR; PG8_MMA(0, 0, At, B0); PG8_MMA(0, 1, At, B1); PG8_BAR; PG8_SCHED;
	v_mfma_f32_16x16x32_bf16 v[60:63], v[144:147], v[190:193], v[60:63]
	v_mfma_f32_16x16x32_bf16 v[56:59], v[166:169], v[190:193], v[56:59]
	v_mfma_f32_16x16x32_bf16 v[52:55], v[144:147], v[198:201], v[52:55]
	v_mfma_f32_16x16x32_bf16 v[48:51], v[166:169], v[198:201], v[48:51]
	v_mfma_f32_16x16x32_bf16 v[28:31], v[144:147], v[206:209], v[28:31]
	v_mfma_f32_16x16x32_bf16 v[24:27], v[166:169], v[206:209], v[24:27]
	v_lshl_add_u64 v[226:227], s[46:47], 0, v[128:129]
	s_mov_b32 m0, s41
	s_nop 0
	global_load_lds_dwordx4 v[226:227], off
	v_mfma_f32_16x16x32_bf16 v[20:23], v[144:147], v[214:217], v[20:23]
	v_mfma_f32_16x16x32_bf16 v[16:19], v[166:169], v[214:217], v[16:19]
	v_mfma_f32_16x16x32_bf16 v[60:63], v[162:165], v[194:197], v[60:63]
	v_mfma_f32_16x16x32_bf16 v[56:59], v[170:173], v[194:197], v[56:59]
	v_mfma_f32_16x16x32_bf16 v[52:55], v[162:165], v[202:205], v[52:55]
	v_mfma_f32_16x16x32_bf16 v[48:51], v[170:173], v[202:205], v[48:51]
	v_mfma_f32_16x16x32_bf16 v[28:31], v[162:165], v[210:213], v[28:31]
	v_mfma_f32_16x16x32_bf16 v[24:27], v[170:173], v[210:213], v[24:27]
	v_mfma_f32_16x16x32_bf16 v[20:23], v[162:165], v[218:221], v[20:23]
	v_mfma_f32_16x16x32_bf16 v[16:19], v[170:173], v[218:221], v[16:19]
	s_setprio 0
	s_setprio 1
	v_mfma_f32_16x16x32_bf16 v[44:47], v[174:177], v[190:193], v[44:47]
	v_mfma_f32_16x16x32_bf16 v[40:43], v[182:185], v[190:193], v[40:43]
	v_mfma_f32_16x16x32_bf16 v[36:39], v[174:177], v[198:201], v[36:39]
	v_mfma_f32_16x16x32_bf16 v[32:35], v[182:185], v[198:201], v[32:35]
	v_mfma_f32_16x16x32_bf16 v[12:15], v[174:177], v[206:209], v[12:15]
	v_mfma_f32_16x16x32_bf16 v[8:11], v[182:185], v[206:209], v[8:11]
	s_mov_b32 m0, s51
	s_nop 0
	global_load_lds_dwordx4 v[228:229], off
	v_mfma_f32_16x16x32_bf16 v[4:7], v[174:177], v[214:217], v[4:7]
	v_mfma_f32_16x16x32_bf16 v[0:3], v[182:185], v[214:217], v[0:3]
	v_mfma_f32_16x16x32_bf16 v[44:47], v[178:181], v[194:197], v[44:47]
	v_mfma_f32_16x16x32_bf16 v[40:43], v[186:189], v[194:197], v[40:43]
	v_mfma_f32_16x16x32_bf16 v[36:39], v[178:181], v[202:205], v[36:39]
	v_mfma_f32_16x16x32_bf16 v[32:35], v[186:189], v[202:205], v[32:35]
	v_mfma_f32_16x16x32_bf16 v[12:15], v[178:181], v[210:213], v[12:15]
	v_mfma_f32_16x16x32_bf16 v[8:11], v[186:189], v[210:213], v[8:11]
	v_mfma_f32_16x16x32_bf16 v[4:7], v[178:181], v[218:221], v[4:7]
	v_mfma_f32_16x16x32_bf16 v[0:3], v[186:189], v[218:221], v[0:3]
	s_setprio 0
	s_barrier
	s_add_i32 s87, 0, 0x18000
	s_add_i32 s88, 0, 0x1c000
	v_add_u32_e32 v170, s87, v157
	v_add_u32_e32 v186, s88, v157
	ds_read_b128 v[144:147], v170
	ds_read_b128 v[162:165], v170 offset:1024
	ds_read_b128 v[166:169], v170 offset:2048
	ds_read_b128 v[170:173], v170 offset:3072
	ds_read_b128 v[174:177], v186
	ds_read_b128 v[178:181], v186 offset:1024
	ds_read_b128 v[182:185], v186 offset:2048
	ds_read_b128 v[186:189], v186 offset:3072
	s_add_u32 s46, s46, 0x20000
	s_addc_u32 s47, s47, 0
	s_mov_b32 m0, s52
	v_lshl_add_u64 v[232:233], s[46:47], 0, v[128:129]
	ds_read_b128 v[190:193], v161 offset:32768
	ds_read_b128 v[194:197], v161 offset:33792
	ds_read_b128 v[198:201], v161 offset:34816
	ds_read_b128 v[202:205], v161 offset:35840
	ds_read_b128 v[206:209], v161 offset:36864
	ds_read_b128 v[210:213], v161 offset:37888
	ds_read_b128 v[214:217], v161 offset:38912
	ds_read_b128 v[218:221], v161 offset:39936
	global_load_lds_dwordx4 v[232:233], off
	v_lshl_add_u64 v[232:233], s[46:47], 0, v[132:133]
	s_mov_b32 m0, s53
	s_nop 0
	global_load_lds_dwordx4 v[232:233], off
	s_waitcnt vmcnt(8)
	s_waitcnt lgkmcnt(0)
	s_setprio 1
	s_barrier
	v_mfma_f32_16x16x32_bf16 v[124:127], v[144:147], v[190:193], v[124:127]
	v_mfma_f32_16x16x32_bf16 v[120:123], v[166:169], v[190:193], v[120:123]
	v_mfma_f32_16x16x32_bf16 v[112:115], v[144:147], v[198:201], v[112:115]
	v_mfma_f32_16x16x32_bf16 v[104:107], v[166:169], v[198:201], v[104:107]
	v_mfma_f32_16x16x32_bf16 v[92:95], v[144:147], v[206:209], v[92:95]
	v_mfma_f32_16x16x32_bf16 v[88:91], v[166:169], v[206:209], v[88:91]
	v_mfma_f32_16x16x32_bf16 v[84:87], v[144:147], v[214:217], v[84:87]
	v_mfma_f32_16x16x32_bf16 v[80:83], v[166:169], v[214:217], v[80:83]
	v_mfma_f32_16x16x32_bf16 v[124:127], v[162:165], v[194:197], v[124:127]
	v_mfma_f32_16x16x32_bf16 v[120:123], v[170:173], v[194:197], v[120:123]
	v_mfma_f32_16x16x32_bf16 v[112:115], v[162:165], v[202:205], v[112:115]
	v_mfma_f32_16x16x32_bf16 v[104:107], v[170:173], v[202:205], v[104:107]
	v_mfma_f32_16x16x32_bf16 v[92:95], v[162:165], v[210:213], v[92:95]
	v_mfma_f32_16x16x32_bf16 v[88:91], v[170:173], v[210:213], v[88:91]
	v_mfma_f32_16x16x32_bf16 v[84:87], v[162:165], v[218:221], v[84:87]
	v_mfma_f32_16x16x32_bf16 v[80:83], v[170:173], v[218:221], v[80:83]
	s_setprio 0
	s_setprio 1
	v_mfma_f32_16x16x32_bf16 v[116:119], v[174:177], v[190:193], v[116:119]
	v_mfma_f32_16x16x32_bf16 v[108:111], v[182:185], v[190:193], v[108:111]
	v_mfma_f32_16x16x32_bf16 v[100:103], v[174:177], v[198:201], v[100:103]
	v_mfma_f32_16x16x32_bf16 v[96:99], v[182:185], v[198:201], v[96:99]
	v_mfma_f32_16x16x32_bf16 v[76:79], v[174:177], v[206:209], v[76:79]
	v_mfma_f32_16x16x32_bf16 v[72:75], v[182:185], v[206:209], v[72:75]
	v_mfma_f32_16x16x32_bf16 v[68:71], v[174:177], v[214:217], v[68:71]
	v_mfma_f32_16x16x32_bf16 v[64:67], v[182:185], v[214:217], v[64:67]
	v_mfma_f32_16x16x32_bf16 v[116:119], v[178:181], v[194:197], v[116:119]
	v_mfma_f32_16x16x32_bf16 v[108:111], v[186:189], v[194:197], v[108:111]
	v_mfma_f32_16x16x32_bf16 v[100:103], v[178:181], v[202:205], v[100:103]
	v_mfma_f32_16x16x32_bf16 v[96:99], v[186:189], v[202:205], v[96:99]
	v_mfma_f32_16x16x32_bf16 v[76:79], v[178:181], v[210:213], v[76:79]
	v_mfma_f32_16x16x32_bf16 v[72:75], v[186:189], v[210:213], v[72:75]
	v_mfma_f32_16x16x32_bf16 v[68:71], v[178:181], v[218:221], v[68:71]
	v_mfma_f32_16x16x32_bf16 v[64:67], v[186:189], v[218:221], v[64:67]
	s_setprio 0
	s_barrier
; #define PG8_STAGE(bufoff, gbase, voff) do { _Pragma("unroll") for (int _i = 0; _i < 2; ++_i) \
;         __builtin_amdgcn_global_load_lds((const unsigned*)((const char*)(gbase) + (voff)[_i]), (PG8_LAS unsigned*)(lds + (bufoff) + ldsw + _i * 8192), 16, 0, 0); } while (0)
; #define PG8_LDA(dst, b, h) do { _Pragma("unroll") for (int m = 0; m < 4; ++m) _Pragma("unroll") for (int k = 0; k < 2; ++k) dst[m][k] = *(const PG8_LAS bf16x8*)(lds + PG8_SA(b, h) + aoff + m * 2048 + k * 1024); } while (0)
; #define PG8_MMA(ai, bj, At, Bt) do { __builtin_amdgcn_s_setprio(1); _Pragma("unroll") for (int m = 0; m < 4; ++m) _Pragma("unroll") for (int n = 0; n < 2; ++n) _Pragma("unroll") for (int k = 0; k < 2; ++k) \
;         acc[ai][bj][m][n] = __builtin_amdgcn_mfma_f32_16x16x32_bf16(Bt[n][k], At[m][k], acc[ai][bj][m][n], 0, 0, 0); __builtin_amdgcn_s_setprio(0); } while (0)
;     __device__ __forceinline__ void operator()(const f32x4 (&acc)[2][2][4][2], const Unit& u, int wr, int wc, int fr, int fq) const {
;         const int row0 = u.pm * BM + wr * 64 + fr, col0 = u.pn * BM + wc * 32 + 8 * fq;
;         const bf16_t* const G = (const bf16_t*)(ws + (ADD ? WS_GB : WS_GA)); bf16_t* const Mg = (bf16_t*)(ws + WS_GA);
; #pragma unroll
;         for (int ai = 0; ai < 2; ++ai)
; #pragma unroll
;         for (int mh = 0; mh < 4; mh += 2) {
;             u32x2 pg[4][2][2], pm_[4][2][2];
; #pragma unroll
;             for (int m = mh; m < mh + 2; ++m)
; #pragma unroll
;                 for (int bj = 0; bj < 2; ++bj)
; #pragma unroll
;                     for (int n = 0; n < 2; ++n) { const size_t off = (size_t)(row0 + ai * HALF + m * 16) * 1024 + col0 + bj * HALF + n * 4;
;                         pg[m][bj][n] = *(const u32x2*)(G + off); if (ADD) pm_[m][bj][n] = *(const u32x2*)(Mg + off); }
; template <class Epi, class Sched, bool ALIGN_EPI = false, bool SP2 = false>
; __device__ __forceinline__ void gemm_phase(PG8_LAS unsigned char* lds, const Gemm g, const Sched& S, const Epi& E) {
;     ...
;             PG8_WAIT_V(8); PG8_WAIT_L(0); PG8_BAR; PG8_MMA(0, 0, At, B0); PG8_MMA(0, 1, At, B1); PG8_BAR; PG8_SCHED;
;             PG8_LDA(At, 1, 1); PG8_STAGE(PG8_SB(1, 0), b3, voffB); PG8_STAGE(PG8_SB(1, 1), b3 + hstep, voffB); PG8_STAGE(PG8_SA(1, 0), a3, voffA);
;             PG8_WAIT_V(8); PG8_WAIT_L(0); PG8_BAR; PG8_MMA(1, 0, At, B0); PG8_MMA(1, 1, At, B1); PG8_BAR; PG8_SCHED;
	s_add_i32 s46, s87, s49
	v_lshl_add_u64 v[222:223], v[222:223], 0, s[6:7]
	s_mov_b32 m0, s46
	ds_read_b128 v[190:193], v161 offset:49152
	ds_read_b128 v[194:197], v161 offset:50176
	ds_read_b128 v[198:201], v161 offset:51200
	ds_read_b128 v[202:205], v161 offset:52224
	ds_read_b128 v[206:209], v161 offset:53248
	ds_read_b128 v[210:213], v161 offset:54272
	ds_read_b128 v[214:217], v161 offset:55296
	ds_read_b128 v[218:221], v161 offset:56320
	global_load_lds_dwordx4 v[222:223], off
	s_add_i32 m0, s46, 0x2000
	s_add_u32 s44, s44, 0x20080
	v_lshl_add_u64 v[222:223], v[224:225], 0, s[6:7]
	s_addc_u32 s45, s45, 0
	s_add_i32 s46, s88, s49
	global_load_lds_dwordx4 v[222:223], off
	v_lshl_add_u64 v[222:223], s[44:45], 0, v[130:131]
	s_mov_b32 m0, s46
	s_nop 0
	global_load_lds_dwordx4 v[222:223], off
	v_lshl_add_u64 v[222:223], s[44:45], 0, v[134:135]
	s_add_i32 m0, s46, 0x2000
	s_nop 0
	global_load_lds_dwordx4 v[222:223], off
	s_waitcnt vmcnt(6)
	s_waitcnt lgkmcnt(0)
	s_setprio 1
	s_barrier
	v_mfma_f32_16x16x32_bf16 v[60:63], v[144:147], v[190:193], v[60:63]
	v_mfma_f32_16x16x32_bf16 v[56:59], v[166:169], v[190:193], v[56:59]
	v_mfma_f32_16x16x32_bf16 v[52:55], v[144:147], v[198:201], v[52:55]
	v_mfma_f32_16x16x32_bf16 v[48:51], v[166:169], v[198:201], v[48:51]
	v_mfma_f32_16x16x32_bf16 v[28:31], v[144:147], v[206:209], v[28:31]
	v_mfma_f32_16x16x32_bf16 v[24:27], v[166:169], v[206:209], v[24:27]
	v_lshl_add_u64 v[222:223], v[226:227], 0, s[6:7]
	s_mov_b32 m0, s61
	s_nop 0
	global_load_lds_dwordx4 v[222:223], off
	v_mfma_f32_16x16x32_bf16 v[20:23], v[144:147], v[214:217], v[20:23]
	v_mfma_f32_16x16x32_bf16 v[16:19], v[166:169], v[214:217], v[16:19]
	v_mfma_f32_16x16x32_bf16 v[60:63], v[162:165], v[194:197], v[60:63]
	v_mfma_f32_16x16x32_bf16 v[56:59], v[170:173], v[194:197], v[56:59]
	v_mfma_f32_16x16x32_bf16 v[52:55], v[162:165], v[202:205], v[52:55]
	v_mfma_f32_16x16x32_bf16 v[48:51], v[170:173], v[202:205], v[48:51]
	v_mfma_f32_16x16x32_bf16 v[28:31], v[162:165], v[210:213], v[28:31]
	v_mfma_f32_16x16x32_bf16 v[24:27], v[170:173], v[210:213], v[24:27]
	v_mfma_f32_16x16x32_bf16 v[20:23], v[162:165], v[218:221], v[20:23]
	v_mfma_f32_16x16x32_bf16 v[16:19], v[170:173], v[218:221], v[16:19]
	s_setprio 0
	s_setprio 1
	v_mfma_f32_16x16x32_bf16 v[44:47], v[174:177], v[190:193], v[44:47]
	v_mfma_f32_16x16x32_bf16 v[40:43], v[182:185], v[190:193], v[40:43]
	v_mfma_f32_16x16x32_bf16 v[36:39], v[174:177], v[198:201], v[36:39]
	v_mfma_f32_16x16x32_bf16 v[32:35], v[182:185], v[198:201], v[32:35]
	v_mfma_f32_16x16x32_bf16 v[12:15], v[174:177], v[206:209], v[12:15]
	v_mfma_f32_16x16x32_bf16 v[8:11], v[182:185], v[206:209], v[8:11]
	v_lshl_add_u64 v[222:223], v[228:229], 0, s[6:7]
	s_mov_b32 m0, s72
	s_nop 0
	global_load_lds_dwordx4 v[222:223], off
	v_mfma_f32_16x16x32_bf16 v[4:7], v[174:177], v[214:217], v[4:7]
	v_mfma_f32_16x16x32_bf16 v[0:3], v[182:185], v[214:217], v[0:3]
	v_mfma_f32_16x16x32_bf16 v[44:47], v[178:181], v[194:197], v[44:47]
	v_mfma_f32_16x16x32_bf16 v[40:43], v[186:189], v[194:197], v[40:43]
	v_mfma_f32_16x16x32_bf16 v[36:39], v[178:181], v[202:205], v[36:39]
	v_mfma_f32_16x16x32_bf16 v[32:35], v[186:189], v[202:205], v[32:35]
	v_mfma_f32_16x16x32_bf16 v[12:15], v[178:181], v[210:213], v[12:15]
	v_mfma_f32_16x16x32_bf16 v[8:11], v[186:189], v[210:213], v[8:11]
	v_mfma_f32_16x16x32_bf16 v[4:7], v[178:181], v[218:221], v[4:7]
	v_mfma_f32_16x16x32_bf16 v[0:3], v[186:189], v[218:221], v[0:3]
	s_setprio 0
	s_barrier
	s_add_i32 s86, s86, 2
	s_add_u32 s42, s42, 0x100
	s_addc_u32 s43, s43, 0
	s_add_u32 s84, s84, 0x100
	s_addc_u32 s85, s85, 0
	s_cmp_gt_u32 s86, 5
	s_cbranch_scc0 .LBB0_735
	v_lshl_add_u32 v178, s40, 8, v156
	v_lshl_or_b32 v144, s81, 8, v158
	v_ashrrev_i32_e32 v145, 31, v144
	v_ashrrev_i32_e32 v179, 31, v178
	v_lshl_add_u64 v[180:181], v[144:145], 1, s[0:1]
	v_lshlrev_b64 v[144:145], 11, v[178:179]
	v_or_b32_e32 v146, 16, v178
	v_lshl_add_u64 v[144:145], v[180:181], 0, v[144:145]
	v_ashrrev_i32_e32 v147, 31, v146
	global_load_dwordx4 v[162:165], v[144:145], off
	global_load_dwordx4 v[166:169], v[144:145], off offset:256
	v_lshlrev_b64 v[146:147], 11, v[146:147]
	v_lshl_add_u64 v[182:183], v[180:181], 0, v[146:147]
	global_load_dwordx4 v[170:173], v[182:183], off
	global_load_dwordx4 v[174:177], v[182:183], off offset:256
	v_or_b32_e32 v146, 32, v178
	v_ashrrev_i32_e32 v147, 31, v146
	v_lshlrev_b64 v[146:147], 11, v[146:147]
	v_lshl_add_u64 v[146:147], v[180:181], 0, v[146:147]
	s_mov_b32 s81, s24
	s_mov_b32 s40, s26
	s_mov_b64 s[44:45], s[38:39]
	s_mov_b64 s[42:43], s[36:37]
	s_waitcnt vmcnt(0)
; __device__ __forceinline__ u32x2 pack4(f32x4 v) { u32x2 w; w.x = cvt_pk_bf16(v[0], v[1]); w.y = cvt_pk_bf16(v[2], v[3]); return w; }
; __device__ __forceinline__ f32x4 unpack4(u32x2 w) { f32x4 v; v[0] = __uint_as_float(w.x << 16); v[1] = __uint_as_float(w.x & 0xffff0000u); v[2] = __uint_as_float(w.y << 16); v[3] = __uint_as_float(w.y & 0xffff0000u); return v; }
;     __device__ __forceinline__ void operator()(const f32x4 (&acc)[2][2][4][2], const Unit& u, int wr, int wc, int fr, int fq) const {
;     ...
;             u32x2 pg[4][2][2], pm_[4][2][2];
; #pragma unroll
;             for (int m = mh; m < mh + 2; ++m)
; #pragma unroll
;                 for (int bj = 0; bj < 2; ++bj)
; #pragma unroll
;                     for (int n = 0; n < 2; ++n) { const size_t off = (size_t)(row0 + ai * HALF + m * 16) * 1024 + col0 + bj * HALF + n * 4;
;                         pg[m][bj][n] = *(const u32x2*)(G + off); if (ADD) pm_[m][bj][n] = *(const u32x2*)(Mg + off); }
;             asm volatile("" ::: "memory");
; #pragma unroll
;             for (int m = mh; m < mh + 2; ++m)
; #pragma unroll
;                 for (int bj = 0; bj < 2; ++bj)
; #pragma unroll
;                     for (int n = 0; n < 2; ++n) { const size_t off = (size_t)(row0 + ai * HALF + m * 16) * 1024 + col0 + bj * HALF + n * 4;
;                         f32x4 o = unpack4(pg[m][bj][n]) * acc[ai][bj][m][n]; if (ADD) o = o + unpack4(pm_[m][bj][n]);
;                         *(u32x2*)(Mg + off) = pack4(o); }
;             asm volatile("" ::: "memory");
;         }
	v_lshlrev_b32_e32 v184, 16, v162
	v_and_b32_e32 v185, 0xffff0000, v162
	v_lshlrev_b32_e32 v162, 16, v163
	v_and_b32_e32 v163, 0xffff0000, v163
	v_lshlrev_b32_e32 v188, 16, v166
	v_and_b32_e32 v189, 0xffff0000, v166
	v_lshlrev_b32_e32 v166, 16, v167
	v_and_b32_e32 v167, 0xffff0000, v167
	v_lshlrev_b32_e32 v190, 16, v168
	v_and_b32_e32 v191, 0xffff0000, v168
	v_lshlrev_b32_e32 v168, 16, v169
	v_and_b32_e32 v169, 0xffff0000, v169
	v_lshlrev_b32_e32 v186, 16, v164
	v_and_b32_e32 v187, 0xffff0000, v164
	v_lshlrev_b32_e32 v164, 16, v165
	v_and_b32_e32 v165, 0xffff0000, v165
	v_pk_mul_f32 v[126:127], v[126:127], v[162:163]
	v_pk_mul_f32 v[118:119], v[118:119], v[166:167]
	v_pk_mul_f32 v[162:163], v[110:111], v[168:169]
	v_lshlrev_b32_e32 v166, 16, v170
	v_and_b32_e32 v167, 0xffff0000, v170
	v_lshlrev_b32_e32 v168, 16, v171
	v_and_b32_e32 v169, 0xffff0000, v171
	v_lshlrev_b32_e32 v170, 16, v172
	v_and_b32_e32 v171, 0xffff0000, v172
	v_lshlrev_b32_e32 v172, 16, v173
	v_and_b32_e32 v173, 0xffff0000, v173
	v_pk_mul_f32 v[124:125], v[124:125], v[184:185]
	v_pk_mul_f32 v[122:123], v[122:123], v[164:165]
	v_pk_mul_f32 v[120:121], v[120:121], v[186:187]
	v_lshlrev_b32_e32 v184, 16, v174
	v_and_b32_e32 v185, 0xffff0000, v174
	v_lshlrev_b32_e32 v174, 16, v175
	v_and_b32_e32 v175, 0xffff0000, v175
	v_lshlrev_b32_e32 v186, 16, v176
	v_and_b32_e32 v187, 0xffff0000, v176
	v_lshlrev_b32_e32 v176, 16, v177
	v_and_b32_e32 v177, 0xffff0000, v177
	v_pk_mul_f32 v[114:115], v[114:115], v[168:169]
	v_pk_mul_f32 v[112:113], v[112:113], v[166:167]
	v_pk_mul_f32 v[106:107], v[106:107], v[172:173]
	v_pk_mul_f32 v[104:105], v[104:105], v[170:171]
	v_pk_mul_f32 v[116:117], v[116:117], v[188:189]
	v_pk_mul_f32 v[164:165], v[108:109], v[190:191]
	v_cvt_pk_bf16_f32 v108, v124, v125
	v_cvt_pk_bf16_f32 v109, v126, v127
	v_cvt_pk_bf16_f32 v110, v120, v121
	v_cvt_pk_bf16_f32 v111, v122, v123
	v_pk_mul_f32 v[102:103], v[102:103], v[174:175]
	v_pk_mul_f32 v[100:101], v[100:101], v[184:185]
	v_pk_mul_f32 v[120:121], v[98:99], v[176:177]
	v_pk_mul_f32 v[122:123], v[96:97], v[186:187]
	v_cvt_pk_bf16_f32 v96, v112, v113
	v_cvt_pk_bf16_f32 v97, v114, v115
	v_cvt_pk_bf16_f32 v98, v104, v105
	v_cvt_pk_bf16_f32 v99, v106, v107
	v_cvt_pk_bf16_f32 v116, v116, v117
	v_cvt_pk_bf16_f32 v117, v118, v119
	v_cvt_pk_bf16_f32 v118, v164, v165
	v_cvt_pk_bf16_f32 v119, v162, v163
	global_store_dwordx4 v[144:145], v[108:111], off
	global_store_dwordx4 v[144:145], v[116:119], off offset:256
	v_cvt_pk_bf16_f32 v100, v100, v101
	v_cvt_pk_bf16_f32 v101, v102, v103
	v_cvt_pk_bf16_f32 v102, v122, v123
	v_cvt_pk_bf16_f32 v103, v120, v121
	global_store_dwordx4 v[182:183], v[96:99], off
	global_store_dwordx4 v[182:183], v[100:103], off offset:256
	global_load_dwordx4 v[98:101], v[146:147], off
	global_load_dwordx4 v[102:105], v[146:147], off offset:256
	v_or_b32_e32 v96, 48, v178
	v_ashrrev_i32_e32 v97, 31, v96
	v_lshlrev_b64 v[96:97], 11, v[96:97]
	v_lshl_add_u64 v[114:115], v[180:181], 0, v[96:97]
	global_load_dwordx4 v[106:109], v[114:115], off
	global_load_dwordx4 v[110:113], v[114:115], off offset:256
	v_add_co_u32_e32 v96, vcc, s77, v144
	s_waitcnt vmcnt(3)
	v_lshlrev_b32_e32 v116, 16, v98
	v_and_b32_e32 v117, 0xffff0000, v98
	v_lshlrev_b32_e32 v98, 16, v99
	v_and_b32_e32 v99, 0xffff0000, v99
	v_lshlrev_b32_e32 v118, 16, v100
	v_and_b32_e32 v119, 0xffff0000, v100
	v_lshlrev_b32_e32 v100, 16, v101
	v_and_b32_e32 v101, 0xffff0000, v101
	s_waitcnt vmcnt(2)
	v_lshlrev_b32_e32 v120, 16, v102
	v_and_b32_e32 v121, 0xffff0000, v102
	v_lshlrev_b32_e32 v102, 16, v103
	v_and_b32_e32 v103, 0xffff0000, v103
	v_lshlrev_b32_e32 v122, 16, v104
	v_and_b32_e32 v123, 0xffff0000, v104
	v_lshlrev_b32_e32 v104, 16, v105
	v_and_b32_e32 v105, 0xffff0000, v105
	s_waitcnt vmcnt(1)
	v_lshlrev_b32_e32 v124, 16, v106
	v_and_b32_e32 v125, 0xffff0000, v106
	v_lshlrev_b32_e32 v106, 16, v107
	v_and_b32_e32 v107, 0xffff0000, v107
	v_lshlrev_b32_e32 v126, 16, v108
	v_and_b32_e32 v127, 0xffff0000, v108
	v_lshlrev_b32_e32 v108, 16, v109
	v_and_b32_e32 v109, 0xffff0000, v109
	s_waitcnt vmcnt(0)
	v_lshlrev_b32_e32 v162, 16, v110
	v_and_b32_e32 v163, 0xffff0000, v110
	v_lshlrev_b32_e32 v110, 16, v111
	v_and_b32_e32 v111, 0xffff0000, v111
	v_lshlrev_b32_e32 v164, 16, v112
	v_and_b32_e32 v165, 0xffff0000, v112
	v_lshlrev_b32_e32 v112, 16, v113
	v_and_b32_e32 v113, 0xffff0000, v113
	v_pk_mul_f32 v[94:95], v[94:95], v[98:99]
	v_pk_mul_f32 v[92:93], v[92:93], v[116:117]
	v_pk_mul_f32 v[90:91], v[90:91], v[100:101]
	v_pk_mul_f32 v[88:89], v[88:89], v[118:119]
	v_pk_mul_f32 v[78:79], v[78:79], v[102:103]
	v_pk_mul_f32 v[76:77], v[76:77], v[120:121]
	v_pk_mul_f32 v[74:75], v[74:75], v[104:105]
	v_pk_mul_f32 v[72:73], v[72:73], v[122:123]
	v_pk_mul_f32 v[86:87], v[86:87], v[106:107]
	v_pk_mul_f32 v[84:85], v[84:85], v[124:125]
	v_pk_mul_f32 v[82:83], v[82:83], v[108:109]
	v_pk_mul_f32 v[80:81], v[80:81], v[126:127]
	v_pk_mul_f32 v[98:99], v[70:71], v[110:111]
	v_pk_mul_f32 v[100:101], v[68:69], v[162:163]
	v_pk_mul_f32 v[102:103], v[66:67], v[112:113]
	v_pk_mul_f32 v[104:105], v[64:65], v[164:165]
	v_cvt_pk_bf16_f32 v64, v92, v93
	v_cvt_pk_bf16_f32 v65, v94, v95
	v_cvt_pk_bf16_f32 v66, v88, v89
	v_cvt_pk_bf16_f32 v67, v90, v91
	v_addc_co_u32_e32 v97, vcc, 0, v145, vcc
	v_cvt_pk_bf16_f32 v68, v76, v77
	v_cvt_pk_bf16_f32 v69, v78, v79
	v_cvt_pk_bf16_f32 v70, v72, v73
	v_cvt_pk_bf16_f32 v71, v74, v75
	v_cvt_pk_bf16_f32 v72, v84, v85
	v_cvt_pk_bf16_f32 v73, v86, v87
	v_cvt_pk_bf16_f32 v74, v80, v81
	v_cvt_pk_bf16_f32 v75, v82, v83
	v_cvt_pk_bf16_f32 v76, v100, v101
	v_cvt_pk_bf16_f32 v77, v98, v99
	v_cvt_pk_bf16_f32 v78, v104, v105
	v_cvt_pk_bf16_f32 v79, v102, v103
	global_store_dwordx4 v[146:147], v[64:67], off
	global_store_dwordx4 v[146:147], v[68:71], off offset:256
	global_store_dwordx4 v[114:115], v[72:75], off
	global_store_dwordx4 v[114:115], v[76:79], off offset:256
	v_add_co_u32_e32 v84, vcc, s78, v144
	global_load_dwordx4 v[66:69], v[96:97], off
	v_lshl_add_u64 v[82:83], v[144:145], 0, s[12:13]
	v_addc_co_u32_e32 v85, vcc, 0, v145, vcc
	v_lshl_add_u64 v[86:87], v[144:145], 0, s[14:15]
	global_load_dwordx4 v[70:73], v[82:83], off offset:256
	global_load_dwordx4 v[74:77], v[84:85], off
	global_load_dwordx4 v[78:81], v[86:87], off offset:256
	v_add_co_u32_e32 v64, vcc, s79, v144
	s_waitcnt vmcnt(3)
; __device__ __forceinline__ u32x2 pack4(f32x4 v) { u32x2 w; w.x = cvt_pk_bf16(v[0], v[1]); w.y = cvt_pk_bf16(v[2], v[3]); return w; }
; __device__ __forceinline__ f32x4 unpack4(u32x2 w) { f32x4 v; v[0] = __uint_as_float(w.x << 16); v[1] = __uint_as_float(w.x & 0xffff0000u); v[2] = __uint_as_float(w.y << 16); v[3] = __uint_as_float(w.y & 0xffff0000u); return v; }
;     __device__ __forceinline__ void operator()(const f32x4 (&acc)[2][2][4][2], const Unit& u, int wr, int wc, int fr, int fq) const {
;     ...
;             u32x2 pg[4][2][2], pm_[4][2][2];
; #pragma unroll
;             for (int m = mh; m < mh + 2; ++m)
; #pragma unroll
;                 for (int bj = 0; bj < 2; ++bj)
; #pragma unroll
;                     for (int n = 0; n < 2; ++n) { const size_t off = (size_t)(row0 + ai * HALF + m * 16) * 1024 + col0 + bj * HALF + n * 4;
;                         pg[m][bj][n] = *(const u32x2*)(G + off); if (ADD) pm_[m][bj][n] = *(const u32x2*)(Mg + off); }
;             asm volatile("" ::: "memory");
; #pragma unroll
;             for (int m = mh; m < mh + 2; ++m)
; #pragma unroll
;                 for (int bj = 0; bj < 2; ++bj)
; #pragma unroll
;                     for (int n = 0; n < 2; ++n) { const size_t off = (size_t)(row0 + ai * HALF + m * 16) * 1024 + col0 + bj * HALF + n * 4;
;                         f32x4 o = unpack4(pg[m][bj][n]) * acc[ai][bj][m][n]; if (ADD) o = o + unpack4(pm_[m][bj][n]);
;                         *(u32x2*)(Mg + off) = pack4(o); }
;             asm volatile("" ::: "memory");
;         }
	v_lshlrev_b32_e32 v88, 16, v66
	v_and_b32_e32 v89, 0xffff0000, v66
	v_lshlrev_b32_e32 v66, 16, v67
	v_and_b32_e32 v67, 0xffff0000, v67
	v_lshlrev_b32_e32 v90, 16, v68
	v_and_b32_e32 v91, 0xffff0000, v68
	v_lshlrev_b32_e32 v68, 16, v69
	v_and_b32_e32 v69, 0xffff0000, v69
	s_waitcnt vmcnt(2)
	v_lshlrev_b32_e32 v92, 16, v70
	v_and_b32_e32 v93, 0xffff0000, v70
	v_lshlrev_b32_e32 v70, 16, v71
	v_and_b32_e32 v71, 0xffff0000, v71
	v_lshlrev_b32_e32 v94, 16, v72
	v_and_b32_e32 v95, 0xffff0000, v72
	v_lshlrev_b32_e32 v72, 16, v73
	v_and_b32_e32 v73, 0xffff0000, v73
	s_waitcnt vmcnt(1)
	v_lshlrev_b32_e32 v98, 16, v74
	v_and_b32_e32 v99, 0xffff0000, v74
	v_lshlrev_b32_e32 v74, 16, v75
	v_and_b32_e32 v75, 0xffff0000, v75
	v_lshlrev_b32_e32 v100, 16, v76
	v_and_b32_e32 v101, 0xffff0000, v76
	v_lshlrev_b32_e32 v76, 16, v77
	v_and_b32_e32 v77, 0xffff0000, v77
	s_waitcnt vmcnt(0)
	v_lshlrev_b32_e32 v102, 16, v78
	v_and_b32_e32 v103, 0xffff0000, v78
	v_lshlrev_b32_e32 v78, 16, v79
	v_and_b32_e32 v79, 0xffff0000, v79
	v_lshlrev_b32_e32 v104, 16, v80
	v_and_b32_e32 v105, 0xffff0000, v80
	v_lshlrev_b32_e32 v80, 16, v81
	v_and_b32_e32 v81, 0xffff0000, v81
	v_pk_mul_f32 v[62:63], v[62:63], v[66:67]
	v_pk_mul_f32 v[60:61], v[60:61], v[88:89]
	v_pk_mul_f32 v[58:59], v[58:59], v[68:69]
	v_pk_mul_f32 v[56:57], v[56:57], v[90:91]
	v_pk_mul_f32 v[46:47], v[46:47], v[70:71]
	v_pk_mul_f32 v[44:45], v[44:45], v[92:93]
	v_pk_mul_f32 v[42:43], v[42:43], v[72:73]
	v_pk_mul_f32 v[40:41], v[40:41], v[94:95]
	v_pk_mul_f32 v[54:55], v[54:55], v[74:75]
	v_pk_mul_f32 v[52:53], v[52:53], v[98:99]
	v_pk_mul_f32 v[50:51], v[50:51], v[76:77]
	v_pk_mul_f32 v[48:49], v[48:49], v[100:101]
	v_pk_mul_f32 v[66:67], v[38:39], v[78:79]
	v_pk_mul_f32 v[68:69], v[36:37], v[102:103]
	v_pk_mul_f32 v[70:71], v[34:35], v[80:81]
	v_pk_mul_f32 v[72:73], v[32:33], v[104:105]
	v_cvt_pk_bf16_f32 v32, v60, v61
	v_cvt_pk_bf16_f32 v33, v62, v63
	v_cvt_pk_bf16_f32 v34, v56, v57
	v_cvt_pk_bf16_f32 v35, v58, v59
	v_addc_co_u32_e32 v65, vcc, 0, v145, vcc
	v_cvt_pk_bf16_f32 v36, v44, v45
	v_cvt_pk_bf16_f32 v37, v46, v47
	v_cvt_pk_bf16_f32 v38, v40, v41
	v_cvt_pk_bf16_f32 v39, v42, v43
	v_cvt_pk_bf16_f32 v40, v52, v53
	v_cvt_pk_bf16_f32 v41, v54, v55
	v_cvt_pk_bf16_f32 v42, v48, v49
	v_cvt_pk_bf16_f32 v43, v50, v51
	v_cvt_pk_bf16_f32 v44, v68, v69
	v_cvt_pk_bf16_f32 v45, v66, v67
	v_cvt_pk_bf16_f32 v46, v72, v73
	v_cvt_pk_bf16_f32 v47, v70, v71
	global_store_dwordx4 v[96:97], v[32:35], off
	global_store_dwordx4 v[82:83], v[36:39], off offset:256
	global_store_dwordx4 v[84:85], v[40:43], off
	global_store_dwordx4 v[86:87], v[44:47], off offset:256
	v_add_co_u32_e32 v50, vcc, s80, v144
	global_load_dwordx4 v[32:35], v[64:65], off
	v_lshl_add_u64 v[48:49], v[144:145], 0, s[20:21]
	v_addc_co_u32_e32 v51, vcc, 0, v145, vcc
	v_lshl_add_u64 v[52:53], v[144:145], 0, s[22:23]
	global_load_dwordx4 v[36:39], v[48:49], off offset:256
	global_load_dwordx4 v[40:43], v[50:51], off
	global_load_dwordx4 v[44:47], v[52:53], off offset:256
	s_and_b64 vcc, exec, s[2:3]
	s_waitcnt vmcnt(3)
	v_lshlrev_b32_e32 v54, 16, v32
	v_and_b32_e32 v55, 0xffff0000, v32
	v_lshlrev_b32_e32 v32, 16, v33
	v_and_b32_e32 v33, 0xffff0000, v33
	v_lshlrev_b32_e32 v56, 16, v34
	v_and_b32_e32 v57, 0xffff0000, v34
	v_lshlrev_b32_e32 v34, 16, v35
	v_and_b32_e32 v35, 0xffff0000, v35
	s_waitcnt vmcnt(2)
	v_lshlrev_b32_e32 v58, 16, v36
	v_and_b32_e32 v59, 0xffff0000, v36
	v_lshlrev_b32_e32 v36, 16, v37
	v_and_b32_e32 v37, 0xffff0000, v37
	v_lshlrev_b32_e32 v60, 16, v38
	v_and_b32_e32 v61, 0xffff0000, v38
	v_lshlrev_b32_e32 v38, 16, v39
	v_and_b32_e32 v39, 0xffff0000, v39
	s_waitcnt vmcnt(1)
	v_lshlrev_b32_e32 v62, 16, v40
	v_and_b32_e32 v63, 0xffff0000, v40
	v_lshlrev_b32_e32 v40, 16, v41
	v_and_b32_e32 v41, 0xffff0000, v41
	v_lshlrev_b32_e32 v66, 16, v42
	v_and_b32_e32 v67, 0xffff0000, v42
	v_lshlrev_b32_e32 v42, 16, v43
	v_and_b32_e32 v43, 0xffff0000, v43
	s_waitcnt vmcnt(0)
	v_lshlrev_b32_e32 v68, 16, v44
	v_and_b32_e32 v69, 0xffff0000, v44
	v_lshlrev_b32_e32 v44, 16, v45
	v_and_b32_e32 v45, 0xffff0000, v45
	v_lshlrev_b32_e32 v70, 16, v46
	v_and_b32_e32 v71, 0xffff0000, v46
	v_lshlrev_b32_e32 v46, 16, v47
	v_and_b32_e32 v47, 0xffff0000, v47
	v_pk_mul_f32 v[30:31], v[30:31], v[32:33]
	v_pk_mul_f32 v[28:29], v[28:29], v[54:55]
	v_pk_mul_f32 v[26:27], v[26:27], v[34:35]
	v_pk_mul_f32 v[24:25], v[24:25], v[56:57]
	v_pk_mul_f32 v[14:15], v[14:15], v[36:37]
	v_pk_mul_f32 v[12:13], v[12:13], v[58:59]
	v_pk_mul_f32 v[10:11], v[10:11], v[38:39]
	v_pk_mul_f32 v[8:9], v[8:9], v[60:61]
	v_pk_mul_f32 v[22:23], v[22:23], v[40:41]
	v_pk_mul_f32 v[20:21], v[20:21], v[62:63]
	v_pk_mul_f32 v[18:19], v[18:19], v[42:43]
	v_pk_mul_f32 v[16:17], v[16:17], v[66:67]
	v_pk_mul_f32 v[32:33], v[6:7], v[44:45]
	v_pk_mul_f32 v[34:35], v[4:5], v[68:69]
	v_pk_mul_f32 v[36:37], v[2:3], v[46:47]
	v_pk_mul_f32 v[38:39], v[0:1], v[70:71]
	v_cvt_pk_bf16_f32 v0, v28, v29
	v_cvt_pk_bf16_f32 v1, v30, v31
	v_cvt_pk_bf16_f32 v2, v24, v25
	v_cvt_pk_bf16_f32 v3, v26, v27
	v_cvt_pk_bf16_f32 v4, v12, v13
	v_cvt_pk_bf16_f32 v5, v14, v15
	v_cvt_pk_bf16_f32 v6, v8, v9
	v_cvt_pk_bf16_f32 v7, v10, v11
	v_cvt_pk_bf16_f32 v8, v20, v21
	v_cvt_pk_bf16_f32 v9, v22, v23
	v_cvt_pk_bf16_f32 v10, v16, v17
	v_cvt_pk_bf16_f32 v11, v18, v19
	v_cvt_pk_bf16_f32 v12, v34, v35
	v_cvt_pk_bf16_f32 v13, v32, v33
	v_cvt_pk_bf16_f32 v14, v38, v39
	v_cvt_pk_bf16_f32 v15, v36, v37
	global_store_dwordx4 v[64:65], v[0:3], off
	global_store_dwordx4 v[48:49], v[4:7], off offset:256
	global_store_dwordx4 v[50:51], v[8:11], off
	global_store_dwordx4 v[52:53], v[12:15], off offset:256
	s_cbranch_vccz .LBB0_732
	s_waitcnt vmcnt(0)
	s_cmpk_gt_u32 s48, 0xff
	s_cbranch_scc1 .LBB0_739
	s_barrier

; #define PG8_STAGE(bufoff, gbase, voff) do { _Pragma("unroll") for (int _i = 0; _i < 2; ++_i) \
;         __builtin_amdgcn_global_load_lds((const unsigned*)((const char*)(gbase) + (voff)[_i]), (PG8_LAS unsigned*)(lds + (bufoff) + ldsw + _i * 8192), 16, 0, 0); } while (0)
; #define PG8_LDA(dst, b, h) do { _Pragma("unroll") for (int m = 0; m < 4; ++m) _Pragma("unroll") for (int k = 0; k < 2; ++k) dst[m][k] = *(const PG8_LAS bf16x8*)(lds + PG8_SA(b, h) + aoff + m * 2048 + k * 1024); } while (0)
; #define PG8_LDB(dst, b, h) do { _Pragma("unroll") for (int n = 0; n < 2; ++n) _Pragma("unroll") for (int k = 0; k < 2; ++k) dst[n][k] = *(const PG8_LAS bf16x8*)(lds + PG8_SB(b, h) + boff + n * 2048 + k * 1024); } while (0)
; #define PG8_MMA(ai, bj, At, Bt) do { __builtin_amdgcn_s_setprio(1); _Pragma("unroll") for (int m = 0; m < 4; ++m) _Pragma("unroll") for (int n = 0; n < 2; ++n) _Pragma("unroll") for (int k = 0; k < 2; ++k) \
;         acc[ai][bj][m][n] = __builtin_amdgcn_mfma_f32_16x16x32_bf16(Bt[n][k], At[m][k], acc[ai][bj][m][n], 0, 0, 0); __builtin_amdgcn_s_setprio(0); } while (0)
; #define PG8_WAIT_V(n) asm volatile("s_waitcnt vmcnt(" #n ")" ::: "memory")
; #define PG8_BAR __builtin_amdgcn_s_barrier()
; template <class Epi, class Sched, bool ALIGN_EPI = false, bool SP2 = false>
; __device__ __forceinline__ void gemm_phase(PG8_LAS unsigned char* lds, const Gemm g, const Sched& S, const Epi& E) {
;     ...
;         for (int t = 0; t < nt; t += 2) {
;             const bool last = (t == nt - 2);
;             const char* a1 = cA + (size_t)(t + 1) * kstep;
;             const char* a2 = last ? nA : cA + (size_t)(t + 2) * kstep; const char* b2 = last ? nB : cB + (size_t)(t + 2) * kstep;
;             const char* a3 = a2 + kstep; const char* b3 = b2 + kstep;
;             if (last && has_next) S.a_ready(nxt);
;             if constexpr (SP2) {
;             PG8_LDB(B0, 0, 0); PG8_LDB(B1, 0, 1); PG8_SCHED; PG8_LDA(At, 0, 0); PG8_STAGE(PG8_SA(1, 1), a1 + hstep, voffA);
;             PG8_WAIT_V(8); PG8_WAIT_L(0); PG8_BAR; PG8_MMA(0, 0, At, B0); PG8_MMA(0, 1, At, B1); PG8_BAR; PG8_SCHED;
;             PG8_LDA(At, 0, 1); PG8_STAGE(PG8_SB(0, 0), b2, voffB); PG8_STAGE(PG8_SB(0, 1), b2 + hstep, voffB); PG8_STAGE(PG8_SA(0, 0), a2, voffA);
;             PG8_WAIT_V(8); PG8_WAIT_L(0); PG8_BAR; PG8_MMA(1, 0, At, B0); PG8_MMA(1, 1, At, B1); PG8_BAR; PG8_SCHED;
.LBB0_747:
	ds_read_b128 v[144:147], v150
	ds_read_b128 v[158:161], v150 offset:1024
	ds_read_b128 v[162:165], v150 offset:2048
	ds_read_b128 v[166:169], v150 offset:3072
	ds_read_b128 v[170:173], v152
	ds_read_b128 v[174:177], v152 offset:1024
	ds_read_b128 v[178:181], v152 offset:2048
	ds_read_b128 v[182:185], v152 offset:3072
	s_add_u32 s36, s26, 0xfffe0080
	s_addc_u32 s37, s27, -1
	s_cmp_eq_u32 s72, 4
	s_cselect_b32 s39, s15, s37
	s_cselect_b32 s38, s60, s36
	s_cselect_b32 s37, s13, s71
	s_cselect_b32 s36, s61, s70
	v_lshl_add_u64 v[148:149], s[26:27], 0, v[136:137]
	s_add_i32 m0, s25, 0xc000
	ds_read_b128 v[186:189], v154
	ds_read_b128 v[190:193], v154 offset:1024
	ds_read_b128 v[194:197], v154 offset:2048
	ds_read_b128 v[198:201], v154 offset:3072
	ds_read_b128 v[202:205], v154 offset:4096
	ds_read_b128 v[206:209], v154 offset:5120
	ds_read_b128 v[210:213], v154 offset:6144
	ds_read_b128 v[214:217], v154 offset:7168
	global_load_lds_dwordx4 v[148:149], off
	v_lshl_add_u64 v[148:149], s[26:27], 0, v[138:139]
	s_add_i32 m0, s25, 0xe000
	s_nop 0
	global_load_lds_dwordx4 v[148:149], off
	s_waitcnt vmcnt(8)
	s_waitcnt lgkmcnt(0)
	s_setprio 1
	s_barrier
	v_mfma_f32_16x16x32_bf16 v[124:127], v[144:147], v[186:189], v[124:127]
	v_mfma_f32_16x16x32_bf16 v[120:123], v[162:165], v[186:189], v[120:123]
	v_mfma_f32_16x16x32_bf16 v[116:119], v[144:147], v[194:197], v[116:119]
	v_mfma_f32_16x16x32_bf16 v[104:107], v[162:165], v[194:197], v[104:107]
	v_mfma_f32_16x16x32_bf16 v[92:95], v[144:147], v[202:205], v[92:95]
	v_mfma_f32_16x16x32_bf16 v[88:91], v[162:165], v[202:205], v[88:91]
	v_mfma_f32_16x16x32_bf16 v[80:83], v[144:147], v[210:213], v[80:83]
	v_mfma_f32_16x16x32_bf16 v[72:75], v[162:165], v[210:213], v[72:75]
	v_mfma_f32_16x16x32_bf16 v[124:127], v[158:161], v[190:193], v[124:127]
	v_mfma_f32_16x16x32_bf16 v[120:123], v[166:169], v[190:193], v[120:123]
	v_mfma_f32_16x16x32_bf16 v[116:119], v[158:161], v[198:201], v[116:119]
	v_mfma_f32_16x16x32_bf16 v[104:107], v[166:169], v[198:201], v[104:107]
	v_mfma_f32_16x16x32_bf16 v[92:95], v[158:161], v[206:209], v[92:95]
	v_mfma_f32_16x16x32_bf16 v[88:91], v[166:169], v[206:209], v[88:91]
	v_mfma_f32_16x16x32_bf16 v[80:83], v[158:161], v[214:217], v[80:83]
	v_mfma_f32_16x16x32_bf16 v[72:75], v[166:169], v[214:217], v[72:75]
	s_setprio 0
	s_setprio 1
	v_mfma_f32_16x16x32_bf16 v[112:115], v[170:173], v[186:189], v[112:115]
	v_mfma_f32_16x16x32_bf16 v[108:111], v[178:181], v[186:189], v[108:111]
	v_mfma_f32_16x16x32_bf16 v[100:103], v[170:173], v[194:197], v[100:103]
	v_mfma_f32_16x16x32_bf16 v[96:99], v[178:181], v[194:197], v[96:99]
	v_mfma_f32_16x16x32_bf16 v[84:87], v[170:173], v[202:205], v[84:87]
	v_mfma_f32_16x16x32_bf16 v[76:79], v[178:181], v[202:205], v[76:79]
	v_mfma_f32_16x16x32_bf16 v[68:71], v[170:173], v[210:213], v[68:71]
	v_mfma_f32_16x16x32_bf16 v[64:67], v[178:181], v[210:213], v[64:67]
	v_mfma_f32_16x16x32_bf16 v[112:115], v[174:177], v[190:193], v[112:115]
	v_mfma_f32_16x16x32_bf16 v[108:111], v[182:185], v[190:193], v[108:111]
	v_mfma_f32_16x16x32_bf16 v[100:103], v[174:177], v[198:201], v[100:103]
	v_mfma_f32_16x16x32_bf16 v[96:99], v[182:185], v[198:201], v[96:99]
	v_mfma_f32_16x16x32_bf16 v[84:87], v[174:177], v[206:209], v[84:87]
	v_mfma_f32_16x16x32_bf16 v[76:79], v[182:185], v[206:209], v[76:79]
	v_mfma_f32_16x16x32_bf16 v[68:71], v[174:177], v[214:217], v[68:71]
	v_mfma_f32_16x16x32_bf16 v[64:67], v[182:185], v[214:217], v[64:67]
	s_setprio 0
	s_barrier
	s_add_i32 s73, s51, s41
	v_lshl_add_u64 v[148:149], s[36:37], 0, v[130:131]
	s_mov_b32 m0, s73
	ds_read_b128 v[186:189], v154 offset:16384
	ds_read_b128 v[190:193], v154 offset:17408
	ds_read_b128 v[194:197], v154 offset:18432
	ds_read_b128 v[198:201], v154 offset:19456
	ds_read_b128 v[202:205], v154 offset:20480
	ds_read_b128 v[206:209], v154 offset:21504
	ds_read_b128 v[210:213], v154 offset:22528
	ds_read_b128 v[214:217], v154 offset:23552
	global_load_lds_dwordx4 v[148:149], off
	s_add_i32 m0, s73, 0x2000
	s_add_u32 s74, s36, 0x20000
	v_lshl_add_u64 v[218:219], s[36:37], 0, v[134:135]
	s_addc_u32 s75, s37, 0
	s_add_i32 s73, s52, s41
	global_load_lds_dwordx4 v[218:219], off
	v_lshl_add_u64 v[220:221], s[74:75], 0, v[130:131]
	s_mov_b32 m0, s73
	v_lshl_add_u64 v[222:223], s[38:39], 0, v[132:133]
	global_load_lds_dwordx4 v[220:221], off
	v_lshl_add_u64 v[220:221], s[74:75], 0, v[134:135]
	s_add_i32 m0, s73, 0x2000
	s_nop 0
	global_load_lds_dwordx4 v[220:221], off
	s_waitcnt vmcnt(6)
	s_waitcnt lgkmcnt(0)
	s_setprio 1
	s_barrier
; #define PG8_STAGE(bufoff, gbase, voff) do { _Pragma("unroll") for (int _i = 0; _i < 2; ++_i) \
;         __builtin_amdgcn_global_load_lds((const unsigned*)((const char*)(gbase) + (voff)[_i]), (PG8_LAS unsigned*)(lds + (bufoff) + ldsw + _i * 8192), 16, 0, 0); } while (0)
; #define PG8_LDA(dst, b, h) do { _Pragma("unroll") for (int m = 0; m < 4; ++m) _Pragma("unroll") for (int k = 0; k < 2; ++k) dst[m][k] = *(const PG8_LAS bf16x8*)(lds + PG8_SA(b, h) + aoff + m * 2048 + k * 1024); } while (0)
; #define PG8_LDB(dst, b, h) do { _Pragma("unroll") for (int n = 0; n < 2; ++n) _Pragma("unroll") for (int k = 0; k < 2; ++k) dst[n][k] = *(const PG8_LAS bf16x8*)(lds + PG8_SB(b, h) + boff + n * 2048 + k * 1024); } while (0)
; #define PG8_MMA(ai, bj, At, Bt) do { __builtin_amdgcn_s_setprio(1); _Pragma("unroll") for (int m = 0; m < 4; ++m) _Pragma("unroll") for (int n = 0; n < 2; ++n) _Pragma("unroll") for (int k = 0; k < 2; ++k) \
;         acc[ai][bj][m][n] = __builtin_amdgcn_mfma_f32_16x16x32_bf16(Bt[n][k], At[m][k], acc[ai][bj][m][n], 0, 0, 0); __builtin_amdgcn_s_setprio(0); } while (0)
; #define PG8_WAIT_V(n) asm volatile("s_waitcnt vmcnt(" #n ")" ::: "memory")
; #define PG8_WAIT_L(n) asm volatile("s_waitcnt lgkmcnt(" #n ")" ::: "memory")
; #define PG8_BAR __builtin_amdgcn_s_barrier()
; #define PG8_SCHED __builtin_amdgcn_sched_barrier(0)
; template <class Epi, class Sched, bool ALIGN_EPI = false, bool SP2 = false>
; __device__ __forceinline__ void gemm_phase(PG8_LAS unsigned char* lds, const Gemm g, const Sched& S, const Epi& E) {
;     ...
;             PG8_WAIT_V(8); PG8_WAIT_L(0); PG8_BAR; PG8_MMA(0, 0, At, B0); PG8_MMA(0, 1, At, B1); PG8_BAR; PG8_SCHED;
;             PG8_LDA(At, 0, 1); PG8_STAGE(PG8_SB(0, 0), b2, voffB); PG8_STAGE(PG8_SB(0, 1), b2 + hstep, voffB); PG8_STAGE(PG8_SA(0, 0), a2, voffA);
;             PG8_WAIT_V(8); PG8_WAIT_L(0); PG8_BAR; PG8_MMA(1, 0, At, B0); PG8_MMA(1, 1, At, B1); PG8_BAR; PG8_SCHED;
;             PG8_LDB(B0, 1, 0); PG8_LDB(B1, 1, 1); PG8_SCHED; PG8_LDA(At, 1, 0); PG8_STAGE(PG8_SA(0, 1), a2 + hstep, voffA);
;             PG8_WAIT_V(8); PG8_WAIT_L(0); PG8_BAR; PG8_MMA(0, 0, At, B0); PG8_MMA(0, 1, At, B1); PG8_BAR; PG8_SCHED;
	v_mfma_f32_16x16x32_bf16 v[60:63], v[144:147], v[186:189], v[60:63]
	v_mfma_f32_16x16x32_bf16 v[56:59], v[162:165], v[186:189], v[56:59]
	v_mfma_f32_16x16x32_bf16 v[48:51], v[144:147], v[194:197], v[48:51]
	v_mfma_f32_16x16x32_bf16 v[40:43], v[162:165], v[194:197], v[40:43]
	v_mfma_f32_16x16x32_bf16 v[28:31], v[144:147], v[202:205], v[28:31]
	v_mfma_f32_16x16x32_bf16 v[24:27], v[162:165], v[202:205], v[24:27]
	v_lshl_add_u64 v[220:221], s[38:39], 0, v[128:129]
	s_mov_b32 m0, s25
	s_nop 0
	global_load_lds_dwordx4 v[220:221], off
	v_mfma_f32_16x16x32_bf16 v[16:19], v[144:147], v[210:213], v[16:19]
	v_mfma_f32_16x16x32_bf16 v[8:11], v[162:165], v[210:213], v[8:11]
	v_mfma_f32_16x16x32_bf16 v[60:63], v[158:161], v[190:193], v[60:63]
	v_mfma_f32_16x16x32_bf16 v[56:59], v[166:169], v[190:193], v[56:59]
	v_mfma_f32_16x16x32_bf16 v[48:51], v[158:161], v[198:201], v[48:51]
	v_mfma_f32_16x16x32_bf16 v[40:43], v[166:169], v[198:201], v[40:43]
	v_mfma_f32_16x16x32_bf16 v[28:31], v[158:161], v[206:209], v[28:31]
	v_mfma_f32_16x16x32_bf16 v[24:27], v[166:169], v[206:209], v[24:27]
	v_mfma_f32_16x16x32_bf16 v[16:19], v[158:161], v[214:217], v[16:19]
	v_mfma_f32_16x16x32_bf16 v[8:11], v[166:169], v[214:217], v[8:11]
	s_setprio 0
	s_setprio 1
	v_mfma_f32_16x16x32_bf16 v[52:55], v[170:173], v[186:189], v[52:55]
	v_mfma_f32_16x16x32_bf16 v[44:47], v[178:181], v[186:189], v[44:47]
	v_mfma_f32_16x16x32_bf16 v[36:39], v[170:173], v[194:197], v[36:39]
	v_mfma_f32_16x16x32_bf16 v[32:35], v[178:181], v[194:197], v[32:35]
	v_mfma_f32_16x16x32_bf16 v[20:23], v[170:173], v[202:205], v[20:23]
	v_mfma_f32_16x16x32_bf16 v[12:15], v[178:181], v[202:205], v[12:15]
	s_mov_b32 m0, s44
	s_nop 0
	global_load_lds_dwordx4 v[222:223], off
	v_mfma_f32_16x16x32_bf16 v[4:7], v[170:173], v[210:213], v[4:7]
	v_mfma_f32_16x16x32_bf16 v[0:3], v[178:181], v[210:213], v[0:3]
	v_mfma_f32_16x16x32_bf16 v[52:55], v[174:177], v[190:193], v[52:55]
	v_mfma_f32_16x16x32_bf16 v[44:47], v[182:185], v[190:193], v[44:47]
	v_mfma_f32_16x16x32_bf16 v[36:39], v[174:177], v[198:201], v[36:39]
	v_mfma_f32_16x16x32_bf16 v[32:35], v[182:185], v[198:201], v[32:35]
	v_mfma_f32_16x16x32_bf16 v[20:23], v[174:177], v[206:209], v[20:23]
	v_mfma_f32_16x16x32_bf16 v[12:15], v[182:185], v[206:209], v[12:15]
	v_mfma_f32_16x16x32_bf16 v[4:7], v[174:177], v[214:217], v[4:7]
	v_mfma_f32_16x16x32_bf16 v[0:3], v[182:185], v[214:217], v[0:3]
	s_setprio 0
	s_barrier
	s_add_i32 s73, 0, 0x18000
	v_add_u32_e32 v155, s73, v153
	s_add_i32 s74, 0, 0x1c000
	ds_read_b128 v[144:147], v155
	ds_read_b128 v[158:161], v155 offset:1024
	ds_read_b128 v[162:165], v155 offset:2048
	ds_read_b128 v[166:169], v155 offset:3072
	v_add_u32_e32 v155, s74, v153
	ds_read_b128 v[170:173], v155
	ds_read_b128 v[174:177], v155 offset:1024
	ds_read_b128 v[178:181], v155 offset:2048
	ds_read_b128 v[182:185], v155 offset:3072
	s_add_u32 s38, s38, 0x20000
	s_addc_u32 s39, s39, 0
	s_mov_b32 m0, s45
	v_lshl_add_u64 v[224:225], s[38:39], 0, v[128:129]
	ds_read_b128 v[186:189], v154 offset:32768
	ds_read_b128 v[190:193], v154 offset:33792
	ds_read_b128 v[194:197], v154 offset:34816
	ds_read_b128 v[198:201], v154 offset:35840
	ds_read_b128 v[202:205], v154 offset:36864
	ds_read_b128 v[206:209], v154 offset:37888
	ds_read_b128 v[210:213], v154 offset:38912
	ds_read_b128 v[214:217], v154 offset:39936
	global_load_lds_dwordx4 v[224:225], off
	v_lshl_add_u64 v[224:225], s[38:39], 0, v[132:133]
	s_mov_b32 m0, s46
	s_nop 0
	global_load_lds_dwordx4 v[224:225], off
	s_waitcnt vmcnt(8)
	s_waitcnt lgkmcnt(0)
	s_setprio 1
	s_barrier
	v_mfma_f32_16x16x32_bf16 v[124:127], v[144:147], v[186:189], v[124:127]
	v_mfma_f32_16x16x32_bf16 v[120:123], v[162:165], v[186:189], v[120:123]
	v_mfma_f32_16x16x32_bf16 v[116:119], v[144:147], v[194:197], v[116:119]
	v_mfma_f32_16x16x32_bf16 v[104:107], v[162:165], v[194:197], v[104:107]
	v_mfma_f32_16x16x32_bf16 v[92:95], v[144:147], v[202:205], v[92:95]
	v_mfma_f32_16x16x32_bf16 v[88:91], v[162:165], v[202:205], v[88:91]
	v_mfma_f32_16x16x32_bf16 v[80:83], v[144:147], v[210:213], v[80:83]
	v_mfma_f32_16x16x32_bf16 v[72:75], v[162:165], v[210:213], v[72:75]
	v_mfma_f32_16x16x32_bf16 v[124:127], v[158:161], v[190:193], v[124:127]
	v_mfma_f32_16x16x32_bf16 v[120:123], v[166:169], v[190:193], v[120:123]
	v_mfma_f32_16x16x32_bf16 v[116:119], v[158:161], v[198:201], v[116:119]
	v_mfma_f32_16x16x32_bf16 v[104:107], v[166:169], v[198:201], v[104:107]
	v_mfma_f32_16x16x32_bf16 v[92:95], v[158:161], v[206:209], v[92:95]
	v_mfma_f32_16x16x32_bf16 v[88:91], v[166:169], v[206:209], v[88:91]
	v_mfma_f32_16x16x32_bf16 v[80:83], v[158:161], v[214:217], v[80:83]
	v_mfma_f32_16x16x32_bf16 v[72:75], v[166:169], v[214:217], v[72:75]
	s_setprio 0
	s_setprio 1
	v_mfma_f32_16x16x32_bf16 v[112:115], v[170:173], v[186:189], v[112:115]
	v_mfma_f32_16x16x32_bf16 v[108:111], v[178:181], v[186:189], v[108:111]
	v_mfma_f32_16x16x32_bf16 v[100:103], v[170:173], v[194:197], v[100:103]
	v_mfma_f32_16x16x32_bf16 v[96:99], v[178:181], v[194:197], v[96:99]
	v_mfma_f32_16x16x32_bf16 v[84:87], v[170:173], v[202:205], v[84:87]
	v_mfma_f32_16x16x32_bf16 v[76:79], v[178:181], v[202:205], v[76:79]
	v_mfma_f32_16x16x32_bf16 v[68:71], v[170:173], v[210:213], v[68:71]
	v_mfma_f32_16x16x32_bf16 v[64:67], v[178:181], v[210:213], v[64:67]
	v_mfma_f32_16x16x32_bf16 v[112:115], v[174:177], v[190:193], v[112:115]
	v_mfma_f32_16x16x32_bf16 v[108:111], v[182:185], v[190:193], v[108:111]
	v_mfma_f32_16x16x32_bf16 v[100:103], v[174:177], v[198:201], v[100:103]
	v_mfma_f32_16x16x32_bf16 v[96:99], v[182:185], v[198:201], v[96:99]
	v_mfma_f32_16x16x32_bf16 v[84:87], v[174:177], v[206:209], v[84:87]
	v_mfma_f32_16x16x32_bf16 v[76:79], v[182:185], v[206:209], v[76:79]
	v_mfma_f32_16x16x32_bf16 v[68:71], v[174:177], v[214:217], v[68:71]
	v_mfma_f32_16x16x32_bf16 v[64:67], v[182:185], v[214:217], v[64:67]
	s_setprio 0
	s_barrier
; #define PG8_STAGE(bufoff, gbase, voff) do { _Pragma("unroll") for (int _i = 0; _i < 2; ++_i) \
;         __builtin_amdgcn_global_load_lds((const unsigned*)((const char*)(gbase) + (voff)[_i]), (PG8_LAS unsigned*)(lds + (bufoff) + ldsw + _i * 8192), 16, 0, 0); } while (0)
; #define PG8_LDA(dst, b, h) do { _Pragma("unroll") for (int m = 0; m < 4; ++m) _Pragma("unroll") for (int k = 0; k < 2; ++k) dst[m][k] = *(const PG8_LAS bf16x8*)(lds + PG8_SA(b, h) + aoff + m * 2048 + k * 1024); } while (0)
; #define PG8_MMA(ai, bj, At, Bt) do { __builtin_amdgcn_s_setprio(1); _Pragma("unroll") for (int m = 0; m < 4; ++m) _Pragma("unroll") for (int n = 0; n < 2; ++n) _Pragma("unroll") for (int k = 0; k < 2; ++k) \
;         acc[ai][bj][m][n] = __builtin_amdgcn_mfma_f32_16x16x32_bf16(Bt[n][k], At[m][k], acc[ai][bj][m][n], 0, 0, 0); __builtin_amdgcn_s_setprio(0); } while (0)
;     __device__ __forceinline__ void operator()(const f32x4 (&acc)[2][2][4][2], const Unit& u, int wr, int wc, int fr, int fq) const {
;         const int row0 = u.pm * BM + wr * 64 + fr, col0 = u.pn * BM + wc * 32 + 8 * fq;
;         const bf16_t* const G = (const bf16_t*)(ws + (ADD ? WS_GB : WS_GA)); bf16_t* const Mg = (bf16_t*)(ws + WS_GA);
; #pragma unroll
;         for (int ai = 0; ai < 2; ++ai)
; #pragma unroll
;         for (int mh = 0; mh < 4; mh += 2) {
;             u32x2 pg[4][2][2], pm_[4][2][2];
; #pragma unroll
;             for (int m = mh; m < mh + 2; ++m)
; #pragma unroll
;                 for (int bj = 0; bj < 2; ++bj)
; #pragma unroll
;                     for (int n = 0; n < 2; ++n) { const size_t off = (size_t)(row0 + ai * HALF + m * 16) * 1024 + col0 + bj * HALF + n * 4;
;                         pg[m][bj][n] = *(const u32x2*)(G + off); if (ADD) pm_[m][bj][n] = *(const u32x2*)(Mg + off); }
; template <class Epi, class Sched, bool ALIGN_EPI = false, bool SP2 = false>
; __device__ __forceinline__ void gemm_phase(PG8_LAS unsigned char* lds, const Gemm g, const Sched& S, const Epi& E) {
;     ...
;             PG8_WAIT_V(8); PG8_WAIT_L(0); PG8_BAR; PG8_MMA(0, 0, At, B0); PG8_MMA(0, 1, At, B1); PG8_BAR; PG8_SCHED;
;             PG8_LDA(At, 1, 1); PG8_STAGE(PG8_SB(1, 0), b3, voffB); PG8_STAGE(PG8_SB(1, 1), b3 + hstep, voffB); PG8_STAGE(PG8_SA(1, 0), a3, voffA);
;             PG8_WAIT_V(8); PG8_WAIT_L(0); PG8_BAR; PG8_MMA(1, 0, At, B0); PG8_MMA(1, 1, At, B1); PG8_BAR; PG8_SCHED;
	s_add_i32 s38, s73, s41
	v_lshl_add_u64 v[148:149], v[148:149], 0, s[4:5]
	s_mov_b32 m0, s38
	ds_read_b128 v[186:189], v154 offset:49152
	ds_read_b128 v[190:193], v154 offset:50176
	ds_read_b128 v[194:197], v154 offset:51200
	ds_read_b128 v[198:201], v154 offset:52224
	ds_read_b128 v[202:205], v154 offset:53248
	ds_read_b128 v[206:209], v154 offset:54272
	ds_read_b128 v[210:213], v154 offset:55296
	ds_read_b128 v[214:217], v154 offset:56320
	global_load_lds_dwordx4 v[148:149], off
	s_add_i32 m0, s38, 0x2000
	s_add_u32 s36, s36, 0x20080
	v_lshl_add_u64 v[148:149], v[218:219], 0, s[4:5]
	s_addc_u32 s37, s37, 0
	s_add_i32 s38, s74, s41
	global_load_lds_dwordx4 v[148:149], off
	v_lshl_add_u64 v[148:149], s[36:37], 0, v[130:131]
	s_mov_b32 m0, s38
	s_nop 0
	global_load_lds_dwordx4 v[148:149], off
	v_lshl_add_u64 v[148:149], s[36:37], 0, v[134:135]
	s_add_i32 m0, s38, 0x2000
	s_nop 0
	global_load_lds_dwordx4 v[148:149], off
	s_waitcnt vmcnt(6)
	s_waitcnt lgkmcnt(0)
	s_setprio 1
	s_barrier
	v_mfma_f32_16x16x32_bf16 v[60:63], v[144:147], v[186:189], v[60:63]
	v_mfma_f32_16x16x32_bf16 v[56:59], v[162:165], v[186:189], v[56:59]
	v_mfma_f32_16x16x32_bf16 v[48:51], v[144:147], v[194:197], v[48:51]
	v_mfma_f32_16x16x32_bf16 v[40:43], v[162:165], v[194:197], v[40:43]
	v_mfma_f32_16x16x32_bf16 v[28:31], v[144:147], v[202:205], v[28:31]
	v_mfma_f32_16x16x32_bf16 v[24:27], v[162:165], v[202:205], v[24:27]
	v_lshl_add_u64 v[148:149], v[220:221], 0, s[4:5]
	s_mov_b32 m0, s48
	s_nop 0
	global_load_lds_dwordx4 v[148:149], off
	v_mfma_f32_16x16x32_bf16 v[16:19], v[144:147], v[210:213], v[16:19]
	v_mfma_f32_16x16x32_bf16 v[8:11], v[162:165], v[210:213], v[8:11]
	v_mfma_f32_16x16x32_bf16 v[60:63], v[158:161], v[190:193], v[60:63]
	v_mfma_f32_16x16x32_bf16 v[56:59], v[166:169], v[190:193], v[56:59]
	v_mfma_f32_16x16x32_bf16 v[48:51], v[158:161], v[198:201], v[48:51]
	v_mfma_f32_16x16x32_bf16 v[40:43], v[166:169], v[198:201], v[40:43]
	v_mfma_f32_16x16x32_bf16 v[28:31], v[158:161], v[206:209], v[28:31]
	v_mfma_f32_16x16x32_bf16 v[24:27], v[166:169], v[206:209], v[24:27]
	v_mfma_f32_16x16x32_bf16 v[16:19], v[158:161], v[214:217], v[16:19]
	v_mfma_f32_16x16x32_bf16 v[8:11], v[166:169], v[214:217], v[8:11]
	s_setprio 0
	s_setprio 1
	v_mfma_f32_16x16x32_bf16 v[52:55], v[170:173], v[186:189], v[52:55]
	v_mfma_f32_16x16x32_bf16 v[44:47], v[178:181], v[186:189], v[44:47]
	v_mfma_f32_16x16x32_bf16 v[36:39], v[170:173], v[194:197], v[36:39]
	v_mfma_f32_16x16x32_bf16 v[32:35], v[178:181], v[194:197], v[32:35]
	v_mfma_f32_16x16x32_bf16 v[20:23], v[170:173], v[202:205], v[20:23]
	v_mfma_f32_16x16x32_bf16 v[12:15], v[178:181], v[202:205], v[12:15]
	v_lshl_add_u64 v[148:149], v[222:223], 0, s[4:5]
	s_mov_b32 m0, s49
	s_nop 0
	global_load_lds_dwordx4 v[148:149], off
	v_mfma_f32_16x16x32_bf16 v[4:7], v[170:173], v[210:213], v[4:7]
	v_mfma_f32_16x16x32_bf16 v[0:3], v[178:181], v[210:213], v[0:3]
	v_mfma_f32_16x16x32_bf16 v[52:55], v[174:177], v[190:193], v[52:55]
	v_mfma_f32_16x16x32_bf16 v[44:47], v[182:185], v[190:193], v[44:47]
	v_mfma_f32_16x16x32_bf16 v[36:39], v[174:177], v[198:201], v[36:39]
	v_mfma_f32_16x16x32_bf16 v[32:35], v[182:185], v[198:201], v[32:35]
	v_mfma_f32_16x16x32_bf16 v[20:23], v[174:177], v[206:209], v[20:23]
	v_mfma_f32_16x16x32_bf16 v[12:15], v[182:185], v[206:209], v[12:15]
	v_mfma_f32_16x16x32_bf16 v[4:7], v[174:177], v[214:217], v[4:7]
	v_mfma_f32_16x16x32_bf16 v[0:3], v[182:185], v[214:217], v[0:3]
	s_setprio 0
	s_barrier
	s_add_i32 s72, s72, 2
	s_add_u32 s26, s26, 0x100
	s_addc_u32 s27, s27, 0
	s_add_u32 s70, s70, 0x100
	s_addc_u32 s71, s71, 0
	s_cmp_gt_u32 s72, 5
	s_cbranch_scc0 .LBB0_747
	v_lshl_add_u32 v146, s24, 8, v156
	v_lshl_or_b32 v144, s53, 8, v151
	v_ashrrev_i32_e32 v147, 31, v146
	v_ashrrev_i32_e32 v145, 31, v144
	v_lshlrev_b64 v[148:149], 10, v[146:147]
	v_lshl_add_u64 v[148:149], v[148:149], 0, v[144:145]
	v_lshlrev_b64 v[170:171], 1, v[148:149]
	v_lshl_add_u64 v[148:149], s[6:7], 0, v[170:171]
	v_or_b32_e32 v170, 0x100, v170
	v_lshl_add_u64 v[166:167], s[6:7], 0, v[170:171]
	v_or_b32_e32 v178, 16, v146
	global_load_dwordx4 v[158:161], v[148:149], off
	v_lshlrev_b64 v[162:163], 11, v[146:147]
	global_load_dwordx4 v[166:169], v[166:167], off
	v_lshl_add_u64 v[148:149], v[144:145], 1, s[0:1]
	v_ashrrev_i32_e32 v179, 31, v178
	v_lshl_add_u64 v[190:191], v[148:149], 0, v[162:163]
	v_lshlrev_b64 v[174:175], 10, v[178:179]
	global_load_dwordx4 v[162:165], v[190:191], off
	v_lshl_add_u64 v[170:171], s[0:1], 0, v[170:171]
	v_lshl_add_u64 v[174:175], v[174:175], 0, v[144:145]
	global_load_dwordx4 v[170:173], v[170:171], off
	v_lshlrev_b64 v[186:187], 1, v[174:175]
	v_lshlrev_b64 v[178:179], 11, v[178:179]
	v_lshl_add_u64 v[174:175], s[6:7], 0, v[186:187]
	v_lshl_add_u64 v[192:193], v[148:149], 0, v[178:179]
	global_load_dwordx4 v[174:177], v[174:175], off
	v_or_b32_e32 v186, 0x100, v186
	global_load_dwordx4 v[178:181], v[192:193], off
	v_lshl_add_u64 v[182:183], s[6:7], 0, v[186:187]
	v_lshl_add_u64 v[186:187], s[0:1], 0, v[186:187]
	global_load_dwordx4 v[182:185], v[182:183], off
	s_and_b64 vcc, exec, s[2:3]
	global_load_dwordx4 v[186:189], v[186:187], off
	s_mov_b32 s53, s12
	s_mov_b32 s24, s14
	s_mov_b64 s[36:37], s[22:23]
	s_mov_b64 s[26:27], s[20:21]
	s_waitcnt vmcnt(0)
; __device__ __forceinline__ u32x2 pack4(f32x4 v) { u32x2 w; w.x = cvt_pk_bf16(v[0], v[1]); w.y = cvt_pk_bf16(v[2], v[3]); return w; }
; __device__ __forceinline__ f32x4 unpack4(u32x2 w) { f32x4 v; v[0] = __uint_as_float(w.x << 16); v[1] = __uint_as_float(w.x & 0xffff0000u); v[2] = __uint_as_float(w.y << 16); v[3] = __uint_as_float(w.y & 0xffff0000u); return v; }
;     __device__ __forceinline__ void operator()(const f32x4 (&acc)[2][2][4][2], const Unit& u, int wr, int wc, int fr, int fq) const {
;     ...
;             for (int m = mh; m < mh + 2; ++m)
; #pragma unroll
;                 for (int bj = 0; bj < 2; ++bj)
; #pragma unroll
;                     for (int n = 0; n < 2; ++n) { const size_t off = (size_t)(row0 + ai * HALF + m * 16) * 1024 + col0 + bj * HALF + n * 4;
;                         pg[m][bj][n] = *(const u32x2*)(G + off); if (ADD) pm_[m][bj][n] = *(const u32x2*)(Mg + off); }
;             asm volatile("" ::: "memory");
; #pragma unroll
;             for (int m = mh; m < mh + 2; ++m)
; #pragma unroll
;                 for (int bj = 0; bj < 2; ++bj)
; #pragma unroll
;                     for (int n = 0; n < 2; ++n) { const size_t off = (size_t)(row0 + ai * HALF + m * 16) * 1024 + col0 + bj * HALF + n * 4;
;                         f32x4 o = unpack4(pg[m][bj][n]) * acc[ai][bj][m][n]; if (ADD) o = o + unpack4(pm_[m][bj][n]);
;                         *(u32x2*)(Mg + off) = pack4(o); }
;             asm volatile("" ::: "memory");
;         }
	v_lshlrev_b32_e32 v194, 16, v158
	v_and_b32_e32 v195, 0xffff0000, v158
	v_lshlrev_b32_e32 v158, 16, v159
	v_and_b32_e32 v159, 0xffff0000, v159
	v_lshlrev_b32_e32 v198, 16, v160
	v_and_b32_e32 v199, 0xffff0000, v160
	v_lshlrev_b32_e32 v160, 16, v161
	v_lshlrev_b32_e32 v196, 16, v162
	v_and_b32_e32 v197, 0xffff0000, v162
	v_lshlrev_b32_e32 v162, 16, v163
	v_and_b32_e32 v163, 0xffff0000, v163
	v_and_b32_e32 v161, 0xffff0000, v161
	v_lshlrev_b32_e32 v200, 16, v164
	v_and_b32_e32 v201, 0xffff0000, v164
	v_lshlrev_b32_e32 v164, 16, v165
	v_and_b32_e32 v165, 0xffff0000, v165
	v_pk_fma_f32 v[126:127], v[126:127], v[158:159], v[162:163]
	v_pk_fma_f32 v[124:125], v[124:125], v[194:195], v[196:197]
	v_pk_fma_f32 v[158:159], v[122:123], v[160:161], v[164:165]
	v_lshlrev_b32_e32 v160, 16, v166
	v_and_b32_e32 v161, 0xffff0000, v166
	v_lshlrev_b32_e32 v162, 16, v167
	v_and_b32_e32 v163, 0xffff0000, v167
	v_lshlrev_b32_e32 v164, 16, v170
	v_and_b32_e32 v165, 0xffff0000, v170
	v_lshlrev_b32_e32 v166, 16, v171
	v_and_b32_e32 v167, 0xffff0000, v171
	v_lshlrev_b32_e32 v170, 16, v168
	v_and_b32_e32 v171, 0xffff0000, v168
	v_lshlrev_b32_e32 v168, 16, v169
	v_and_b32_e32 v169, 0xffff0000, v169
	v_lshlrev_b32_e32 v194, 16, v172
	v_and_b32_e32 v195, 0xffff0000, v172
	v_lshlrev_b32_e32 v172, 16, v173
	v_and_b32_e32 v173, 0xffff0000, v173
	v_pk_fma_f32 v[122:123], v[120:121], v[198:199], v[200:201]
	v_cvt_pk_bf16_f32 v120, v124, v125
	v_pk_fma_f32 v[114:115], v[114:115], v[162:163], v[166:167]
	v_pk_fma_f32 v[112:113], v[112:113], v[160:161], v[164:165]
	v_pk_fma_f32 v[124:125], v[110:111], v[168:169], v[172:173]
	v_pk_fma_f32 v[110:111], v[108:109], v[170:171], v[194:195]
	v_lshlrev_b32_e32 v196, 16, v174
	v_and_b32_e32 v197, 0xffff0000, v174
	v_lshlrev_b32_e32 v174, 16, v175
	v_and_b32_e32 v175, 0xffff0000, v175
	v_lshlrev_b32_e32 v198, 16, v178
	v_and_b32_e32 v199, 0xffff0000, v178
	v_lshlrev_b32_e32 v178, 16, v179
	v_cvt_pk_bf16_f32 v108, v112, v113
	v_cvt_pk_bf16_f32 v109, v114, v115
	v_cvt_pk_bf16_f32 v110, v110, v111
	v_cvt_pk_bf16_f32 v111, v124, v125
	v_and_b32_e32 v179, 0xffff0000, v179
	global_store_dwordx4 v[190:191], v[108:111], off offset:256
	v_lshlrev_b32_e32 v112, 16, v177
	v_and_b32_e32 v113, 0xffff0000, v177
	v_pk_fma_f32 v[110:111], v[118:119], v[174:175], v[178:179]
	v_pk_fma_f32 v[108:109], v[116:117], v[196:197], v[198:199]
	v_lshlrev_b32_e32 v114, 16, v180
	v_cvt_pk_bf16_f32 v108, v108, v109
	v_cvt_pk_bf16_f32 v109, v110, v111
	v_lshlrev_b32_e32 v110, 16, v176
	v_and_b32_e32 v111, 0xffff0000, v176
	v_and_b32_e32 v115, 0xffff0000, v180
	v_lshlrev_b32_e32 v116, 16, v181
	v_and_b32_e32 v117, 0xffff0000, v181
	v_pk_fma_f32 v[106:107], v[106:107], v[112:113], v[116:117]
	v_pk_fma_f32 v[104:105], v[104:105], v[110:111], v[114:115]
	v_cvt_pk_bf16_f32 v111, v106, v107
	v_cvt_pk_bf16_f32 v110, v104, v105
	global_store_dwordx4 v[192:193], v[108:111], off
	v_lshlrev_b32_e32 v104, 16, v182
	v_and_b32_e32 v105, 0xffff0000, v182
	v_lshlrev_b32_e32 v106, 16, v183
	v_and_b32_e32 v107, 0xffff0000, v183
	v_lshlrev_b32_e32 v108, 16, v186
	v_and_b32_e32 v109, 0xffff0000, v186
	v_lshlrev_b32_e32 v110, 16, v187
	v_and_b32_e32 v111, 0xffff0000, v187
	v_pk_fma_f32 v[102:103], v[102:103], v[106:107], v[110:111]
	v_pk_fma_f32 v[100:101], v[100:101], v[104:105], v[108:109]
	v_lshlrev_b32_e32 v104, 16, v185
	v_cvt_pk_bf16_f32 v100, v100, v101
	v_cvt_pk_bf16_f32 v101, v102, v103
	v_lshlrev_b32_e32 v102, 16, v184
	v_and_b32_e32 v103, 0xffff0000, v184
	v_and_b32_e32 v105, 0xffff0000, v185
	v_lshlrev_b32_e32 v106, 16, v188
	v_and_b32_e32 v107, 0xffff0000, v188
	v_lshlrev_b32_e32 v108, 16, v189
	v_and_b32_e32 v109, 0xffff0000, v189
	v_pk_fma_f32 v[98:99], v[98:99], v[104:105], v[108:109]
	v_pk_fma_f32 v[96:97], v[96:97], v[102:103], v[106:107]
	v_cvt_pk_bf16_f32 v103, v98, v99
	v_cvt_pk_bf16_f32 v102, v96, v97
	global_store_dwordx4 v[192:193], v[100:103], off offset:256
	v_cvt_pk_bf16_f32 v121, v126, v127
	v_cvt_pk_bf16_f32 v122, v122, v123
	v_or_b32_e32 v100, 32, v146
	v_ashrrev_i32_e32 v101, 31, v100
	v_lshlrev_b64 v[96:97], 10, v[100:101]
	v_cvt_pk_bf16_f32 v123, v158, v159
	v_lshl_add_u64 v[96:97], v[96:97], 0, v[144:145]
	global_store_dwordx4 v[190:191], v[120:123], off
	v_lshlrev_b64 v[108:109], 1, v[96:97]
	v_lshlrev_b64 v[100:101], 11, v[100:101]
	v_lshl_add_u64 v[96:97], s[6:7], 0, v[108:109]
	v_lshl_add_u64 v[158:159], v[148:149], 0, v[100:101]
	global_load_dwordx4 v[96:99], v[96:97], off
	v_or_b32_e32 v108, 0x100, v108
	global_load_dwordx4 v[100:103], v[158:159], off
	v_lshl_add_u64 v[104:105], s[6:7], 0, v[108:109]
	v_lshl_add_u64 v[108:109], s[0:1], 0, v[108:109]
	v_or_b32_e32 v116, 48, v146
	global_load_dwordx4 v[104:107], v[104:105], off
	v_ashrrev_i32_e32 v117, 31, v116
	global_load_dwordx4 v[108:111], v[108:109], off
	v_lshlrev_b64 v[112:113], 10, v[116:117]
	v_lshl_add_u64 v[112:113], v[112:113], 0, v[144:145]
	v_lshlrev_b64 v[124:125], 1, v[112:113]
	v_lshlrev_b64 v[116:117], 11, v[116:117]
	v_lshl_add_u64 v[112:113], s[6:7], 0, v[124:125]
	v_lshl_add_u64 v[160:161], v[148:149], 0, v[116:117]
	global_load_dwordx4 v[112:115], v[112:113], off
	v_or_b32_e32 v124, 0x100, v124
	global_load_dwordx4 v[116:119], v[160:161], off
	v_lshl_add_u64 v[120:121], s[6:7], 0, v[124:125]
	v_lshl_add_u64 v[124:125], s[0:1], 0, v[124:125]
	global_load_dwordx4 v[120:123], v[120:121], off
	s_waitcnt vmcnt(6)
	v_lshlrev_b32_e32 v162, 16, v96
	global_load_dwordx4 v[124:127], v[124:125], off
	v_and_b32_e32 v163, 0xffff0000, v96
	v_lshlrev_b32_e32 v96, 16, v97
	v_and_b32_e32 v97, 0xffff0000, v97
	s_waitcnt vmcnt(6)
; __device__ __forceinline__ u32x2 pack4(f32x4 v) { u32x2 w; w.x = cvt_pk_bf16(v[0], v[1]); w.y = cvt_pk_bf16(v[2], v[3]); return w; }
; __device__ __forceinline__ f32x4 unpack4(u32x2 w) { f32x4 v; v[0] = __uint_as_float(w.x << 16); v[1] = __uint_as_float(w.x & 0xffff0000u); v[2] = __uint_as_float(w.y << 16); v[3] = __uint_as_float(w.y & 0xffff0000u); return v; }
;     __device__ __forceinline__ void operator()(const f32x4 (&acc)[2][2][4][2], const Unit& u, int wr, int wc, int fr, int fq) const {
;     ...
;             for (int m = mh; m < mh + 2; ++m)
; #pragma unroll
;                 for (int bj = 0; bj < 2; ++bj)
; #pragma unroll
;                     for (int n = 0; n < 2; ++n) { const size_t off = (size_t)(row0 + ai * HALF + m * 16) * 1024 + col0 + bj * HALF + n * 4;
;                         pg[m][bj][n] = *(const u32x2*)(G + off); if (ADD) pm_[m][bj][n] = *(const u32x2*)(Mg + off); }
;             asm volatile("" ::: "memory");
; #pragma unroll
;             for (int m = mh; m < mh + 2; ++m)
; #pragma unroll
;                 for (int bj = 0; bj < 2; ++bj)
; #pragma unroll
;                     for (int n = 0; n < 2; ++n) { const size_t off = (size_t)(row0 + ai * HALF + m * 16) * 1024 + col0 + bj * HALF + n * 4;
;                         f32x4 o = unpack4(pg[m][bj][n]) * acc[ai][bj][m][n]; if (ADD) o = o + unpack4(pm_[m][bj][n]);
;                         *(u32x2*)(Mg + off) = pack4(o); }
;             asm volatile("" ::: "memory");
;         }
	v_lshlrev_b32_e32 v164, 16, v100
	v_and_b32_e32 v165, 0xffff0000, v100
	v_lshlrev_b32_e32 v100, 16, v101
	v_and_b32_e32 v101, 0xffff0000, v101
	v_pk_fma_f32 v[94:95], v[94:95], v[96:97], v[100:101]
	v_pk_fma_f32 v[92:93], v[92:93], v[162:163], v[164:165]
	v_lshlrev_b32_e32 v96, 16, v99
	v_cvt_pk_bf16_f32 v92, v92, v93
	v_cvt_pk_bf16_f32 v93, v94, v95
	v_lshlrev_b32_e32 v94, 16, v98
	v_and_b32_e32 v95, 0xffff0000, v98
	v_and_b32_e32 v97, 0xffff0000, v99
	v_lshlrev_b32_e32 v98, 16, v102
	v_and_b32_e32 v99, 0xffff0000, v102
	v_lshlrev_b32_e32 v100, 16, v103
	v_and_b32_e32 v101, 0xffff0000, v103
	v_pk_fma_f32 v[90:91], v[90:91], v[96:97], v[100:101]
	v_pk_fma_f32 v[88:89], v[88:89], v[94:95], v[98:99]
	v_cvt_pk_bf16_f32 v95, v90, v91
	v_cvt_pk_bf16_f32 v94, v88, v89
	global_store_dwordx4 v[158:159], v[92:95], off
	s_waitcnt vmcnt(6)
	v_lshlrev_b32_e32 v88, 16, v104
	v_and_b32_e32 v89, 0xffff0000, v104
	v_lshlrev_b32_e32 v90, 16, v105
	v_and_b32_e32 v91, 0xffff0000, v105
	s_waitcnt vmcnt(5)
	v_lshlrev_b32_e32 v92, 16, v108
	v_and_b32_e32 v93, 0xffff0000, v108
	v_lshlrev_b32_e32 v94, 16, v109
	v_and_b32_e32 v95, 0xffff0000, v109
	v_pk_fma_f32 v[86:87], v[86:87], v[90:91], v[94:95]
	v_pk_fma_f32 v[84:85], v[84:85], v[88:89], v[92:93]
	v_lshlrev_b32_e32 v88, 16, v107
	v_cvt_pk_bf16_f32 v84, v84, v85
	v_cvt_pk_bf16_f32 v85, v86, v87
	v_lshlrev_b32_e32 v86, 16, v106
	v_and_b32_e32 v87, 0xffff0000, v106
	v_and_b32_e32 v89, 0xffff0000, v107
	v_lshlrev_b32_e32 v90, 16, v110
	v_and_b32_e32 v91, 0xffff0000, v110
	v_lshlrev_b32_e32 v92, 16, v111
	v_and_b32_e32 v93, 0xffff0000, v111
	v_pk_fma_f32 v[78:79], v[78:79], v[88:89], v[92:93]
	v_pk_fma_f32 v[76:77], v[76:77], v[86:87], v[90:91]
	v_cvt_pk_bf16_f32 v87, v78, v79
	v_cvt_pk_bf16_f32 v86, v76, v77
	global_store_dwordx4 v[158:159], v[84:87], off offset:256
	s_waitcnt vmcnt(5)
	v_lshlrev_b32_e32 v76, 16, v112
	v_and_b32_e32 v77, 0xffff0000, v112
	v_lshlrev_b32_e32 v78, 16, v113
	v_and_b32_e32 v79, 0xffff0000, v113
	s_waitcnt vmcnt(4)
	v_lshlrev_b32_e32 v84, 16, v116
	v_and_b32_e32 v85, 0xffff0000, v116
	v_lshlrev_b32_e32 v86, 16, v117
	v_and_b32_e32 v87, 0xffff0000, v117
	v_pk_fma_f32 v[78:79], v[82:83], v[78:79], v[86:87]
	v_pk_fma_f32 v[76:77], v[80:81], v[76:77], v[84:85]
	v_lshlrev_b32_e32 v80, 16, v115
	v_cvt_pk_bf16_f32 v76, v76, v77
	v_cvt_pk_bf16_f32 v77, v78, v79
	v_lshlrev_b32_e32 v78, 16, v114
	v_and_b32_e32 v79, 0xffff0000, v114
	v_and_b32_e32 v81, 0xffff0000, v115
	v_lshlrev_b32_e32 v82, 16, v118
	v_and_b32_e32 v83, 0xffff0000, v118
	v_lshlrev_b32_e32 v84, 16, v119
	v_and_b32_e32 v85, 0xffff0000, v119
	v_pk_fma_f32 v[74:75], v[74:75], v[80:81], v[84:85]
	v_pk_fma_f32 v[72:73], v[72:73], v[78:79], v[82:83]
	v_cvt_pk_bf16_f32 v79, v74, v75
	v_cvt_pk_bf16_f32 v78, v72, v73
	global_store_dwordx4 v[160:161], v[76:79], off
	s_waitcnt vmcnt(4)
	v_lshlrev_b32_e32 v72, 16, v120
	v_and_b32_e32 v73, 0xffff0000, v120
	v_lshlrev_b32_e32 v74, 16, v121
	v_and_b32_e32 v75, 0xffff0000, v121
	s_waitcnt vmcnt(3)
	v_lshlrev_b32_e32 v76, 16, v124
	v_and_b32_e32 v77, 0xffff0000, v124
	v_lshlrev_b32_e32 v78, 16, v125
	v_and_b32_e32 v79, 0xffff0000, v125
	v_pk_fma_f32 v[70:71], v[70:71], v[74:75], v[78:79]
	v_pk_fma_f32 v[68:69], v[68:69], v[72:73], v[76:77]
	v_lshlrev_b32_e32 v72, 16, v123
	v_cvt_pk_bf16_f32 v68, v68, v69
	v_cvt_pk_bf16_f32 v69, v70, v71
	v_lshlrev_b32_e32 v70, 16, v122
	v_and_b32_e32 v71, 0xffff0000, v122
	v_and_b32_e32 v73, 0xffff0000, v123
	v_lshlrev_b32_e32 v74, 16, v126
	v_and_b32_e32 v75, 0xffff0000, v126
	v_lshlrev_b32_e32 v76, 16, v127
	v_and_b32_e32 v77, 0xffff0000, v127
	v_pk_fma_f32 v[66:67], v[66:67], v[72:73], v[76:77]
	v_pk_fma_f32 v[64:65], v[64:65], v[70:71], v[74:75]
	v_cvt_pk_bf16_f32 v71, v66, v67
	v_cvt_pk_bf16_f32 v70, v64, v65
	global_store_dwordx4 v[160:161], v[68:71], off offset:256
	v_add_u32_e32 v84, 0x90, v146
	v_ashrrev_i32_e32 v85, 31, v84
	v_add_u32_e32 v68, 0x80, v146
	v_ashrrev_i32_e32 v69, 31, v68
	v_lshlrev_b64 v[64:65], 10, v[68:69]
	v_lshl_add_u64 v[64:65], v[64:65], 0, v[144:145]
	v_lshlrev_b64 v[76:77], 1, v[64:65]
	v_lshlrev_b64 v[68:69], 11, v[68:69]
	v_lshl_add_u64 v[64:65], s[6:7], 0, v[76:77]
	v_lshl_add_u64 v[96:97], v[148:149], 0, v[68:69]
	global_load_dwordx4 v[64:67], v[64:65], off
	v_or_b32_e32 v76, 0x100, v76
	global_load_dwordx4 v[68:71], v[96:97], off
	v_lshl_add_u64 v[72:73], s[6:7], 0, v[76:77]
	v_lshl_add_u64 v[76:77], s[0:1], 0, v[76:77]
	global_load_dwordx4 v[72:75], v[72:73], off
	v_lshlrev_b64 v[80:81], 10, v[84:85]
	global_load_dwordx4 v[76:79], v[76:77], off
	v_lshl_add_u64 v[80:81], v[80:81], 0, v[144:145]
	v_lshlrev_b64 v[92:93], 1, v[80:81]
	v_lshlrev_b64 v[84:85], 11, v[84:85]
	v_lshl_add_u64 v[80:81], s[6:7], 0, v[92:93]
	v_lshl_add_u64 v[98:99], v[148:149], 0, v[84:85]
	global_load_dwordx4 v[80:83], v[80:81], off
	v_or_b32_e32 v92, 0x100, v92
	global_load_dwordx4 v[84:87], v[98:99], off
	v_lshl_add_u64 v[88:89], s[6:7], 0, v[92:93]
	v_lshl_add_u64 v[92:93], s[0:1], 0, v[92:93]
	global_load_dwordx4 v[88:91], v[88:89], off
	s_waitcnt vmcnt(6)
	v_lshlrev_b32_e32 v100, 16, v64
	global_load_dwordx4 v[92:95], v[92:93], off
	v_and_b32_e32 v101, 0xffff0000, v64
	v_lshlrev_b32_e32 v64, 16, v65
	v_and_b32_e32 v65, 0xffff0000, v65
	s_waitcnt vmcnt(6)
; __device__ __forceinline__ u32x2 pack4(f32x4 v) { u32x2 w; w.x = cvt_pk_bf16(v[0], v[1]); w.y = cvt_pk_bf16(v[2], v[3]); return w; }
; __device__ __forceinline__ f32x4 unpack4(u32x2 w) { f32x4 v; v[0] = __uint_as_float(w.x << 16); v[1] = __uint_as_float(w.x & 0xffff0000u); v[2] = __uint_as_float(w.y << 16); v[3] = __uint_as_float(w.y & 0xffff0000u); return v; }
;     __device__ __forceinline__ void operator()(const f32x4 (&acc)[2][2][4][2], const Unit& u, int wr, int wc, int fr, int fq) const {
;     ...
;             for (int m = mh; m < mh + 2; ++m)
; #pragma unroll
;                 for (int bj = 0; bj < 2; ++bj)
; #pragma unroll
;                     for (int n = 0; n < 2; ++n) { const size_t off = (size_t)(row0 + ai * HALF + m * 16) * 1024 + col0 + bj * HALF + n * 4;
;                         pg[m][bj][n] = *(const u32x2*)(G + off); if (ADD) pm_[m][bj][n] = *(const u32x2*)(Mg + off); }
;             asm volatile("" ::: "memory");
; #pragma unroll
;             for (int m = mh; m < mh + 2; ++m)
; #pragma unroll
;                 for (int bj = 0; bj < 2; ++bj)
; #pragma unroll
;                     for (int n = 0; n < 2; ++n) { const size_t off = (size_t)(row0 + ai * HALF + m * 16) * 1024 + col0 + bj * HALF + n * 4;
;                         f32x4 o = unpack4(pg[m][bj][n]) * acc[ai][bj][m][n]; if (ADD) o = o + unpack4(pm_[m][bj][n]);
;                         *(u32x2*)(Mg + off) = pack4(o); }
;             asm volatile("" ::: "memory");
;         }
	v_lshlrev_b32_e32 v102, 16, v68
	v_and_b32_e32 v103, 0xffff0000, v68
	v_lshlrev_b32_e32 v68, 16, v69
	v_and_b32_e32 v69, 0xffff0000, v69
	v_pk_fma_f32 v[62:63], v[62:63], v[64:65], v[68:69]
	v_pk_fma_f32 v[60:61], v[60:61], v[100:101], v[102:103]
	v_lshlrev_b32_e32 v64, 16, v67
	v_cvt_pk_bf16_f32 v60, v60, v61
	v_cvt_pk_bf16_f32 v61, v62, v63
	v_lshlrev_b32_e32 v62, 16, v66
	v_and_b32_e32 v63, 0xffff0000, v66
	v_and_b32_e32 v65, 0xffff0000, v67
	v_lshlrev_b32_e32 v66, 16, v70
	v_and_b32_e32 v67, 0xffff0000, v70
	v_lshlrev_b32_e32 v68, 16, v71
	v_and_b32_e32 v69, 0xffff0000, v71
	v_pk_fma_f32 v[58:59], v[58:59], v[64:65], v[68:69]
	v_pk_fma_f32 v[56:57], v[56:57], v[62:63], v[66:67]
	v_cvt_pk_bf16_f32 v63, v58, v59
	v_cvt_pk_bf16_f32 v62, v56, v57
	global_store_dwordx4 v[96:97], v[60:63], off
	s_waitcnt vmcnt(6)
	v_lshlrev_b32_e32 v56, 16, v72
	v_and_b32_e32 v57, 0xffff0000, v72
	v_lshlrev_b32_e32 v58, 16, v73
	v_and_b32_e32 v59, 0xffff0000, v73
	s_waitcnt vmcnt(5)
	v_lshlrev_b32_e32 v60, 16, v76
	v_and_b32_e32 v61, 0xffff0000, v76
	v_lshlrev_b32_e32 v62, 16, v77
	v_and_b32_e32 v63, 0xffff0000, v77
	v_pk_fma_f32 v[54:55], v[54:55], v[58:59], v[62:63]
	v_pk_fma_f32 v[52:53], v[52:53], v[56:57], v[60:61]
	v_lshlrev_b32_e32 v56, 16, v75
	v_cvt_pk_bf16_f32 v52, v52, v53
	v_cvt_pk_bf16_f32 v53, v54, v55
	v_lshlrev_b32_e32 v54, 16, v74
	v_and_b32_e32 v55, 0xffff0000, v74
	v_and_b32_e32 v57, 0xffff0000, v75
	v_lshlrev_b32_e32 v58, 16, v78
	v_and_b32_e32 v59, 0xffff0000, v78
	v_lshlrev_b32_e32 v60, 16, v79
	v_and_b32_e32 v61, 0xffff0000, v79
	v_pk_fma_f32 v[46:47], v[46:47], v[56:57], v[60:61]
	v_pk_fma_f32 v[44:45], v[44:45], v[54:55], v[58:59]
	v_cvt_pk_bf16_f32 v55, v46, v47
	v_cvt_pk_bf16_f32 v54, v44, v45
	global_store_dwordx4 v[96:97], v[52:55], off offset:256
	s_waitcnt vmcnt(5)
	v_lshlrev_b32_e32 v44, 16, v80
	v_and_b32_e32 v45, 0xffff0000, v80
	v_lshlrev_b32_e32 v46, 16, v81
	v_and_b32_e32 v47, 0xffff0000, v81
	s_waitcnt vmcnt(4)
	v_lshlrev_b32_e32 v52, 16, v84
	v_and_b32_e32 v53, 0xffff0000, v84
	v_lshlrev_b32_e32 v54, 16, v85
	v_and_b32_e32 v55, 0xffff0000, v85
	v_pk_fma_f32 v[46:47], v[50:51], v[46:47], v[54:55]
	v_pk_fma_f32 v[44:45], v[48:49], v[44:45], v[52:53]
	v_lshlrev_b32_e32 v48, 16, v83
	v_cvt_pk_bf16_f32 v44, v44, v45
	v_cvt_pk_bf16_f32 v45, v46, v47
	v_lshlrev_b32_e32 v46, 16, v82
	v_and_b32_e32 v47, 0xffff0000, v82
	v_and_b32_e32 v49, 0xffff0000, v83
	v_lshlrev_b32_e32 v50, 16, v86
	v_and_b32_e32 v51, 0xffff0000, v86
	v_lshlrev_b32_e32 v52, 16, v87
	v_and_b32_e32 v53, 0xffff0000, v87
	v_pk_fma_f32 v[42:43], v[42:43], v[48:49], v[52:53]
	v_pk_fma_f32 v[40:41], v[40:41], v[46:47], v[50:51]
	v_cvt_pk_bf16_f32 v47, v42, v43
	v_cvt_pk_bf16_f32 v46, v40, v41
	global_store_dwordx4 v[98:99], v[44:47], off
	s_waitcnt vmcnt(4)
	v_lshlrev_b32_e32 v40, 16, v88
	v_and_b32_e32 v41, 0xffff0000, v88
	v_lshlrev_b32_e32 v42, 16, v89
	v_and_b32_e32 v43, 0xffff0000, v89
	s_waitcnt vmcnt(3)
	v_lshlrev_b32_e32 v44, 16, v92
	v_and_b32_e32 v45, 0xffff0000, v92
	v_lshlrev_b32_e32 v46, 16, v93
	v_and_b32_e32 v47, 0xffff0000, v93
	v_pk_fma_f32 v[38:39], v[38:39], v[42:43], v[46:47]
	v_pk_fma_f32 v[36:37], v[36:37], v[40:41], v[44:45]
	v_lshlrev_b32_e32 v40, 16, v91
	v_cvt_pk_bf16_f32 v36, v36, v37
	v_cvt_pk_bf16_f32 v37, v38, v39
	v_lshlrev_b32_e32 v38, 16, v90
	v_and_b32_e32 v39, 0xffff0000, v90
	v_and_b32_e32 v41, 0xffff0000, v91
	v_lshlrev_b32_e32 v42, 16, v94
	v_and_b32_e32 v43, 0xffff0000, v94
	v_lshlrev_b32_e32 v44, 16, v95
	v_and_b32_e32 v45, 0xffff0000, v95
	v_pk_fma_f32 v[34:35], v[34:35], v[40:41], v[44:45]
	v_pk_fma_f32 v[32:33], v[32:33], v[38:39], v[42:43]
	v_cvt_pk_bf16_f32 v39, v34, v35
	v_cvt_pk_bf16_f32 v38, v32, v33
	global_store_dwordx4 v[98:99], v[36:39], off offset:256
	v_add_u32_e32 v52, 0xb0, v146
	v_ashrrev_i32_e32 v53, 31, v52
	v_add_u32_e32 v36, 0xa0, v146
	v_ashrrev_i32_e32 v37, 31, v36
	v_lshlrev_b64 v[32:33], 10, v[36:37]
	v_lshl_add_u64 v[32:33], v[32:33], 0, v[144:145]
	v_lshlrev_b64 v[44:45], 1, v[32:33]
	v_lshlrev_b64 v[36:37], 11, v[36:37]
	v_lshl_add_u64 v[32:33], s[6:7], 0, v[44:45]
	v_lshl_add_u64 v[64:65], v[148:149], 0, v[36:37]
	global_load_dwordx4 v[32:35], v[32:33], off
	v_or_b32_e32 v44, 0x100, v44
	global_load_dwordx4 v[36:39], v[64:65], off
	v_lshl_add_u64 v[40:41], s[6:7], 0, v[44:45]
	v_lshl_add_u64 v[44:45], s[0:1], 0, v[44:45]
	global_load_dwordx4 v[40:43], v[40:41], off
	v_lshlrev_b64 v[48:49], 10, v[52:53]
	global_load_dwordx4 v[44:47], v[44:45], off
	v_lshl_add_u64 v[48:49], v[48:49], 0, v[144:145]
	v_lshlrev_b64 v[60:61], 1, v[48:49]
	v_lshlrev_b64 v[52:53], 11, v[52:53]
	v_lshl_add_u64 v[48:49], s[6:7], 0, v[60:61]
	v_lshl_add_u64 v[66:67], v[148:149], 0, v[52:53]
	global_load_dwordx4 v[48:51], v[48:49], off
	v_or_b32_e32 v60, 0x100, v60
	global_load_dwordx4 v[52:55], v[66:67], off
	v_lshl_add_u64 v[56:57], s[6:7], 0, v[60:61]
	v_lshl_add_u64 v[60:61], s[0:1], 0, v[60:61]
	global_load_dwordx4 v[56:59], v[56:57], off
	s_waitcnt vmcnt(6)
; __device__ __forceinline__ u32x2 pack4(f32x4 v) { u32x2 w; w.x = cvt_pk_bf16(v[0], v[1]); w.y = cvt_pk_bf16(v[2], v[3]); return w; }
; __device__ __forceinline__ f32x4 unpack4(u32x2 w) { f32x4 v; v[0] = __uint_as_float(w.x << 16); v[1] = __uint_as_float(w.x & 0xffff0000u); v[2] = __uint_as_float(w.y << 16); v[3] = __uint_as_float(w.y & 0xffff0000u); return v; }
;     __device__ __forceinline__ void operator()(const f32x4 (&acc)[2][2][4][2], const Unit& u, int wr, int wc, int fr, int fq) const {
;     ...
;             for (int m = mh; m < mh + 2; ++m)
; #pragma unroll
;                 for (int bj = 0; bj < 2; ++bj)
; #pragma unroll
;                     for (int n = 0; n < 2; ++n) { const size_t off = (size_t)(row0 + ai * HALF + m * 16) * 1024 + col0 + bj * HALF + n * 4;
;                         pg[m][bj][n] = *(const u32x2*)(G + off); if (ADD) pm_[m][bj][n] = *(const u32x2*)(Mg + off); }
;             asm volatile("" ::: "memory");
; #pragma unroll
;             for (int m = mh; m < mh + 2; ++m)
; #pragma unroll
;                 for (int bj = 0; bj < 2; ++bj)
; #pragma unroll
;                     for (int n = 0; n < 2; ++n) { const size_t off = (size_t)(row0 + ai * HALF + m * 16) * 1024 + col0 + bj * HALF + n * 4;
;                         f32x4 o = unpack4(pg[m][bj][n]) * acc[ai][bj][m][n]; if (ADD) o = o + unpack4(pm_[m][bj][n]);
;                         *(u32x2*)(Mg + off) = pack4(o); }
;             asm volatile("" ::: "memory");
;         }
	v_lshlrev_b32_e32 v68, 16, v32
	global_load_dwordx4 v[60:63], v[60:61], off
	v_and_b32_e32 v69, 0xffff0000, v32
	v_lshlrev_b32_e32 v32, 16, v33
	v_and_b32_e32 v33, 0xffff0000, v33
	s_waitcnt vmcnt(6)
	v_lshlrev_b32_e32 v70, 16, v36
	v_and_b32_e32 v71, 0xffff0000, v36
	v_lshlrev_b32_e32 v36, 16, v37
	v_and_b32_e32 v37, 0xffff0000, v37
	v_pk_fma_f32 v[30:31], v[30:31], v[32:33], v[36:37]
	v_pk_fma_f32 v[28:29], v[28:29], v[68:69], v[70:71]
	v_lshlrev_b32_e32 v32, 16, v35
	v_cvt_pk_bf16_f32 v28, v28, v29
	v_cvt_pk_bf16_f32 v29, v30, v31
	v_lshlrev_b32_e32 v30, 16, v34
	v_and_b32_e32 v31, 0xffff0000, v34
	v_and_b32_e32 v33, 0xffff0000, v35
	v_lshlrev_b32_e32 v34, 16, v38
	v_and_b32_e32 v35, 0xffff0000, v38
	v_lshlrev_b32_e32 v36, 16, v39
	v_and_b32_e32 v37, 0xffff0000, v39
	v_pk_fma_f32 v[26:27], v[26:27], v[32:33], v[36:37]
	v_pk_fma_f32 v[24:25], v[24:25], v[30:31], v[34:35]
	v_cvt_pk_bf16_f32 v31, v26, v27
	v_cvt_pk_bf16_f32 v30, v24, v25
	global_store_dwordx4 v[64:65], v[28:31], off
	s_waitcnt vmcnt(6)
	v_lshlrev_b32_e32 v24, 16, v40
	v_and_b32_e32 v25, 0xffff0000, v40
	v_lshlrev_b32_e32 v26, 16, v41
	v_and_b32_e32 v27, 0xffff0000, v41
	s_waitcnt vmcnt(5)
	v_lshlrev_b32_e32 v28, 16, v44
	v_and_b32_e32 v29, 0xffff0000, v44
	v_lshlrev_b32_e32 v30, 16, v45
	v_and_b32_e32 v31, 0xffff0000, v45
	v_pk_fma_f32 v[22:23], v[22:23], v[26:27], v[30:31]
	v_pk_fma_f32 v[20:21], v[20:21], v[24:25], v[28:29]
	v_lshlrev_b32_e32 v24, 16, v43
	v_cvt_pk_bf16_f32 v20, v20, v21
	v_cvt_pk_bf16_f32 v21, v22, v23
	v_lshlrev_b32_e32 v22, 16, v42
	v_and_b32_e32 v23, 0xffff0000, v42
	v_and_b32_e32 v25, 0xffff0000, v43
	v_lshlrev_b32_e32 v26, 16, v46
	v_and_b32_e32 v27, 0xffff0000, v46
	v_lshlrev_b32_e32 v28, 16, v47
	v_and_b32_e32 v29, 0xffff0000, v47
	v_pk_fma_f32 v[14:15], v[14:15], v[24:25], v[28:29]
	v_pk_fma_f32 v[12:13], v[12:13], v[22:23], v[26:27]
	v_cvt_pk_bf16_f32 v23, v14, v15
	v_cvt_pk_bf16_f32 v22, v12, v13
	global_store_dwordx4 v[64:65], v[20:23], off offset:256
	s_waitcnt vmcnt(5)
	v_lshlrev_b32_e32 v12, 16, v48
	v_and_b32_e32 v13, 0xffff0000, v48
	v_lshlrev_b32_e32 v14, 16, v49
	v_and_b32_e32 v15, 0xffff0000, v49
	s_waitcnt vmcnt(4)
	v_lshlrev_b32_e32 v20, 16, v52
	v_and_b32_e32 v21, 0xffff0000, v52
	v_lshlrev_b32_e32 v22, 16, v53
	v_and_b32_e32 v23, 0xffff0000, v53
	v_pk_fma_f32 v[14:15], v[18:19], v[14:15], v[22:23]
	v_pk_fma_f32 v[12:13], v[16:17], v[12:13], v[20:21]
	v_lshlrev_b32_e32 v16, 16, v51
	v_cvt_pk_bf16_f32 v12, v12, v13
	v_cvt_pk_bf16_f32 v13, v14, v15
	v_lshlrev_b32_e32 v14, 16, v50
	v_and_b32_e32 v15, 0xffff0000, v50
	v_and_b32_e32 v17, 0xffff0000, v51
	v_lshlrev_b32_e32 v18, 16, v54
	v_and_b32_e32 v19, 0xffff0000, v54
	v_lshlrev_b32_e32 v20, 16, v55
	v_and_b32_e32 v21, 0xffff0000, v55
	v_pk_fma_f32 v[10:11], v[10:11], v[16:17], v[20:21]
	v_pk_fma_f32 v[8:9], v[8:9], v[14:15], v[18:19]
	v_cvt_pk_bf16_f32 v15, v10, v11
	v_cvt_pk_bf16_f32 v14, v8, v9
	global_store_dwordx4 v[66:67], v[12:15], off
	s_waitcnt vmcnt(4)
	v_lshlrev_b32_e32 v8, 16, v56
	v_and_b32_e32 v9, 0xffff0000, v56
	v_lshlrev_b32_e32 v10, 16, v57
	v_and_b32_e32 v11, 0xffff0000, v57
	s_waitcnt vmcnt(3)
	v_lshlrev_b32_e32 v12, 16, v60
	v_and_b32_e32 v13, 0xffff0000, v60
	v_lshlrev_b32_e32 v14, 16, v61
	v_and_b32_e32 v15, 0xffff0000, v61
	v_pk_fma_f32 v[6:7], v[6:7], v[10:11], v[14:15]
	v_pk_fma_f32 v[4:5], v[4:5], v[8:9], v[12:13]
	v_lshlrev_b32_e32 v8, 16, v59
	v_cvt_pk_bf16_f32 v4, v4, v5
	v_cvt_pk_bf16_f32 v5, v6, v7
	v_lshlrev_b32_e32 v6, 16, v58
	v_and_b32_e32 v7, 0xffff0000, v58
	v_and_b32_e32 v9, 0xffff0000, v59
	v_lshlrev_b32_e32 v10, 16, v62
	v_and_b32_e32 v11, 0xffff0000, v62
	v_lshlrev_b32_e32 v12, 16, v63
	v_and_b32_e32 v13, 0xffff0000, v63
	v_pk_fma_f32 v[2:3], v[2:3], v[8:9], v[12:13]
	v_pk_fma_f32 v[0:1], v[0:1], v[6:7], v[10:11]
	v_cvt_pk_bf16_f32 v7, v2, v3
	v_cvt_pk_bf16_f32 v6, v0, v1
	global_store_dwordx4 v[66:67], v[4:7], off offset:256
	s_cbranch_vccz .LBB0_744
	s_waitcnt vmcnt(0)
	s_cmpk_gt_u32 s40, 0xff
	s_cbranch_scc1 .LBB0_751
	s_barrier

; #define PG8_STAGE(bufoff, gbase, voff) do { _Pragma("unroll") for (int _i = 0; _i < 2; ++_i) \
;         __builtin_amdgcn_global_load_lds((const unsigned*)((const char*)(gbase) + (voff)[_i]), (PG8_LAS unsigned*)(lds + (bufoff) + ldsw + _i * 8192), 16, 0, 0); } while (0)
; #define PG8_LDA(dst, b, h) do { _Pragma("unroll") for (int m = 0; m < 4; ++m) _Pragma("unroll") for (int k = 0; k < 2; ++k) dst[m][k] = *(const PG8_LAS bf16x8*)(lds + PG8_SA(b, h) + aoff + m * 2048 + k * 1024); } while (0)
; #define PG8_LDB(dst, b, h) do { _Pragma("unroll") for (int n = 0; n < 2; ++n) _Pragma("unroll") for (int k = 0; k < 2; ++k) dst[n][k] = *(const PG8_LAS bf16x8*)(lds + PG8_SB(b, h) + boff + n * 2048 + k * 1024); } while (0)
; #define PG8_MMA(ai, bj, At, Bt) do { __builtin_amdgcn_s_setprio(1); _Pragma("unroll") for (int m = 0; m < 4; ++m) _Pragma("unroll") for (int n = 0; n < 2; ++n) _Pragma("unroll") for (int k = 0; k < 2; ++k) \
;         acc[ai][bj][m][n] = __builtin_amdgcn_mfma_f32_16x16x32_bf16(Bt[n][k], At[m][k], acc[ai][bj][m][n], 0, 0, 0); __builtin_amdgcn_s_setprio(0); } while (0)
; #define PG8_WAIT_V(n) asm volatile("s_waitcnt vmcnt(" #n ")" ::: "memory")
; #define PG8_BAR __builtin_amdgcn_s_barrier()
; template <class Epi, class Sched, bool ALIGN_EPI = false, bool SP2 = false>
; __device__ __forceinline__ void gemm_phase(PG8_LAS unsigned char* lds, const Gemm g, const Sched& S, const Epi& E) {
;     ...
;         for (int t = 0; t < nt; t += 2) {
;             const bool last = (t == nt - 2);
;             const char* a1 = cA + (size_t)(t + 1) * kstep;
;             const char* a2 = last ? nA : cA + (size_t)(t + 2) * kstep; const char* b2 = last ? nB : cB + (size_t)(t + 2) * kstep;
;             const char* a3 = a2 + kstep; const char* b3 = b2 + kstep;
;             if (last && has_next) S.a_ready(nxt);
;             if constexpr (SP2) {
;             PG8_LDB(B0, 0, 0); PG8_LDB(B1, 0, 1); PG8_SCHED; PG8_LDA(At, 0, 0); PG8_STAGE(PG8_SA(1, 1), a1 + hstep, voffA);
;             PG8_WAIT_V(8); PG8_WAIT_L(0); PG8_BAR; PG8_MMA(0, 0, At, B0); PG8_MMA(0, 1, At, B1); PG8_BAR; PG8_SCHED;
;             PG8_LDA(At, 0, 1); PG8_STAGE(PG8_SB(0, 0), b2, voffB); PG8_STAGE(PG8_SB(0, 1), b2 + hstep, voffB); PG8_STAGE(PG8_SA(0, 0), a2, voffA);
;             PG8_WAIT_V(8); PG8_WAIT_L(0); PG8_BAR; PG8_MMA(1, 0, At, B0); PG8_MMA(1, 1, At, B1); PG8_BAR; PG8_SCHED;
.LBB0_813:
	ds_read_b128 v[128:131], v173
	ds_read_b128 v[132:135], v173 offset:1024
	ds_read_b128 v[136:139], v173 offset:2048
	ds_read_b128 v[140:143], v173 offset:3072
	ds_read_b128 v[160:163], v174
	ds_read_b128 v[164:167], v174 offset:1024
	ds_read_b128 v[178:181], v174 offset:2048
	ds_read_b128 v[182:185], v174 offset:3072
	s_add_u32 s26, s24, 0xfffc0080
	s_addc_u32 s27, s25, -1
	s_cmp_eq_u32 s70, 12
	s_cselect_b32 s37, s15, s27
	s_cselect_b32 s36, s60, s26
	s_cselect_b32 s27, s13, s69
	s_cselect_b32 s26, s61, s68
	v_lshl_add_u64 v[168:169], s[24:25], 0, v[152:153]
	s_add_i32 m0, s42, 0xc000
	ds_read_b128 v[186:189], v175
	ds_read_b128 v[190:193], v175 offset:1024
	ds_read_b128 v[194:197], v175 offset:2048
	ds_read_b128 v[198:201], v175 offset:3072
	ds_read_b128 v[202:205], v175 offset:4096
	ds_read_b128 v[206:209], v175 offset:5120
	ds_read_b128 v[210:213], v175 offset:6144
	ds_read_b128 v[214:217], v175 offset:7168
	global_load_lds_dwordx4 v[168:169], off
	v_lshl_add_u64 v[168:169], s[24:25], 0, v[154:155]
	s_add_i32 m0, s42, 0xe000
	s_nop 0
	global_load_lds_dwordx4 v[168:169], off
	s_waitcnt vmcnt(8)
	s_waitcnt lgkmcnt(0)
	s_setprio 1
	s_barrier
	v_mfma_f32_16x16x32_bf16 v[124:127], v[128:131], v[186:189], v[124:127]
	v_mfma_f32_16x16x32_bf16 v[120:123], v[136:139], v[186:189], v[120:123]
	v_mfma_f32_16x16x32_bf16 v[108:111], v[128:131], v[194:197], v[108:111]
	v_mfma_f32_16x16x32_bf16 v[104:107], v[136:139], v[194:197], v[104:107]
	v_mfma_f32_16x16x32_bf16 v[92:95], v[128:131], v[202:205], v[92:95]
	v_mfma_f32_16x16x32_bf16 v[88:91], v[136:139], v[202:205], v[88:91]
	v_mfma_f32_16x16x32_bf16 v[76:79], v[128:131], v[210:213], v[76:79]
	v_mfma_f32_16x16x32_bf16 v[72:75], v[136:139], v[210:213], v[72:75]
	v_mfma_f32_16x16x32_bf16 v[124:127], v[132:135], v[190:193], v[124:127]
	v_mfma_f32_16x16x32_bf16 v[120:123], v[140:143], v[190:193], v[120:123]
	v_mfma_f32_16x16x32_bf16 v[108:111], v[132:135], v[198:201], v[108:111]
	v_mfma_f32_16x16x32_bf16 v[104:107], v[140:143], v[198:201], v[104:107]
	v_mfma_f32_16x16x32_bf16 v[92:95], v[132:135], v[206:209], v[92:95]
	v_mfma_f32_16x16x32_bf16 v[88:91], v[140:143], v[206:209], v[88:91]
	v_mfma_f32_16x16x32_bf16 v[76:79], v[132:135], v[214:217], v[76:79]
	v_mfma_f32_16x16x32_bf16 v[72:75], v[140:143], v[214:217], v[72:75]
	s_setprio 0
	s_setprio 1
	v_mfma_f32_16x16x32_bf16 v[116:119], v[160:163], v[186:189], v[116:119]
	v_mfma_f32_16x16x32_bf16 v[112:115], v[178:181], v[186:189], v[112:115]
	v_mfma_f32_16x16x32_bf16 v[100:103], v[160:163], v[194:197], v[100:103]
	v_mfma_f32_16x16x32_bf16 v[96:99], v[178:181], v[194:197], v[96:99]
	v_mfma_f32_16x16x32_bf16 v[84:87], v[160:163], v[202:205], v[84:87]
	v_mfma_f32_16x16x32_bf16 v[80:83], v[178:181], v[202:205], v[80:83]
	v_mfma_f32_16x16x32_bf16 v[68:71], v[160:163], v[210:213], v[68:71]
	v_mfma_f32_16x16x32_bf16 v[64:67], v[178:181], v[210:213], v[64:67]
	v_mfma_f32_16x16x32_bf16 v[116:119], v[164:167], v[190:193], v[116:119]
	v_mfma_f32_16x16x32_bf16 v[112:115], v[182:185], v[190:193], v[112:115]
	v_mfma_f32_16x16x32_bf16 v[100:103], v[164:167], v[198:201], v[100:103]
	v_mfma_f32_16x16x32_bf16 v[96:99], v[182:185], v[198:201], v[96:99]
	v_mfma_f32_16x16x32_bf16 v[84:87], v[164:167], v[206:209], v[84:87]
	v_mfma_f32_16x16x32_bf16 v[80:83], v[182:185], v[206:209], v[80:83]
	v_mfma_f32_16x16x32_bf16 v[68:71], v[164:167], v[214:217], v[68:71]
	v_mfma_f32_16x16x32_bf16 v[64:67], v[182:185], v[214:217], v[64:67]
	s_setprio 0
	s_barrier
	s_add_i32 s71, s52, s39
	v_lshl_add_u64 v[168:169], s[26:27], 0, v[148:149]
	s_mov_b32 m0, s71
	ds_read_b128 v[186:189], v175 offset:16384
	ds_read_b128 v[190:193], v175 offset:17408
	ds_read_b128 v[194:197], v175 offset:18432
	ds_read_b128 v[198:201], v175 offset:19456
	ds_read_b128 v[202:205], v175 offset:20480
	ds_read_b128 v[206:209], v175 offset:21504
	ds_read_b128 v[210:213], v175 offset:22528
	ds_read_b128 v[214:217], v175 offset:23552
	global_load_lds_dwordx4 v[168:169], off
	s_add_i32 m0, s71, 0x2000
	s_add_u32 s72, s26, 0x40000
	v_lshl_add_u64 v[218:219], s[26:27], 0, v[144:145]
	s_addc_u32 s73, s27, 0
	s_add_i32 s71, s53, s39
	global_load_lds_dwordx4 v[218:219], off
	v_lshl_add_u64 v[220:221], s[72:73], 0, v[148:149]
	s_mov_b32 m0, s71
	v_lshl_add_u64 v[222:223], s[36:37], 0, v[146:147]
	global_load_lds_dwordx4 v[220:221], off
	v_lshl_add_u64 v[220:221], s[72:73], 0, v[144:145]
	s_add_i32 m0, s71, 0x2000
	s_nop 0
	global_load_lds_dwordx4 v[220:221], off
	s_waitcnt vmcnt(6)
	s_waitcnt lgkmcnt(0)
	s_setprio 1
	s_barrier
; #define PG8_STAGE(bufoff, gbase, voff) do { _Pragma("unroll") for (int _i = 0; _i < 2; ++_i) \
;         __builtin_amdgcn_global_load_lds((const unsigned*)((const char*)(gbase) + (voff)[_i]), (PG8_LAS unsigned*)(lds + (bufoff) + ldsw + _i * 8192), 16, 0, 0); } while (0)
; #define PG8_LDA(dst, b, h) do { _Pragma("unroll") for (int m = 0; m < 4; ++m) _Pragma("unroll") for (int k = 0; k < 2; ++k) dst[m][k] = *(const PG8_LAS bf16x8*)(lds + PG8_SA(b, h) + aoff + m * 2048 + k * 1024); } while (0)
; #define PG8_LDB(dst, b, h) do { _Pragma("unroll") for (int n = 0; n < 2; ++n) _Pragma("unroll") for (int k = 0; k < 2; ++k) dst[n][k] = *(const PG8_LAS bf16x8*)(lds + PG8_SB(b, h) + boff + n * 2048 + k * 1024); } while (0)
; #define PG8_MMA(ai, bj, At, Bt) do { __builtin_amdgcn_s_setprio(1); _Pragma("unroll") for (int m = 0; m < 4; ++m) _Pragma("unroll") for (int n = 0; n < 2; ++n) _Pragma("unroll") for (int k = 0; k < 2; ++k) \
;         acc[ai][bj][m][n] = __builtin_amdgcn_mfma_f32_16x16x32_bf16(Bt[n][k], At[m][k], acc[ai][bj][m][n], 0, 0, 0); __builtin_amdgcn_s_setprio(0); } while (0)
; #define PG8_WAIT_V(n) asm volatile("s_waitcnt vmcnt(" #n ")" ::: "memory")
; #define PG8_WAIT_L(n) asm volatile("s_waitcnt lgkmcnt(" #n ")" ::: "memory")
; #define PG8_BAR __builtin_amdgcn_s_barrier()
; #define PG8_SCHED __builtin_amdgcn_sched_barrier(0)
; template <class Epi, class Sched, bool ALIGN_EPI = false, bool SP2 = false>
; __device__ __forceinline__ void gemm_phase(PG8_LAS unsigned char* lds, const Gemm g, const Sched& S, const Epi& E) {
;     ...
;             PG8_LDA(At, 0, 1); PG8_STAGE(PG8_SB(0, 0), b2, voffB); PG8_STAGE(PG8_SB(0, 1), b2 + hstep, voffB); PG8_STAGE(PG8_SA(0, 0), a2, voffA);
;             PG8_WAIT_V(8); PG8_WAIT_L(0); PG8_BAR; PG8_MMA(1, 0, At, B0); PG8_MMA(1, 1, At, B1); PG8_BAR; PG8_SCHED;
;             PG8_LDB(B0, 1, 0); PG8_LDB(B1, 1, 1); PG8_SCHED; PG8_LDA(At, 1, 0); PG8_STAGE(PG8_SA(0, 1), a2 + hstep, voffA);
;             PG8_WAIT_V(8); PG8_WAIT_L(0); PG8_BAR; PG8_MMA(0, 0, At, B0); PG8_MMA(0, 1, At, B1); PG8_BAR; PG8_SCHED;
	v_mfma_f32_16x16x32_bf16 v[60:63], v[128:131], v[186:189], v[60:63]
	v_mfma_f32_16x16x32_bf16 v[56:59], v[136:139], v[186:189], v[56:59]
	v_mfma_f32_16x16x32_bf16 v[44:47], v[128:131], v[194:197], v[44:47]
	v_mfma_f32_16x16x32_bf16 v[40:43], v[136:139], v[194:197], v[40:43]
	v_mfma_f32_16x16x32_bf16 v[28:31], v[128:131], v[202:205], v[28:31]
	v_mfma_f32_16x16x32_bf16 v[24:27], v[136:139], v[202:205], v[24:27]
	v_lshl_add_u64 v[220:221], s[36:37], 0, v[150:151]
	s_mov_b32 m0, s42
	s_nop 0
	global_load_lds_dwordx4 v[220:221], off
	v_mfma_f32_16x16x32_bf16 v[12:15], v[128:131], v[210:213], v[12:15]
	v_mfma_f32_16x16x32_bf16 v[8:11], v[136:139], v[210:213], v[8:11]
	v_mfma_f32_16x16x32_bf16 v[60:63], v[132:135], v[190:193], v[60:63]
	v_mfma_f32_16x16x32_bf16 v[56:59], v[140:143], v[190:193], v[56:59]
	v_mfma_f32_16x16x32_bf16 v[44:47], v[132:135], v[198:201], v[44:47]
	v_mfma_f32_16x16x32_bf16 v[40:43], v[140:143], v[198:201], v[40:43]
	v_mfma_f32_16x16x32_bf16 v[28:31], v[132:135], v[206:209], v[28:31]
	v_mfma_f32_16x16x32_bf16 v[24:27], v[140:143], v[206:209], v[24:27]
	v_mfma_f32_16x16x32_bf16 v[12:15], v[132:135], v[214:217], v[12:15]
	v_mfma_f32_16x16x32_bf16 v[8:11], v[140:143], v[214:217], v[8:11]
	s_setprio 0
	s_setprio 1
	v_mfma_f32_16x16x32_bf16 v[52:55], v[160:163], v[186:189], v[52:55]
	v_mfma_f32_16x16x32_bf16 v[48:51], v[178:181], v[186:189], v[48:51]
	v_mfma_f32_16x16x32_bf16 v[36:39], v[160:163], v[194:197], v[36:39]
	v_mfma_f32_16x16x32_bf16 v[32:35], v[178:181], v[194:197], v[32:35]
	v_mfma_f32_16x16x32_bf16 v[20:23], v[160:163], v[202:205], v[20:23]
	v_mfma_f32_16x16x32_bf16 v[16:19], v[178:181], v[202:205], v[16:19]
	s_mov_b32 m0, s43
	s_nop 0
	global_load_lds_dwordx4 v[222:223], off
	v_mfma_f32_16x16x32_bf16 v[4:7], v[160:163], v[210:213], v[4:7]
	v_mfma_f32_16x16x32_bf16 v[0:3], v[178:181], v[210:213], v[0:3]
	v_mfma_f32_16x16x32_bf16 v[52:55], v[164:167], v[190:193], v[52:55]
	v_mfma_f32_16x16x32_bf16 v[48:51], v[182:185], v[190:193], v[48:51]
	v_mfma_f32_16x16x32_bf16 v[36:39], v[164:167], v[198:201], v[36:39]
	v_mfma_f32_16x16x32_bf16 v[32:35], v[182:185], v[198:201], v[32:35]
	v_mfma_f32_16x16x32_bf16 v[20:23], v[164:167], v[206:209], v[20:23]
	v_mfma_f32_16x16x32_bf16 v[16:19], v[182:185], v[206:209], v[16:19]
	v_mfma_f32_16x16x32_bf16 v[4:7], v[164:167], v[214:217], v[4:7]
	v_mfma_f32_16x16x32_bf16 v[0:3], v[182:185], v[214:217], v[0:3]
	s_setprio 0
	s_barrier
	s_add_i32 s71, 0, 0x18000
	s_add_i32 s72, 0, 0x1c000
	v_add_u32_e32 v140, s71, v171
	v_add_u32_e32 v177, s72, v171
	ds_read_b128 v[128:131], v140
	ds_read_b128 v[132:135], v140 offset:1024
	ds_read_b128 v[136:139], v140 offset:2048
	ds_read_b128 v[140:143], v140 offset:3072
	ds_read_b128 v[160:163], v177
	ds_read_b128 v[164:167], v177 offset:1024
	ds_read_b128 v[178:181], v177 offset:2048
	ds_read_b128 v[182:185], v177 offset:3072
	s_add_u32 s36, s36, 0x40000
	s_addc_u32 s37, s37, 0
	s_mov_b32 m0, s44
	v_lshl_add_u64 v[224:225], s[36:37], 0, v[150:151]
	ds_read_b128 v[186:189], v175 offset:32768
	ds_read_b128 v[190:193], v175 offset:33792
	ds_read_b128 v[194:197], v175 offset:34816
	ds_read_b128 v[198:201], v175 offset:35840
	ds_read_b128 v[202:205], v175 offset:36864
	ds_read_b128 v[206:209], v175 offset:37888
	ds_read_b128 v[210:213], v175 offset:38912
	ds_read_b128 v[214:217], v175 offset:39936
	global_load_lds_dwordx4 v[224:225], off
	v_lshl_add_u64 v[224:225], s[36:37], 0, v[146:147]
	s_mov_b32 m0, s45
	s_nop 0
	global_load_lds_dwordx4 v[224:225], off
	s_waitcnt vmcnt(8)
	s_waitcnt lgkmcnt(0)
	s_setprio 1
	s_barrier
	v_mfma_f32_16x16x32_bf16 v[124:127], v[128:131], v[186:189], v[124:127]
	v_mfma_f32_16x16x32_bf16 v[120:123], v[136:139], v[186:189], v[120:123]
	v_mfma_f32_16x16x32_bf16 v[108:111], v[128:131], v[194:197], v[108:111]
	v_mfma_f32_16x16x32_bf16 v[104:107], v[136:139], v[194:197], v[104:107]
	v_mfma_f32_16x16x32_bf16 v[92:95], v[128:131], v[202:205], v[92:95]
	v_mfma_f32_16x16x32_bf16 v[88:91], v[136:139], v[202:205], v[88:91]
	v_mfma_f32_16x16x32_bf16 v[76:79], v[128:131], v[210:213], v[76:79]
	v_mfma_f32_16x16x32_bf16 v[72:75], v[136:139], v[210:213], v[72:75]
	v_mfma_f32_16x16x32_bf16 v[124:127], v[132:135], v[190:193], v[124:127]
	v_mfma_f32_16x16x32_bf16 v[120:123], v[140:143], v[190:193], v[120:123]
	v_mfma_f32_16x16x32_bf16 v[108:111], v[132:135], v[198:201], v[108:111]
	v_mfma_f32_16x16x32_bf16 v[104:107], v[140:143], v[198:201], v[104:107]
	v_mfma_f32_16x16x32_bf16 v[92:95], v[132:135], v[206:209], v[92:95]
	v_mfma_f32_16x16x32_bf16 v[88:91], v[140:143], v[206:209], v[88:91]
	v_mfma_f32_16x16x32_bf16 v[76:79], v[132:135], v[214:217], v[76:79]
	v_mfma_f32_16x16x32_bf16 v[72:75], v[140:143], v[214:217], v[72:75]
	s_setprio 0
	s_setprio 1
	v_mfma_f32_16x16x32_bf16 v[116:119], v[160:163], v[186:189], v[116:119]
	v_mfma_f32_16x16x32_bf16 v[112:115], v[178:181], v[186:189], v[112:115]
	v_mfma_f32_16x16x32_bf16 v[100:103], v[160:163], v[194:197], v[100:103]
	v_mfma_f32_16x16x32_bf16 v[96:99], v[178:181], v[194:197], v[96:99]
	v_mfma_f32_16x16x32_bf16 v[84:87], v[160:163], v[202:205], v[84:87]
	v_mfma_f32_16x16x32_bf16 v[80:83], v[178:181], v[202:205], v[80:83]
	v_mfma_f32_16x16x32_bf16 v[68:71], v[160:163], v[210:213], v[68:71]
	v_mfma_f32_16x16x32_bf16 v[64:67], v[178:181], v[210:213], v[64:67]
	v_mfma_f32_16x16x32_bf16 v[116:119], v[164:167], v[190:193], v[116:119]
	v_mfma_f32_16x16x32_bf16 v[112:115], v[182:185], v[190:193], v[112:115]
	v_mfma_f32_16x16x32_bf16 v[100:103], v[164:167], v[198:201], v[100:103]
	v_mfma_f32_16x16x32_bf16 v[96:99], v[182:185], v[198:201], v[96:99]
	v_mfma_f32_16x16x32_bf16 v[84:87], v[164:167], v[206:209], v[84:87]
	v_mfma_f32_16x16x32_bf16 v[80:83], v[182:185], v[206:209], v[80:83]
	v_mfma_f32_16x16x32_bf16 v[68:71], v[164:167], v[214:217], v[68:71]
	v_mfma_f32_16x16x32_bf16 v[64:67], v[182:185], v[214:217], v[64:67]
	s_setprio 0
	s_barrier
; #define PG8_STAGE(bufoff, gbase, voff) do { _Pragma("unroll") for (int _i = 0; _i < 2; ++_i) \
;         __builtin_amdgcn_global_load_lds((const unsigned*)((const char*)(gbase) + (voff)[_i]), (PG8_LAS unsigned*)(lds + (bufoff) + ldsw + _i * 8192), 16, 0, 0); } while (0)
; #define PG8_LDA(dst, b, h) do { _Pragma("unroll") for (int m = 0; m < 4; ++m) _Pragma("unroll") for (int k = 0; k < 2; ++k) dst[m][k] = *(const PG8_LAS bf16x8*)(lds + PG8_SA(b, h) + aoff + m * 2048 + k * 1024); } while (0)
; #define PG8_MMA(ai, bj, At, Bt) do { __builtin_amdgcn_s_setprio(1); _Pragma("unroll") for (int m = 0; m < 4; ++m) _Pragma("unroll") for (int n = 0; n < 2; ++n) _Pragma("unroll") for (int k = 0; k < 2; ++k) \
;         acc[ai][bj][m][n] = __builtin_amdgcn_mfma_f32_16x16x32_bf16(Bt[n][k], At[m][k], acc[ai][bj][m][n], 0, 0, 0); __builtin_amdgcn_s_setprio(0); } while (0)
; #define PG8_WAIT_V(n) asm volatile("s_waitcnt vmcnt(" #n ")" ::: "memory")
; #define PG8_WAIT_L(n) asm volatile("s_waitcnt lgkmcnt(" #n ")" ::: "memory")
; #define PG8_BAR __builtin_amdgcn_s_barrier()
; #define PG8_SCHED __builtin_amdgcn_sched_barrier(0)
; template <class Epi, class Sched, bool ALIGN_EPI = false, bool SP2 = false>
; __device__ __forceinline__ void gemm_phase(PG8_LAS unsigned char* lds, const Gemm g, const Sched& S, const Epi& E) {
;     ...
;             PG8_LDA(At, 1, 1); PG8_STAGE(PG8_SB(1, 0), b3, voffB); PG8_STAGE(PG8_SB(1, 1), b3 + hstep, voffB); PG8_STAGE(PG8_SA(1, 0), a3, voffA);
;             PG8_WAIT_V(8); PG8_WAIT_L(0); PG8_BAR; PG8_MMA(1, 0, At, B0); PG8_MMA(1, 1, At, B1); PG8_BAR; PG8_SCHED;
	s_add_i32 s36, s71, s39
	v_lshl_add_u64 v[168:169], v[168:169], 0, s[6:7]
	s_mov_b32 m0, s36
	ds_read_b128 v[186:189], v175 offset:49152
	ds_read_b128 v[190:193], v175 offset:50176
	ds_read_b128 v[194:197], v175 offset:51200
	ds_read_b128 v[198:201], v175 offset:52224
	ds_read_b128 v[202:205], v175 offset:53248
	ds_read_b128 v[206:209], v175 offset:54272
	ds_read_b128 v[210:213], v175 offset:55296
	ds_read_b128 v[214:217], v175 offset:56320
	global_load_lds_dwordx4 v[168:169], off
	s_add_i32 m0, s36, 0x2000
	s_add_u32 s26, s26, 0x40080
	v_lshl_add_u64 v[168:169], v[218:219], 0, s[6:7]
	s_addc_u32 s27, s27, 0
	s_add_i32 s36, s72, s39
	global_load_lds_dwordx4 v[168:169], off
	v_lshl_add_u64 v[168:169], s[26:27], 0, v[148:149]
	s_mov_b32 m0, s36
	s_nop 0
	global_load_lds_dwordx4 v[168:169], off
	v_lshl_add_u64 v[168:169], s[26:27], 0, v[144:145]
	s_add_i32 m0, s36, 0x2000
	s_nop 0
	global_load_lds_dwordx4 v[168:169], off
	s_waitcnt vmcnt(6)
	s_waitcnt lgkmcnt(0)
	s_setprio 1
	s_barrier
	v_mfma_f32_16x16x32_bf16 v[60:63], v[128:131], v[186:189], v[60:63]
	v_mfma_f32_16x16x32_bf16 v[56:59], v[136:139], v[186:189], v[56:59]
	v_mfma_f32_16x16x32_bf16 v[44:47], v[128:131], v[194:197], v[44:47]
	v_mfma_f32_16x16x32_bf16 v[40:43], v[136:139], v[194:197], v[40:43]
	v_mfma_f32_16x16x32_bf16 v[28:31], v[128:131], v[202:205], v[28:31]
	v_mfma_f32_16x16x32_bf16 v[24:27], v[136:139], v[202:205], v[24:27]
	v_lshl_add_u64 v[168:169], v[220:221], 0, s[6:7]
	s_mov_b32 m0, s47
	s_nop 0
	global_load_lds_dwordx4 v[168:169], off
	v_mfma_f32_16x16x32_bf16 v[12:15], v[128:131], v[210:213], v[12:15]
	v_mfma_f32_16x16x32_bf16 v[8:11], v[136:139], v[210:213], v[8:11]
	v_mfma_f32_16x16x32_bf16 v[60:63], v[132:135], v[190:193], v[60:63]
	v_mfma_f32_16x16x32_bf16 v[56:59], v[140:143], v[190:193], v[56:59]
	v_mfma_f32_16x16x32_bf16 v[44:47], v[132:135], v[198:201], v[44:47]
	v_mfma_f32_16x16x32_bf16 v[40:43], v[140:143], v[198:201], v[40:43]
	v_mfma_f32_16x16x32_bf16 v[28:31], v[132:135], v[206:209], v[28:31]
	v_mfma_f32_16x16x32_bf16 v[24:27], v[140:143], v[206:209], v[24:27]
	v_mfma_f32_16x16x32_bf16 v[12:15], v[132:135], v[214:217], v[12:15]
	v_mfma_f32_16x16x32_bf16 v[8:11], v[140:143], v[214:217], v[8:11]
	s_setprio 0
	s_setprio 1
	v_mfma_f32_16x16x32_bf16 v[52:55], v[160:163], v[186:189], v[52:55]
	v_mfma_f32_16x16x32_bf16 v[48:51], v[178:181], v[186:189], v[48:51]
	v_mfma_f32_16x16x32_bf16 v[36:39], v[160:163], v[194:197], v[36:39]
	v_mfma_f32_16x16x32_bf16 v[32:35], v[178:181], v[194:197], v[32:35]
	v_mfma_f32_16x16x32_bf16 v[20:23], v[160:163], v[202:205], v[20:23]
	v_mfma_f32_16x16x32_bf16 v[16:19], v[178:181], v[202:205], v[16:19]
	v_lshl_add_u64 v[168:169], v[222:223], 0, s[6:7]
	s_mov_b32 m0, s48
	s_nop 0
	global_load_lds_dwordx4 v[168:169], off
	v_mfma_f32_16x16x32_bf16 v[4:7], v[160:163], v[210:213], v[4:7]
	v_mfma_f32_16x16x32_bf16 v[0:3], v[178:181], v[210:213], v[0:3]
	v_mfma_f32_16x16x32_bf16 v[52:55], v[164:167], v[190:193], v[52:55]
	v_mfma_f32_16x16x32_bf16 v[48:51], v[182:185], v[190:193], v[48:51]
	v_mfma_f32_16x16x32_bf16 v[36:39], v[164:167], v[198:201], v[36:39]
	v_mfma_f32_16x16x32_bf16 v[32:35], v[182:185], v[198:201], v[32:35]
	v_mfma_f32_16x16x32_bf16 v[20:23], v[164:167], v[206:209], v[20:23]
	v_mfma_f32_16x16x32_bf16 v[16:19], v[182:185], v[206:209], v[16:19]
	v_mfma_f32_16x16x32_bf16 v[4:7], v[164:167], v[214:217], v[4:7]
	v_mfma_f32_16x16x32_bf16 v[0:3], v[182:185], v[214:217], v[0:3]
	s_setprio 0
	s_barrier
	s_add_i32 s70, s70, 2
	s_add_u32 s24, s24, 0x100
	s_addc_u32 s25, s25, 0
	s_add_u32 s68, s68, 0x100
	s_addc_u32 s69, s69, 0
	s_cmp_gt_u32 s70, 13
	s_cbranch_scc0 .LBB0_813
; __device__ __forceinline__ u32x2 pack4(f32x4 v) { u32x2 w; w.x = cvt_pk_bf16(v[0], v[1]); w.y = cvt_pk_bf16(v[2], v[3]); return w; }
;     __device__ __forceinline__ void operator()(const f32x4 (&acc)[2][2][4][2], const Unit& u, int wr, int wc, int fr, int fq) const {
;         const int row0 = u.pm * BM + wr * 64 + fr, col0 = u.pn * BM + wc * 32 + 8 * fq;
;         const float* base = (u.pm * BM < split) ? base0 : base1; bf16_t* const xn = (bf16_t*)(ws + WS_XN); float* const ssq = (float*)(ws + WS_SSQ);
; #pragma unroll
;         for (int ai = 0; ai < 2; ++ai)
; #pragma unroll
;         for (int mh = 0; mh < 4; mh += 2) {
;             f32x4 pre[4][2][2];
; #pragma unroll
;             for (int m = mh; m < mh + 2; ++m)
; #pragma unroll
;                 for (int bj = 0; bj < 2; ++bj)
; #pragma unroll
;                     for (int n = 0; n < 2; ++n) pre[m][bj][n] = *(const f32x4*)(base + (size_t)(row0 + ai * HALF + m * 16) * 1024 + col0 + bj * HALF + n * 4);
;             asm volatile("" ::: "memory");
; #pragma unroll
;             for (int m = mh; m < mh + 2; ++m) { const int row = row0 + ai * HALF + m * 16; const size_t off = (size_t)row * 1024 + col0; float ss = 0.f;
; #pragma unroll
;                 for (int bj = 0; bj < 2; ++bj) { u32x4e w;
; #pragma unroll
;                     for (int n = 0; n < 2; ++n) { const f32x4 o = pre[m][bj][n] + acc[ai][bj][m][n] * s;
;                         *(f32x4*)(out + off + bj * HALF + n * 4) = o;
;                         if (NORMOUT) { const u32x2 p = pack4(o); w[2 * n] = p.x; w[2 * n + 1] = p.y; ss += (o[0] * o[0] + o[1] * o[1]) + (o[2] * o[2] + o[3] * o[3]); } }
;                     if (NORMOUT) *(u32x4e*)(xn + off + bj * HALF) = w; }
;                 if (NORMOUT) { ss += __shfl_xor(ss, 16); ss += __shfl_xor(ss, 32); if (fq == 0) ssq[(size_t)row * 16 + u.pn * 4 + wc] = ss; } }
	v_lshl_add_u32 v164, s22, 8, v170
	v_lshl_or_b32 v160, s23, 8, v172
	v_ashrrev_i32_e32 v161, 31, v160
	v_ashrrev_i32_e32 v165, 31, v164
	v_lshl_add_u64 v[162:163], v[160:161], 2, s[56:57]
	v_lshlrev_b64 v[128:129], 12, v[164:165]
	v_lshl_add_u64 v[196:197], v[162:163], 0, v[128:129]
	global_load_dwordx4 v[180:183], v[196:197], off
	global_load_dwordx4 v[184:187], v[196:197], off offset:16
	global_load_dwordx4 v[188:191], v[196:197], off offset:512
	global_load_dwordx4 v[192:195], v[196:197], off offset:528
	v_or_b32_e32 v166, 16, v164
	v_ashrrev_i32_e32 v167, 31, v166
	v_lshlrev_b64 v[128:129], 12, v[166:167]
	v_lshl_add_u64 v[168:169], v[162:163], 0, v[128:129]
	global_load_dwordx4 v[136:139], v[168:169], off offset:16
	global_load_dwordx4 v[140:143], v[168:169], off
	global_load_dwordx4 v[128:131], v[168:169], off offset:528
	global_load_dwordx4 v[132:135], v[168:169], off offset:512
	v_and_b32_e32 v178, 64, v176
	v_xor_b32_e32 v177, 16, v176
	v_add_u32_e32 v178, 64, v178
	v_xor_b32_e32 v179, 32, v176
	v_cmp_lt_i32_e32 vcc, v177, v178
	v_lshlrev_b64 v[198:199], 10, v[164:165]
	v_lshl_add_u64 v[198:199], v[198:199], 0, v[160:161]
	v_cndmask_b32_e32 v177, v176, v177, vcc
	v_cmp_lt_i32_e32 vcc, v179, v178
	v_lshlrev_b32_e32 v178, 2, v177
	v_lshl_add_u64 v[198:199], v[198:199], 1, s[64:65]
	v_cndmask_b32_e32 v179, v176, v179, vcc
	v_lshlrev_b32_e32 v177, 2, v179
	s_lshl_b32 s22, s23, 2
	s_ashr_i32 s23, s22, 31
	s_lshl_b64 s[22:23], s[22:23], 2
	s_add_u32 s22, s50, s22
	s_addc_u32 s23, s51, s23
	s_waitcnt vmcnt(0)
	v_pk_add_f32 v[126:127], v[182:183], v[126:127]
	v_pk_add_f32 v[124:125], v[180:181], v[124:125]
	v_pk_add_f32 v[122:123], v[186:187], v[122:123]
	v_pk_add_f32 v[120:121], v[184:185], v[120:121]
	v_pk_add_f32 v[118:119], v[190:191], v[118:119]
	v_pk_add_f32 v[116:117], v[188:189], v[116:117]
	v_pk_add_f32 v[182:183], v[194:195], v[114:115]
	v_pk_add_f32 v[180:181], v[192:193], v[112:113]
	global_store_dwordx4 v[196:197], v[124:127], off
	v_cvt_pk_bf16_f32 v112, v124, v125
	v_cvt_pk_bf16_f32 v113, v126, v127
	v_mul_f32_e32 v125, v125, v125
	v_mul_f32_e32 v127, v127, v127
	global_store_dwordx4 v[196:197], v[120:123], off offset:16
	v_cvt_pk_bf16_f32 v114, v120, v121
	v_cvt_pk_bf16_f32 v115, v122, v123
	v_mul_f32_e32 v121, v121, v121
	v_mul_f32_e32 v123, v123, v123
	v_mul_f32_e32 v179, v117, v117
	v_mul_f32_e32 v184, v119, v119
	v_fmac_f32_e32 v125, v124, v124
	v_fmac_f32_e32 v127, v126, v126
	v_fmac_f32_e32 v121, v120, v120
	v_fmac_f32_e32 v123, v122, v122
	v_mul_f32_e32 v185, v181, v181
	v_mul_f32_e32 v186, v183, v183
	v_fmac_f32_e32 v179, v116, v116
	v_fmac_f32_e32 v184, v118, v118
	v_add_f32_e32 v120, v125, v127
	v_add_f32_e32 v121, v121, v123
	v_fmac_f32_e32 v185, v180, v180
	v_fmac_f32_e32 v186, v182, v182
	v_add_f32_e32 v122, v179, v184
	v_add_f32_e32 v120, v120, v121
	v_add_f32_e32 v120, v122, v120
	v_add_f32_e32 v121, v185, v186
	v_add_f32_e32 v120, v121, v120
	ds_bpermute_b32 v121, v178, v120
	global_store_dwordx4 v[198:199], v[112:115], off
	global_store_dwordx4 v[196:197], v[116:119], off offset:512
	global_store_dwordx4 v[196:197], v[180:183], off offset:528
	v_cvt_pk_bf16_f32 v114, v116, v117
	v_cvt_pk_bf16_f32 v115, v118, v119
	s_waitcnt lgkmcnt(0)
	v_add_f32_e32 v112, v120, v121
	ds_bpermute_b32 v113, v177, v112
	v_cvt_pk_bf16_f32 v116, v180, v181
	v_cvt_pk_bf16_f32 v117, v182, v183
	global_store_dwordx4 v[198:199], v[114:117], off offset:256
	s_and_saveexec_b64 s[24:25], s[2:3]
	s_cbranch_execz .LBB0_816
	v_lshlrev_b64 v[114:115], 6, v[164:165]
	v_lshl_add_u64 v[114:115], s[22:23], 0, v[114:115]
	s_waitcnt lgkmcnt(0)
	v_add_f32_e32 v112, v112, v113
	global_store_dword v[114:115], v112, off

; #define PG8_STAGE(bufoff, gbase, voff) do { _Pragma("unroll") for (int _i = 0; _i < 2; ++_i) \
;         __builtin_amdgcn_global_load_lds((const unsigned*)((const char*)(gbase) + (voff)[_i]), (PG8_LAS unsigned*)(lds + (bufoff) + ldsw + _i * 8192), 16, 0, 0); } while (0)
; #define PG8_LDA(dst, b, h) do { _Pragma("unroll") for (int m = 0; m < 4; ++m) _Pragma("unroll") for (int k = 0; k < 2; ++k) dst[m][k] = *(const PG8_LAS bf16x8*)(lds + PG8_SA(b, h) + aoff + m * 2048 + k * 1024); } while (0)
; #define PG8_LDB(dst, b, h) do { _Pragma("unroll") for (int n = 0; n < 2; ++n) _Pragma("unroll") for (int k = 0; k < 2; ++k) dst[n][k] = *(const PG8_LAS bf16x8*)(lds + PG8_SB(b, h) + boff + n * 2048 + k * 1024); } while (0)
; #define PG8_MMA(ai, bj, At, Bt) do { __builtin_amdgcn_s_setprio(1); _Pragma("unroll") for (int m = 0; m < 4; ++m) _Pragma("unroll") for (int n = 0; n < 2; ++n) _Pragma("unroll") for (int k = 0; k < 2; ++k) \
;         acc[ai][bj][m][n] = __builtin_amdgcn_mfma_f32_16x16x32_bf16(Bt[n][k], At[m][k], acc[ai][bj][m][n], 0, 0, 0); __builtin_amdgcn_s_setprio(0); } while (0)
; #define PG8_WAIT_V(n) asm volatile("s_waitcnt vmcnt(" #n ")" ::: "memory")
; #define PG8_WAIT_L(n) asm volatile("s_waitcnt lgkmcnt(" #n ")" ::: "memory")
; #define PG8_BAR __builtin_amdgcn_s_barrier()
; #define PG8_SCHED __builtin_amdgcn_sched_barrier(0)
; template <class Epi, class Sched, bool ALIGN_EPI = false, bool SP2 = false>
; __device__ __forceinline__ void gemm_phase(PG8_LAS unsigned char* lds, const Gemm g, const Sched& S, const Epi& E) {
;     ...
;             PG8_LDB(B0, 0, 0); PG8_LDB(B1, 0, 1); PG8_SCHED; PG8_LDA(At, 0, 0); PG8_STAGE(PG8_SA(1, 1), a1 + hstep, voffA);
;             PG8_WAIT_V(8); PG8_WAIT_L(0); PG8_BAR; PG8_MMA(0, 0, At, B0); PG8_MMA(0, 1, At, B1); PG8_BAR; PG8_SCHED;
;             PG8_LDA(At, 0, 1); PG8_STAGE(PG8_SB(0, 0), b2, voffB); PG8_STAGE(PG8_SB(0, 1), b2 + hstep, voffB); PG8_STAGE(PG8_SA(0, 0), a2, voffA);
.LBB0_895:
	ds_read_b128 v[128:131], v183
	ds_read_b128 v[132:135], v183 offset:1024
	ds_read_b128 v[136:139], v183 offset:2048
	ds_read_b128 v[140:143], v183 offset:3072
	ds_read_b128 v[162:165], v184
	ds_read_b128 v[166:169], v184 offset:1024
	ds_read_b128 v[170:173], v184 offset:2048
	ds_read_b128 v[174:177], v184 offset:3072
	s_add_u32 s26, s4, 0xfffc0080
	s_addc_u32 s27, s5, -1
	s_cmp_eq_u32 s67, 12
	s_cselect_b32 s37, s1, s27
	s_cselect_b32 s36, s21, s26
	s_cselect_b32 s27, s19, s66
	s_cselect_b32 s26, s60, s61
	v_lshl_add_u64 v[222:223], s[4:5], 0, v[154:155]
	s_add_i32 m0, s41, 0xc000
	ds_read_b128 v[190:193], v185
	ds_read_b128 v[194:197], v185 offset:1024
	ds_read_b128 v[198:201], v185 offset:2048
	ds_read_b128 v[202:205], v185 offset:3072
	ds_read_b128 v[206:209], v185 offset:4096
	ds_read_b128 v[210:213], v185 offset:5120
	ds_read_b128 v[214:217], v185 offset:6144
	ds_read_b128 v[218:221], v185 offset:7168
	global_load_lds_dwordx4 v[222:223], off
	v_lshl_add_u64 v[222:223], s[4:5], 0, v[156:157]
	s_add_i32 m0, s41, 0xe000
	s_nop 0
	global_load_lds_dwordx4 v[222:223], off
	s_waitcnt vmcnt(8)
	s_waitcnt lgkmcnt(0)
	s_setprio 1
	s_barrier
	v_mfma_f32_16x16x32_bf16 v[124:127], v[128:131], v[190:193], v[124:127]
	v_mfma_f32_16x16x32_bf16 v[120:123], v[136:139], v[190:193], v[120:123]
	v_mfma_f32_16x16x32_bf16 v[108:111], v[128:131], v[198:201], v[108:111]
	v_mfma_f32_16x16x32_bf16 v[104:107], v[136:139], v[198:201], v[104:107]
	v_mfma_f32_16x16x32_bf16 v[92:95], v[128:131], v[206:209], v[92:95]
	v_mfma_f32_16x16x32_bf16 v[88:91], v[136:139], v[206:209], v[88:91]
	v_mfma_f32_16x16x32_bf16 v[76:79], v[128:131], v[214:217], v[76:79]
	v_mfma_f32_16x16x32_bf16 v[72:75], v[136:139], v[214:217], v[72:75]
	v_mfma_f32_16x16x32_bf16 v[124:127], v[132:135], v[194:197], v[124:127]
	v_mfma_f32_16x16x32_bf16 v[120:123], v[140:143], v[194:197], v[120:123]
	v_mfma_f32_16x16x32_bf16 v[108:111], v[132:135], v[202:205], v[108:111]
	v_mfma_f32_16x16x32_bf16 v[104:107], v[140:143], v[202:205], v[104:107]
	v_mfma_f32_16x16x32_bf16 v[92:95], v[132:135], v[210:213], v[92:95]
	v_mfma_f32_16x16x32_bf16 v[88:91], v[140:143], v[210:213], v[88:91]
	v_mfma_f32_16x16x32_bf16 v[76:79], v[132:135], v[218:221], v[76:79]
	v_mfma_f32_16x16x32_bf16 v[72:75], v[140:143], v[218:221], v[72:75]
	s_setprio 0
	s_setprio 1
	v_mfma_f32_16x16x32_bf16 v[116:119], v[162:165], v[190:193], v[116:119]
	v_mfma_f32_16x16x32_bf16 v[112:115], v[170:173], v[190:193], v[112:115]
	v_mfma_f32_16x16x32_bf16 v[100:103], v[162:165], v[198:201], v[100:103]
	v_mfma_f32_16x16x32_bf16 v[96:99], v[170:173], v[198:201], v[96:99]
	v_mfma_f32_16x16x32_bf16 v[84:87], v[162:165], v[206:209], v[84:87]
	v_mfma_f32_16x16x32_bf16 v[80:83], v[170:173], v[206:209], v[80:83]
	v_mfma_f32_16x16x32_bf16 v[68:71], v[162:165], v[214:217], v[68:71]
	v_mfma_f32_16x16x32_bf16 v[64:67], v[170:173], v[214:217], v[64:67]
	v_mfma_f32_16x16x32_bf16 v[116:119], v[166:169], v[194:197], v[116:119]
	v_mfma_f32_16x16x32_bf16 v[112:115], v[174:177], v[194:197], v[112:115]
	v_mfma_f32_16x16x32_bf16 v[100:103], v[166:169], v[202:205], v[100:103]
	v_mfma_f32_16x16x32_bf16 v[96:99], v[174:177], v[202:205], v[96:99]
	v_mfma_f32_16x16x32_bf16 v[84:87], v[166:169], v[210:213], v[84:87]
	v_mfma_f32_16x16x32_bf16 v[80:83], v[174:177], v[210:213], v[80:83]
	v_mfma_f32_16x16x32_bf16 v[68:71], v[166:169], v[218:221], v[68:71]
	v_mfma_f32_16x16x32_bf16 v[64:67], v[174:177], v[218:221], v[64:67]
	s_setprio 0
	s_barrier
	s_add_i32 s68, s49, s38
	v_lshl_add_u64 v[222:223], s[26:27], 0, v[148:149]
	s_mov_b32 m0, s68
	ds_read_b128 v[190:193], v185 offset:16384
	ds_read_b128 v[194:197], v185 offset:17408
	ds_read_b128 v[198:201], v185 offset:18432
	ds_read_b128 v[202:205], v185 offset:19456
	ds_read_b128 v[206:209], v185 offset:20480
	ds_read_b128 v[210:213], v185 offset:21504
	ds_read_b128 v[214:217], v185 offset:22528
	ds_read_b128 v[218:221], v185 offset:23552
	global_load_lds_dwordx4 v[222:223], off
	s_add_i32 m0, s68, 0x2000
	s_add_u32 s68, s26, 0x40000
	v_lshl_add_u64 v[224:225], s[26:27], 0, v[144:145]
	s_addc_u32 s69, s27, 0
	s_add_i32 s70, s50, s38
	global_load_lds_dwordx4 v[224:225], off
	v_lshl_add_u64 v[226:227], s[68:69], 0, v[148:149]
	s_mov_b32 m0, s70
	v_lshl_add_u64 v[228:229], s[36:37], 0, v[146:147]
	global_load_lds_dwordx4 v[226:227], off
	v_lshl_add_u64 v[226:227], s[68:69], 0, v[144:145]
	s_add_i32 m0, s70, 0x2000
	s_nop 0
	global_load_lds_dwordx4 v[226:227], off
	s_waitcnt vmcnt(6)
	s_waitcnt lgkmcnt(0)
	s_setprio 1
	s_barrier
; #define PG8_STAGE(bufoff, gbase, voff) do { _Pragma("unroll") for (int _i = 0; _i < 2; ++_i) \
;         __builtin_amdgcn_global_load_lds((const unsigned*)((const char*)(gbase) + (voff)[_i]), (PG8_LAS unsigned*)(lds + (bufoff) + ldsw + _i * 8192), 16, 0, 0); } while (0)
; #define PG8_LDA(dst, b, h) do { _Pragma("unroll") for (int m = 0; m < 4; ++m) _Pragma("unroll") for (int k = 0; k < 2; ++k) dst[m][k] = *(const PG8_LAS bf16x8*)(lds + PG8_SA(b, h) + aoff + m * 2048 + k * 1024); } while (0)
; #define PG8_LDB(dst, b, h) do { _Pragma("unroll") for (int n = 0; n < 2; ++n) _Pragma("unroll") for (int k = 0; k < 2; ++k) dst[n][k] = *(const PG8_LAS bf16x8*)(lds + PG8_SB(b, h) + boff + n * 2048 + k * 1024); } while (0)
; #define PG8_MMA(ai, bj, At, Bt) do { __builtin_amdgcn_s_setprio(1); _Pragma("unroll") for (int m = 0; m < 4; ++m) _Pragma("unroll") for (int n = 0; n < 2; ++n) _Pragma("unroll") for (int k = 0; k < 2; ++k) \
;         acc[ai][bj][m][n] = __builtin_amdgcn_mfma_f32_16x16x32_bf16(Bt[n][k], At[m][k], acc[ai][bj][m][n], 0, 0, 0); __builtin_amdgcn_s_setprio(0); } while (0)
; #define PG8_WAIT_V(n) asm volatile("s_waitcnt vmcnt(" #n ")" ::: "memory")
; #define PG8_WAIT_L(n) asm volatile("s_waitcnt lgkmcnt(" #n ")" ::: "memory")
; #define PG8_BAR __builtin_amdgcn_s_barrier()
; #define PG8_SCHED __builtin_amdgcn_sched_barrier(0)
; template <class Epi, class Sched, bool ALIGN_EPI = false, bool SP2 = false>
; __device__ __forceinline__ void gemm_phase(PG8_LAS unsigned char* lds, const Gemm g, const Sched& S, const Epi& E) {
;     ...
;             PG8_WAIT_V(8); PG8_WAIT_L(0); PG8_BAR; PG8_MMA(1, 0, At, B0); PG8_MMA(1, 1, At, B1); PG8_BAR; PG8_SCHED;
;             PG8_LDB(B0, 1, 0); PG8_LDB(B1, 1, 1); PG8_SCHED; PG8_LDA(At, 1, 0); PG8_STAGE(PG8_SA(0, 1), a2 + hstep, voffA);
;             PG8_WAIT_V(8); PG8_WAIT_L(0); PG8_BAR; PG8_MMA(0, 0, At, B0); PG8_MMA(0, 1, At, B1); PG8_BAR; PG8_SCHED;
	v_mfma_f32_16x16x32_bf16 v[60:63], v[128:131], v[190:193], v[60:63]
	v_mfma_f32_16x16x32_bf16 v[56:59], v[136:139], v[190:193], v[56:59]
	v_mfma_f32_16x16x32_bf16 v[44:47], v[128:131], v[198:201], v[44:47]
	v_mfma_f32_16x16x32_bf16 v[40:43], v[136:139], v[198:201], v[40:43]
	v_mfma_f32_16x16x32_bf16 v[28:31], v[128:131], v[206:209], v[28:31]
	v_mfma_f32_16x16x32_bf16 v[24:27], v[136:139], v[206:209], v[24:27]
	v_lshl_add_u64 v[226:227], s[36:37], 0, v[150:151]
	s_mov_b32 m0, s41
	s_nop 0
	global_load_lds_dwordx4 v[226:227], off
	v_mfma_f32_16x16x32_bf16 v[12:15], v[128:131], v[214:217], v[12:15]
	v_mfma_f32_16x16x32_bf16 v[8:11], v[136:139], v[214:217], v[8:11]
	v_mfma_f32_16x16x32_bf16 v[60:63], v[132:135], v[194:197], v[60:63]
	v_mfma_f32_16x16x32_bf16 v[56:59], v[140:143], v[194:197], v[56:59]
	v_mfma_f32_16x16x32_bf16 v[44:47], v[132:135], v[202:205], v[44:47]
	v_mfma_f32_16x16x32_bf16 v[40:43], v[140:143], v[202:205], v[40:43]
	v_mfma_f32_16x16x32_bf16 v[28:31], v[132:135], v[210:213], v[28:31]
	v_mfma_f32_16x16x32_bf16 v[24:27], v[140:143], v[210:213], v[24:27]
	v_mfma_f32_16x16x32_bf16 v[12:15], v[132:135], v[218:221], v[12:15]
	v_mfma_f32_16x16x32_bf16 v[8:11], v[140:143], v[218:221], v[8:11]
	s_setprio 0
	s_setprio 1
	v_mfma_f32_16x16x32_bf16 v[52:55], v[162:165], v[190:193], v[52:55]
	v_mfma_f32_16x16x32_bf16 v[48:51], v[170:173], v[190:193], v[48:51]
	v_mfma_f32_16x16x32_bf16 v[36:39], v[162:165], v[198:201], v[36:39]
	v_mfma_f32_16x16x32_bf16 v[32:35], v[170:173], v[198:201], v[32:35]
	v_mfma_f32_16x16x32_bf16 v[20:23], v[162:165], v[206:209], v[20:23]
	v_mfma_f32_16x16x32_bf16 v[16:19], v[170:173], v[206:209], v[16:19]
	s_mov_b32 m0, s42
	s_nop 0
	global_load_lds_dwordx4 v[228:229], off
	v_mfma_f32_16x16x32_bf16 v[4:7], v[162:165], v[214:217], v[4:7]
	v_mfma_f32_16x16x32_bf16 v[0:3], v[170:173], v[214:217], v[0:3]
	v_mfma_f32_16x16x32_bf16 v[52:55], v[166:169], v[194:197], v[52:55]
	v_mfma_f32_16x16x32_bf16 v[48:51], v[174:177], v[194:197], v[48:51]
	v_mfma_f32_16x16x32_bf16 v[36:39], v[166:169], v[202:205], v[36:39]
	v_mfma_f32_16x16x32_bf16 v[32:35], v[174:177], v[202:205], v[32:35]
	v_mfma_f32_16x16x32_bf16 v[20:23], v[166:169], v[210:213], v[20:23]
	v_mfma_f32_16x16x32_bf16 v[16:19], v[174:177], v[210:213], v[16:19]
	v_mfma_f32_16x16x32_bf16 v[4:7], v[166:169], v[218:221], v[4:7]
	v_mfma_f32_16x16x32_bf16 v[0:3], v[174:177], v[218:221], v[0:3]
	s_setprio 0
	s_barrier
	s_add_i32 s68, 0, 0x18000
	s_add_i32 s69, 0, 0x1c000
	v_add_u32_e32 v140, s68, v181
	v_add_u32_e32 v174, s69, v181
	ds_read_b128 v[128:131], v140
	ds_read_b128 v[132:135], v140 offset:1024
	ds_read_b128 v[136:139], v140 offset:2048
	ds_read_b128 v[140:143], v140 offset:3072
	ds_read_b128 v[162:165], v174
	ds_read_b128 v[166:169], v174 offset:1024
	ds_read_b128 v[170:173], v174 offset:2048
	ds_read_b128 v[174:177], v174 offset:3072
	s_add_u32 s36, s36, 0x40000
	s_addc_u32 s37, s37, 0
	s_mov_b32 m0, s43
	v_lshl_add_u64 v[232:233], s[36:37], 0, v[150:151]
	ds_read_b128 v[190:193], v185 offset:32768
	ds_read_b128 v[194:197], v185 offset:33792
	ds_read_b128 v[198:201], v185 offset:34816
	ds_read_b128 v[202:205], v185 offset:35840
	ds_read_b128 v[206:209], v185 offset:36864
	ds_read_b128 v[210:213], v185 offset:37888
	ds_read_b128 v[214:217], v185 offset:38912
	ds_read_b128 v[218:221], v185 offset:39936
	global_load_lds_dwordx4 v[232:233], off
	v_lshl_add_u64 v[232:233], s[36:37], 0, v[146:147]
	s_mov_b32 m0, s44
	s_nop 0
	global_load_lds_dwordx4 v[232:233], off
	s_waitcnt vmcnt(8)
	s_waitcnt lgkmcnt(0)
	s_setprio 1
	s_barrier
	v_mfma_f32_16x16x32_bf16 v[124:127], v[128:131], v[190:193], v[124:127]
	v_mfma_f32_16x16x32_bf16 v[120:123], v[136:139], v[190:193], v[120:123]
	v_mfma_f32_16x16x32_bf16 v[108:111], v[128:131], v[198:201], v[108:111]
	v_mfma_f32_16x16x32_bf16 v[104:107], v[136:139], v[198:201], v[104:107]
	v_mfma_f32_16x16x32_bf16 v[92:95], v[128:131], v[206:209], v[92:95]
	v_mfma_f32_16x16x32_bf16 v[88:91], v[136:139], v[206:209], v[88:91]
	v_mfma_f32_16x16x32_bf16 v[76:79], v[128:131], v[214:217], v[76:79]
	v_mfma_f32_16x16x32_bf16 v[72:75], v[136:139], v[214:217], v[72:75]
	v_mfma_f32_16x16x32_bf16 v[124:127], v[132:135], v[194:197], v[124:127]
	v_mfma_f32_16x16x32_bf16 v[120:123], v[140:143], v[194:197], v[120:123]
	v_mfma_f32_16x16x32_bf16 v[108:111], v[132:135], v[202:205], v[108:111]
	v_mfma_f32_16x16x32_bf16 v[104:107], v[140:143], v[202:205], v[104:107]
	v_mfma_f32_16x16x32_bf16 v[92:95], v[132:135], v[210:213], v[92:95]
	v_mfma_f32_16x16x32_bf16 v[88:91], v[140:143], v[210:213], v[88:91]
	v_mfma_f32_16x16x32_bf16 v[76:79], v[132:135], v[218:221], v[76:79]
	v_mfma_f32_16x16x32_bf16 v[72:75], v[140:143], v[218:221], v[72:75]
	s_setprio 0
	s_setprio 1
	v_mfma_f32_16x16x32_bf16 v[116:119], v[162:165], v[190:193], v[116:119]
	v_mfma_f32_16x16x32_bf16 v[112:115], v[170:173], v[190:193], v[112:115]
	v_mfma_f32_16x16x32_bf16 v[100:103], v[162:165], v[198:201], v[100:103]
	v_mfma_f32_16x16x32_bf16 v[96:99], v[170:173], v[198:201], v[96:99]
	v_mfma_f32_16x16x32_bf16 v[84:87], v[162:165], v[206:209], v[84:87]
	v_mfma_f32_16x16x32_bf16 v[80:83], v[170:173], v[206:209], v[80:83]
	v_mfma_f32_16x16x32_bf16 v[68:71], v[162:165], v[214:217], v[68:71]
	v_mfma_f32_16x16x32_bf16 v[64:67], v[170:173], v[214:217], v[64:67]
	v_mfma_f32_16x16x32_bf16 v[116:119], v[166:169], v[194:197], v[116:119]
	v_mfma_f32_16x16x32_bf16 v[112:115], v[174:177], v[194:197], v[112:115]
	v_mfma_f32_16x16x32_bf16 v[100:103], v[166:169], v[202:205], v[100:103]
	v_mfma_f32_16x16x32_bf16 v[96:99], v[174:177], v[202:205], v[96:99]
	v_mfma_f32_16x16x32_bf16 v[84:87], v[166:169], v[210:213], v[84:87]
	v_mfma_f32_16x16x32_bf16 v[80:83], v[174:177], v[210:213], v[80:83]
	v_mfma_f32_16x16x32_bf16 v[68:71], v[166:169], v[218:221], v[68:71]
	v_mfma_f32_16x16x32_bf16 v[64:67], v[174:177], v[218:221], v[64:67]
	s_setprio 0
	s_barrier
; #define PG8_STAGE(bufoff, gbase, voff) do { _Pragma("unroll") for (int _i = 0; _i < 2; ++_i) \
;         __builtin_amdgcn_global_load_lds((const unsigned*)((const char*)(gbase) + (voff)[_i]), (PG8_LAS unsigned*)(lds + (bufoff) + ldsw + _i * 8192), 16, 0, 0); } while (0)
; #define PG8_LDA(dst, b, h) do { _Pragma("unroll") for (int m = 0; m < 4; ++m) _Pragma("unroll") for (int k = 0; k < 2; ++k) dst[m][k] = *(const PG8_LAS bf16x8*)(lds + PG8_SA(b, h) + aoff + m * 2048 + k * 1024); } while (0)
; #define PG8_MMA(ai, bj, At, Bt) do { __builtin_amdgcn_s_setprio(1); _Pragma("unroll") for (int m = 0; m < 4; ++m) _Pragma("unroll") for (int n = 0; n < 2; ++n) _Pragma("unroll") for (int k = 0; k < 2; ++k) \
;         acc[ai][bj][m][n] = __builtin_amdgcn_mfma_f32_16x16x32_bf16(Bt[n][k], At[m][k], acc[ai][bj][m][n], 0, 0, 0); __builtin_amdgcn_s_setprio(0); } while (0)
; #define PG8_WAIT_V(n) asm volatile("s_waitcnt vmcnt(" #n ")" ::: "memory")
; #define PG8_WAIT_L(n) asm volatile("s_waitcnt lgkmcnt(" #n ")" ::: "memory")
; #define PG8_BAR __builtin_amdgcn_s_barrier()
; #define PG8_SCHED __builtin_amdgcn_sched_barrier(0)
; template <class Epi, class Sched, bool ALIGN_EPI = false, bool SP2 = false>
; __device__ __forceinline__ void gemm_phase(PG8_LAS unsigned char* lds, const Gemm g, const Sched& S, const Epi& E) {
;     ...
;             PG8_LDA(At, 1, 1); PG8_STAGE(PG8_SB(1, 0), b3, voffB); PG8_STAGE(PG8_SB(1, 1), b3 + hstep, voffB); PG8_STAGE(PG8_SA(1, 0), a3, voffA);
;             PG8_WAIT_V(8); PG8_WAIT_L(0); PG8_BAR; PG8_MMA(1, 0, At, B0); PG8_MMA(1, 1, At, B1); PG8_BAR; PG8_SCHED;
;     ...
;         if constexpr (ALIGN_EPI) { if (wr == 0) PG8_BAR; }
	s_add_i32 s36, s68, s38
	v_lshl_add_u64 v[222:223], v[222:223], 0, s[12:13]
	s_mov_b32 m0, s36
	ds_read_b128 v[190:193], v185 offset:49152
	ds_read_b128 v[194:197], v185 offset:50176
	ds_read_b128 v[198:201], v185 offset:51200
	ds_read_b128 v[202:205], v185 offset:52224
	ds_read_b128 v[206:209], v185 offset:53248
	ds_read_b128 v[210:213], v185 offset:54272
	ds_read_b128 v[214:217], v185 offset:55296
	ds_read_b128 v[218:221], v185 offset:56320
	global_load_lds_dwordx4 v[222:223], off
	s_add_i32 m0, s36, 0x2000
	s_add_u32 s26, s26, 0x40080
	v_lshl_add_u64 v[222:223], v[224:225], 0, s[12:13]
	s_addc_u32 s27, s27, 0
	s_add_i32 s36, s69, s38
	global_load_lds_dwordx4 v[222:223], off
	v_lshl_add_u64 v[222:223], s[26:27], 0, v[148:149]
	s_mov_b32 m0, s36
	s_nop 0
	global_load_lds_dwordx4 v[222:223], off
	v_lshl_add_u64 v[222:223], s[26:27], 0, v[144:145]
	s_add_i32 m0, s36, 0x2000
	s_nop 0
	global_load_lds_dwordx4 v[222:223], off
	s_waitcnt vmcnt(6)
	s_waitcnt lgkmcnt(0)
	s_setprio 1
	s_barrier
	v_mfma_f32_16x16x32_bf16 v[60:63], v[128:131], v[190:193], v[60:63]
	v_mfma_f32_16x16x32_bf16 v[56:59], v[136:139], v[190:193], v[56:59]
	v_mfma_f32_16x16x32_bf16 v[44:47], v[128:131], v[198:201], v[44:47]
	v_mfma_f32_16x16x32_bf16 v[40:43], v[136:139], v[198:201], v[40:43]
	v_mfma_f32_16x16x32_bf16 v[28:31], v[128:131], v[206:209], v[28:31]
	v_mfma_f32_16x16x32_bf16 v[24:27], v[136:139], v[206:209], v[24:27]
	v_lshl_add_u64 v[222:223], v[226:227], 0, s[12:13]
	s_mov_b32 m0, s46
	s_nop 0
	global_load_lds_dwordx4 v[222:223], off
	v_mfma_f32_16x16x32_bf16 v[12:15], v[128:131], v[214:217], v[12:15]
	v_mfma_f32_16x16x32_bf16 v[8:11], v[136:139], v[214:217], v[8:11]
	v_mfma_f32_16x16x32_bf16 v[60:63], v[132:135], v[194:197], v[60:63]
	v_mfma_f32_16x16x32_bf16 v[56:59], v[140:143], v[194:197], v[56:59]
	v_mfma_f32_16x16x32_bf16 v[44:47], v[132:135], v[202:205], v[44:47]
	v_mfma_f32_16x16x32_bf16 v[40:43], v[140:143], v[202:205], v[40:43]
	v_mfma_f32_16x16x32_bf16 v[28:31], v[132:135], v[210:213], v[28:31]
	v_mfma_f32_16x16x32_bf16 v[24:27], v[140:143], v[210:213], v[24:27]
	v_mfma_f32_16x16x32_bf16 v[12:15], v[132:135], v[218:221], v[12:15]
	v_mfma_f32_16x16x32_bf16 v[8:11], v[140:143], v[218:221], v[8:11]
	s_setprio 0
	s_setprio 1
	v_mfma_f32_16x16x32_bf16 v[52:55], v[162:165], v[190:193], v[52:55]
	v_mfma_f32_16x16x32_bf16 v[48:51], v[170:173], v[190:193], v[48:51]
	v_mfma_f32_16x16x32_bf16 v[36:39], v[162:165], v[198:201], v[36:39]
	v_mfma_f32_16x16x32_bf16 v[32:35], v[170:173], v[198:201], v[32:35]
	v_mfma_f32_16x16x32_bf16 v[20:23], v[162:165], v[206:209], v[20:23]
	v_mfma_f32_16x16x32_bf16 v[16:19], v[170:173], v[206:209], v[16:19]
	v_lshl_add_u64 v[222:223], v[228:229], 0, s[12:13]
	s_mov_b32 m0, s47
	s_nop 0
	global_load_lds_dwordx4 v[222:223], off
	v_mfma_f32_16x16x32_bf16 v[4:7], v[162:165], v[214:217], v[4:7]
	v_mfma_f32_16x16x32_bf16 v[0:3], v[170:173], v[214:217], v[0:3]
	v_mfma_f32_16x16x32_bf16 v[52:55], v[166:169], v[194:197], v[52:55]
	v_mfma_f32_16x16x32_bf16 v[48:51], v[174:177], v[194:197], v[48:51]
	v_mfma_f32_16x16x32_bf16 v[36:39], v[166:169], v[202:205], v[36:39]
	v_mfma_f32_16x16x32_bf16 v[32:35], v[174:177], v[202:205], v[32:35]
	v_mfma_f32_16x16x32_bf16 v[20:23], v[166:169], v[210:213], v[20:23]
	v_mfma_f32_16x16x32_bf16 v[16:19], v[174:177], v[210:213], v[16:19]
	v_mfma_f32_16x16x32_bf16 v[4:7], v[166:169], v[218:221], v[4:7]
	v_mfma_f32_16x16x32_bf16 v[0:3], v[174:177], v[218:221], v[0:3]
	s_setprio 0
	s_barrier
	s_add_i32 s67, s67, 2
	s_add_u32 s4, s4, 0x100
	s_addc_u32 s5, s5, 0
	s_add_u32 s61, s61, 0x100
	s_addc_u32 s66, s66, 0
	s_cmp_gt_u32 s67, 13
	s_cbranch_scc0 .LBB0_895
	s_and_b64 vcc, exec, s[14:15]
	s_cbranch_vccz .LBB0_898
	s_barrier

; #define PG8_STAGE(bufoff, gbase, voff) do { _Pragma("unroll") for (int _i = 0; _i < 2; ++_i) \
;         __builtin_amdgcn_global_load_lds((const unsigned*)((const char*)(gbase) + (voff)[_i]), (PG8_LAS unsigned*)(lds + (bufoff) + ldsw + _i * 8192), 16, 0, 0); } while (0)
; #define PG8_LDA(dst, b, h) do { _Pragma("unroll") for (int m = 0; m < 4; ++m) _Pragma("unroll") for (int k = 0; k < 2; ++k) dst[m][k] = *(const PG8_LAS bf16x8*)(lds + PG8_SA(b, h) + aoff + m * 2048 + k * 1024); } while (0)
; #define PG8_LDB(dst, b, h) do { _Pragma("unroll") for (int n = 0; n < 2; ++n) _Pragma("unroll") for (int k = 0; k < 2; ++k) dst[n][k] = *(const PG8_LAS bf16x8*)(lds + PG8_SB(b, h) + boff + n * 2048 + k * 1024); } while (0)
; #define PG8_MMA(ai, bj, At, Bt) do { __builtin_amdgcn_s_setprio(1); _Pragma("unroll") for (int m = 0; m < 4; ++m) _Pragma("unroll") for (int n = 0; n < 2; ++n) _Pragma("unroll") for (int k = 0; k < 2; ++k) \
;         acc[ai][bj][m][n] = __builtin_amdgcn_mfma_f32_16x16x32_bf16(Bt[n][k], At[m][k], acc[ai][bj][m][n], 0, 0, 0); __builtin_amdgcn_s_setprio(0); } while (0)
; #define PG8_WAIT_V(n) asm volatile("s_waitcnt vmcnt(" #n ")" ::: "memory")
; #define PG8_WAIT_L(n) asm volatile("s_waitcnt lgkmcnt(" #n ")" ::: "memory")
; #define PG8_BAR __builtin_amdgcn_s_barrier()
; #define PG8_SCHED __builtin_amdgcn_sched_barrier(0)
; template <class Epi, class Sched, bool ALIGN_EPI = false, bool SP2 = false>
; __device__ __forceinline__ void gemm_phase(PG8_LAS unsigned char* lds, const Gemm g, const Sched& S, const Epi& E) {
;     ...
;             PG8_LDB(B0, 0, 0); PG8_LDB(B1, 0, 1); PG8_SCHED; PG8_LDA(At, 0, 0); PG8_STAGE(PG8_SA(1, 1), a1 + hstep, voffA);
;             PG8_WAIT_V(8); PG8_WAIT_L(0); PG8_BAR; PG8_MMA(0, 0, At, B0); PG8_MMA(0, 1, At, B1); PG8_BAR; PG8_SCHED;
;             PG8_LDA(At, 0, 1); PG8_STAGE(PG8_SB(0, 0), b2, voffB); PG8_STAGE(PG8_SB(0, 1), b2 + hstep, voffB); PG8_STAGE(PG8_SA(0, 0), a2, voffA);
.LBB0_970:
	ds_read_b128 v[144:147], v154
	ds_read_b128 v[162:165], v154 offset:1024
	ds_read_b128 v[166:169], v154 offset:2048
	ds_read_b128 v[170:173], v154 offset:3072
	ds_read_b128 v[174:177], v155
	ds_read_b128 v[178:181], v155 offset:1024
	ds_read_b128 v[182:185], v155 offset:2048
	ds_read_b128 v[186:189], v155 offset:3072
	s_add_u32 s44, s4, 0xfff50080
	s_addc_u32 s45, s5, -1
	s_cmp_eq_u32 s73, 40
	s_cselect_b32 s47, s39, s45
	s_cselect_b32 s46, s38, s44
	s_cselect_b32 s45, s41, s72
	s_cselect_b32 s44, s40, s43
	v_lshl_add_u64 v[148:149], s[4:5], 0, v[136:137]
	s_add_i32 m0, s48, 0xc000
	ds_read_b128 v[190:193], v156
	ds_read_b128 v[194:197], v156 offset:1024
	ds_read_b128 v[198:201], v156 offset:2048
	ds_read_b128 v[202:205], v156 offset:3072
	ds_read_b128 v[206:209], v156 offset:4096
	ds_read_b128 v[210:213], v156 offset:5120
	ds_read_b128 v[214:217], v156 offset:6144
	ds_read_b128 v[218:221], v156 offset:7168
	global_load_lds_dwordx4 v[148:149], off
	v_lshl_add_u64 v[148:149], s[4:5], 0, v[138:139]
	s_add_i32 m0, s48, 0xe000
	s_nop 0
	global_load_lds_dwordx4 v[148:149], off
	s_waitcnt vmcnt(8)
	s_waitcnt lgkmcnt(0)
	s_setprio 1
	s_barrier
	v_mfma_f32_16x16x32_bf16 v[124:127], v[144:147], v[190:193], v[124:127]
	v_mfma_f32_16x16x32_bf16 v[120:123], v[166:169], v[190:193], v[120:123]
	v_mfma_f32_16x16x32_bf16 v[104:107], v[144:147], v[198:201], v[104:107]
	v_mfma_f32_16x16x32_bf16 v[108:111], v[166:169], v[198:201], v[108:111]
	v_mfma_f32_16x16x32_bf16 v[88:91], v[144:147], v[206:209], v[88:91]
	v_mfma_f32_16x16x32_bf16 v[92:95], v[166:169], v[206:209], v[92:95]
	v_mfma_f32_16x16x32_bf16 v[72:75], v[144:147], v[214:217], v[72:75]
	v_mfma_f32_16x16x32_bf16 v[76:79], v[166:169], v[214:217], v[76:79]
	v_mfma_f32_16x16x32_bf16 v[124:127], v[162:165], v[194:197], v[124:127]
	v_mfma_f32_16x16x32_bf16 v[120:123], v[170:173], v[194:197], v[120:123]
	v_mfma_f32_16x16x32_bf16 v[104:107], v[162:165], v[202:205], v[104:107]
	v_mfma_f32_16x16x32_bf16 v[108:111], v[170:173], v[202:205], v[108:111]
	v_mfma_f32_16x16x32_bf16 v[88:91], v[162:165], v[210:213], v[88:91]
	v_mfma_f32_16x16x32_bf16 v[92:95], v[170:173], v[210:213], v[92:95]
	v_mfma_f32_16x16x32_bf16 v[72:75], v[162:165], v[218:221], v[72:75]
	v_mfma_f32_16x16x32_bf16 v[76:79], v[170:173], v[218:221], v[76:79]
	s_setprio 0
	s_setprio 1
	v_mfma_f32_16x16x32_bf16 v[116:119], v[174:177], v[190:193], v[116:119]
	v_mfma_f32_16x16x32_bf16 v[112:115], v[182:185], v[190:193], v[112:115]
	v_mfma_f32_16x16x32_bf16 v[100:103], v[174:177], v[198:201], v[100:103]
	v_mfma_f32_16x16x32_bf16 v[96:99], v[182:185], v[198:201], v[96:99]
	v_mfma_f32_16x16x32_bf16 v[84:87], v[174:177], v[206:209], v[84:87]
	v_mfma_f32_16x16x32_bf16 v[80:83], v[182:185], v[206:209], v[80:83]
	v_mfma_f32_16x16x32_bf16 v[68:71], v[174:177], v[214:217], v[68:71]
	v_mfma_f32_16x16x32_bf16 v[64:67], v[182:185], v[214:217], v[64:67]
	v_mfma_f32_16x16x32_bf16 v[116:119], v[178:181], v[194:197], v[116:119]
	v_mfma_f32_16x16x32_bf16 v[112:115], v[186:189], v[194:197], v[112:115]
	v_mfma_f32_16x16x32_bf16 v[100:103], v[178:181], v[202:205], v[100:103]
	v_mfma_f32_16x16x32_bf16 v[96:99], v[186:189], v[202:205], v[96:99]
	v_mfma_f32_16x16x32_bf16 v[84:87], v[178:181], v[210:213], v[84:87]
	v_mfma_f32_16x16x32_bf16 v[80:83], v[186:189], v[210:213], v[80:83]
	v_mfma_f32_16x16x32_bf16 v[68:71], v[178:181], v[218:221], v[68:71]
	v_mfma_f32_16x16x32_bf16 v[64:67], v[186:189], v[218:221], v[64:67]
	s_setprio 0
	s_barrier
	s_add_i32 s74, s66, s33
	v_lshl_add_u64 v[148:149], s[44:45], 0, v[130:131]
	s_mov_b32 m0, s74
	ds_read_b128 v[190:193], v156 offset:16384
	ds_read_b128 v[194:197], v156 offset:17408
	ds_read_b128 v[198:201], v156 offset:18432
	ds_read_b128 v[202:205], v156 offset:19456
	ds_read_b128 v[206:209], v156 offset:20480
	ds_read_b128 v[210:213], v156 offset:21504
	ds_read_b128 v[214:217], v156 offset:22528
	ds_read_b128 v[218:221], v156 offset:23552
	global_load_lds_dwordx4 v[148:149], off
	s_add_i32 m0, s74, 0x2000
	s_add_u32 s74, s44, 0xb0000
	v_lshl_add_u64 v[222:223], s[44:45], 0, v[134:135]
	s_addc_u32 s75, s45, 0
	s_add_i32 s76, s67, s33
	global_load_lds_dwordx4 v[222:223], off
	v_lshl_add_u64 v[224:225], s[74:75], 0, v[130:131]
	s_mov_b32 m0, s76
	v_lshl_add_u64 v[226:227], s[46:47], 0, v[132:133]
	global_load_lds_dwordx4 v[224:225], off
	v_lshl_add_u64 v[224:225], s[74:75], 0, v[134:135]
	s_add_i32 m0, s76, 0x2000
	s_nop 0
	global_load_lds_dwordx4 v[224:225], off
	s_waitcnt vmcnt(6)
	s_waitcnt lgkmcnt(0)
	s_setprio 1
	s_barrier
; #define PG8_STAGE(bufoff, gbase, voff) do { _Pragma("unroll") for (int _i = 0; _i < 2; ++_i) \
;         __builtin_amdgcn_global_load_lds((const unsigned*)((const char*)(gbase) + (voff)[_i]), (PG8_LAS unsigned*)(lds + (bufoff) + ldsw + _i * 8192), 16, 0, 0); } while (0)
; #define PG8_LDA(dst, b, h) do { _Pragma("unroll") for (int m = 0; m < 4; ++m) _Pragma("unroll") for (int k = 0; k < 2; ++k) dst[m][k] = *(const PG8_LAS bf16x8*)(lds + PG8_SA(b, h) + aoff + m * 2048 + k * 1024); } while (0)
; #define PG8_LDB(dst, b, h) do { _Pragma("unroll") for (int n = 0; n < 2; ++n) _Pragma("unroll") for (int k = 0; k < 2; ++k) dst[n][k] = *(const PG8_LAS bf16x8*)(lds + PG8_SB(b, h) + boff + n * 2048 + k * 1024); } while (0)
; #define PG8_MMA(ai, bj, At, Bt) do { __builtin_amdgcn_s_setprio(1); _Pragma("unroll") for (int m = 0; m < 4; ++m) _Pragma("unroll") for (int n = 0; n < 2; ++n) _Pragma("unroll") for (int k = 0; k < 2; ++k) \
;         acc[ai][bj][m][n] = __builtin_amdgcn_mfma_f32_16x16x32_bf16(Bt[n][k], At[m][k], acc[ai][bj][m][n], 0, 0, 0); __builtin_amdgcn_s_setprio(0); } while (0)
; #define PG8_WAIT_V(n) asm volatile("s_waitcnt vmcnt(" #n ")" ::: "memory")
; #define PG8_WAIT_L(n) asm volatile("s_waitcnt lgkmcnt(" #n ")" ::: "memory")
; #define PG8_BAR __builtin_amdgcn_s_barrier()
; #define PG8_SCHED __builtin_amdgcn_sched_barrier(0)
; template <class Epi, class Sched, bool ALIGN_EPI = false, bool SP2 = false>
; __device__ __forceinline__ void gemm_phase(PG8_LAS unsigned char* lds, const Gemm g, const Sched& S, const Epi& E) {
;     ...
;             PG8_WAIT_V(8); PG8_WAIT_L(0); PG8_BAR; PG8_MMA(1, 0, At, B0); PG8_MMA(1, 1, At, B1); PG8_BAR; PG8_SCHED;
;             PG8_LDB(B0, 1, 0); PG8_LDB(B1, 1, 1); PG8_SCHED; PG8_LDA(At, 1, 0); PG8_STAGE(PG8_SA(0, 1), a2 + hstep, voffA);
;             PG8_WAIT_V(8); PG8_WAIT_L(0); PG8_BAR; PG8_MMA(0, 0, At, B0); PG8_MMA(0, 1, At, B1); PG8_BAR; PG8_SCHED;
	v_mfma_f32_16x16x32_bf16 v[56:59], v[144:147], v[190:193], v[56:59]
	v_mfma_f32_16x16x32_bf16 v[60:63], v[166:169], v[190:193], v[60:63]
	v_mfma_f32_16x16x32_bf16 v[40:43], v[144:147], v[198:201], v[40:43]
	v_mfma_f32_16x16x32_bf16 v[44:47], v[166:169], v[198:201], v[44:47]
	v_mfma_f32_16x16x32_bf16 v[24:27], v[144:147], v[206:209], v[24:27]
	v_mfma_f32_16x16x32_bf16 v[28:31], v[166:169], v[206:209], v[28:31]
	v_lshl_add_u64 v[224:225], s[46:47], 0, v[128:129]
	s_mov_b32 m0, s48
	s_nop 0
	global_load_lds_dwordx4 v[224:225], off
	v_mfma_f32_16x16x32_bf16 v[8:11], v[144:147], v[214:217], v[8:11]
	v_mfma_f32_16x16x32_bf16 v[12:15], v[166:169], v[214:217], v[12:15]
	v_mfma_f32_16x16x32_bf16 v[56:59], v[162:165], v[194:197], v[56:59]
	v_mfma_f32_16x16x32_bf16 v[60:63], v[170:173], v[194:197], v[60:63]
	v_mfma_f32_16x16x32_bf16 v[40:43], v[162:165], v[202:205], v[40:43]
	v_mfma_f32_16x16x32_bf16 v[44:47], v[170:173], v[202:205], v[44:47]
	v_mfma_f32_16x16x32_bf16 v[24:27], v[162:165], v[210:213], v[24:27]
	v_mfma_f32_16x16x32_bf16 v[28:31], v[170:173], v[210:213], v[28:31]
	v_mfma_f32_16x16x32_bf16 v[8:11], v[162:165], v[218:221], v[8:11]
	v_mfma_f32_16x16x32_bf16 v[12:15], v[170:173], v[218:221], v[12:15]
	s_setprio 0
	s_setprio 1
	v_mfma_f32_16x16x32_bf16 v[52:55], v[174:177], v[190:193], v[52:55]
	v_mfma_f32_16x16x32_bf16 v[48:51], v[182:185], v[190:193], v[48:51]
	v_mfma_f32_16x16x32_bf16 v[36:39], v[174:177], v[198:201], v[36:39]
	v_mfma_f32_16x16x32_bf16 v[32:35], v[182:185], v[198:201], v[32:35]
	v_mfma_f32_16x16x32_bf16 v[20:23], v[174:177], v[206:209], v[20:23]
	v_mfma_f32_16x16x32_bf16 v[16:19], v[182:185], v[206:209], v[16:19]
	s_mov_b32 m0, s49
	s_nop 0
	global_load_lds_dwordx4 v[226:227], off
	v_mfma_f32_16x16x32_bf16 v[4:7], v[174:177], v[214:217], v[4:7]
	v_mfma_f32_16x16x32_bf16 v[0:3], v[182:185], v[214:217], v[0:3]
	v_mfma_f32_16x16x32_bf16 v[52:55], v[178:181], v[194:197], v[52:55]
	v_mfma_f32_16x16x32_bf16 v[48:51], v[186:189], v[194:197], v[48:51]
	v_mfma_f32_16x16x32_bf16 v[36:39], v[178:181], v[202:205], v[36:39]
	v_mfma_f32_16x16x32_bf16 v[32:35], v[186:189], v[202:205], v[32:35]
	v_mfma_f32_16x16x32_bf16 v[20:23], v[178:181], v[210:213], v[20:23]
	v_mfma_f32_16x16x32_bf16 v[16:19], v[186:189], v[210:213], v[16:19]
	v_mfma_f32_16x16x32_bf16 v[4:7], v[178:181], v[218:221], v[4:7]
	v_mfma_f32_16x16x32_bf16 v[0:3], v[186:189], v[218:221], v[0:3]
	s_setprio 0
	s_barrier
	s_add_i32 s74, 0, 0x18000
	s_add_i32 s75, 0, 0x1c000
	v_add_u32_e32 v170, s74, v151
	v_add_u32_e32 v186, s75, v151
	ds_read_b128 v[144:147], v170
	ds_read_b128 v[162:165], v170 offset:1024
	ds_read_b128 v[166:169], v170 offset:2048
	ds_read_b128 v[170:173], v170 offset:3072
	ds_read_b128 v[174:177], v186
	ds_read_b128 v[178:181], v186 offset:1024
	ds_read_b128 v[182:185], v186 offset:2048
	ds_read_b128 v[186:189], v186 offset:3072
	s_add_u32 s46, s46, 0xb0000
	s_addc_u32 s47, s47, 0
	s_mov_b32 m0, s50
	v_lshl_add_u64 v[228:229], s[46:47], 0, v[128:129]
	ds_read_b128 v[190:193], v156 offset:32768
	ds_read_b128 v[194:197], v156 offset:33792
	ds_read_b128 v[198:201], v156 offset:34816
	ds_read_b128 v[202:205], v156 offset:35840
	ds_read_b128 v[206:209], v156 offset:36864
	ds_read_b128 v[210:213], v156 offset:37888
	ds_read_b128 v[214:217], v156 offset:38912
	ds_read_b128 v[218:221], v156 offset:39936
	global_load_lds_dwordx4 v[228:229], off
	v_lshl_add_u64 v[228:229], s[46:47], 0, v[132:133]
	s_mov_b32 m0, s51
	s_nop 0
	global_load_lds_dwordx4 v[228:229], off
	s_waitcnt vmcnt(8)
	s_waitcnt lgkmcnt(0)
	s_setprio 1
	s_barrier
	v_mfma_f32_16x16x32_bf16 v[124:127], v[144:147], v[190:193], v[124:127]
	v_mfma_f32_16x16x32_bf16 v[120:123], v[166:169], v[190:193], v[120:123]
	v_mfma_f32_16x16x32_bf16 v[104:107], v[144:147], v[198:201], v[104:107]
	v_mfma_f32_16x16x32_bf16 v[108:111], v[166:169], v[198:201], v[108:111]
	v_mfma_f32_16x16x32_bf16 v[88:91], v[144:147], v[206:209], v[88:91]
	v_mfma_f32_16x16x32_bf16 v[92:95], v[166:169], v[206:209], v[92:95]
	v_mfma_f32_16x16x32_bf16 v[72:75], v[144:147], v[214:217], v[72:75]
	v_mfma_f32_16x16x32_bf16 v[76:79], v[166:169], v[214:217], v[76:79]
	v_mfma_f32_16x16x32_bf16 v[124:127], v[162:165], v[194:197], v[124:127]
	v_mfma_f32_16x16x32_bf16 v[120:123], v[170:173], v[194:197], v[120:123]
	v_mfma_f32_16x16x32_bf16 v[104:107], v[162:165], v[202:205], v[104:107]
	v_mfma_f32_16x16x32_bf16 v[108:111], v[170:173], v[202:205], v[108:111]
	v_mfma_f32_16x16x32_bf16 v[88:91], v[162:165], v[210:213], v[88:91]
	v_mfma_f32_16x16x32_bf16 v[92:95], v[170:173], v[210:213], v[92:95]
	v_mfma_f32_16x16x32_bf16 v[72:75], v[162:165], v[218:221], v[72:75]
	v_mfma_f32_16x16x32_bf16 v[76:79], v[170:173], v[218:221], v[76:79]
	s_setprio 0
	s_setprio 1
	v_mfma_f32_16x16x32_bf16 v[116:119], v[174:177], v[190:193], v[116:119]
	v_mfma_f32_16x16x32_bf16 v[112:115], v[182:185], v[190:193], v[112:115]
	v_mfma_f32_16x16x32_bf16 v[100:103], v[174:177], v[198:201], v[100:103]
	v_mfma_f32_16x16x32_bf16 v[96:99], v[182:185], v[198:201], v[96:99]
	v_mfma_f32_16x16x32_bf16 v[84:87], v[174:177], v[206:209], v[84:87]
	v_mfma_f32_16x16x32_bf16 v[80:83], v[182:185], v[206:209], v[80:83]
	v_mfma_f32_16x16x32_bf16 v[68:71], v[174:177], v[214:217], v[68:71]
	v_mfma_f32_16x16x32_bf16 v[64:67], v[182:185], v[214:217], v[64:67]
	v_mfma_f32_16x16x32_bf16 v[116:119], v[178:181], v[194:197], v[116:119]
	v_mfma_f32_16x16x32_bf16 v[112:115], v[186:189], v[194:197], v[112:115]
	v_mfma_f32_16x16x32_bf16 v[100:103], v[178:181], v[202:205], v[100:103]
	v_mfma_f32_16x16x32_bf16 v[96:99], v[186:189], v[202:205], v[96:99]
	v_mfma_f32_16x16x32_bf16 v[84:87], v[178:181], v[210:213], v[84:87]
	v_mfma_f32_16x16x32_bf16 v[80:83], v[186:189], v[210:213], v[80:83]
	v_mfma_f32_16x16x32_bf16 v[68:71], v[178:181], v[218:221], v[68:71]
	v_mfma_f32_16x16x32_bf16 v[64:67], v[186:189], v[218:221], v[64:67]
	s_setprio 0
	s_barrier
; #define PG8_STAGE(bufoff, gbase, voff) do { _Pragma("unroll") for (int _i = 0; _i < 2; ++_i) \
;         __builtin_amdgcn_global_load_lds((const unsigned*)((const char*)(gbase) + (voff)[_i]), (PG8_LAS unsigned*)(lds + (bufoff) + ldsw + _i * 8192), 16, 0, 0); } while (0)
; #define PG8_LDA(dst, b, h) do { _Pragma("unroll") for (int m = 0; m < 4; ++m) _Pragma("unroll") for (int k = 0; k < 2; ++k) dst[m][k] = *(const PG8_LAS bf16x8*)(lds + PG8_SA(b, h) + aoff + m * 2048 + k * 1024); } while (0)
; #define PG8_MMA(ai, bj, At, Bt) do { __builtin_amdgcn_s_setprio(1); _Pragma("unroll") for (int m = 0; m < 4; ++m) _Pragma("unroll") for (int n = 0; n < 2; ++n) _Pragma("unroll") for (int k = 0; k < 2; ++k) \
;         acc[ai][bj][m][n] = __builtin_amdgcn_mfma_f32_16x16x32_bf16(Bt[n][k], At[m][k], acc[ai][bj][m][n], 0, 0, 0); __builtin_amdgcn_s_setprio(0); } while (0)
; #define PG8_WAIT_V(n) asm volatile("s_waitcnt vmcnt(" #n ")" ::: "memory")
; #define PG8_WAIT_L(n) asm volatile("s_waitcnt lgkmcnt(" #n ")" ::: "memory")
; #define PG8_BAR __builtin_amdgcn_s_barrier()
; #define PG8_SCHED __builtin_amdgcn_sched_barrier(0)
; template <class Epi, class Sched, bool ALIGN_EPI = false, bool SP2 = false>
; __device__ __forceinline__ void gemm_phase(PG8_LAS unsigned char* lds, const Gemm g, const Sched& S, const Epi& E) {
;     ...
;             PG8_LDA(At, 1, 1); PG8_STAGE(PG8_SB(1, 0), b3, voffB); PG8_STAGE(PG8_SB(1, 1), b3 + hstep, voffB); PG8_STAGE(PG8_SA(1, 0), a3, voffA);
;             PG8_WAIT_V(8); PG8_WAIT_L(0); PG8_BAR; PG8_MMA(1, 0, At, B0); PG8_MMA(1, 1, At, B1); PG8_BAR; PG8_SCHED;
;     ...
;         if constexpr (ALIGN_EPI) { if (wr == 0) PG8_BAR; }
	s_add_i32 s46, s74, s33
	v_lshl_add_u64 v[148:149], v[148:149], 0, s[12:13]
	s_mov_b32 m0, s46
	ds_read_b128 v[190:193], v156 offset:49152
	ds_read_b128 v[194:197], v156 offset:50176
	ds_read_b128 v[198:201], v156 offset:51200
	ds_read_b128 v[202:205], v156 offset:52224
	ds_read_b128 v[206:209], v156 offset:53248
	ds_read_b128 v[210:213], v156 offset:54272
	ds_read_b128 v[214:217], v156 offset:55296
	ds_read_b128 v[218:221], v156 offset:56320
	global_load_lds_dwordx4 v[148:149], off
	s_add_i32 m0, s46, 0x2000
	s_add_u32 s44, s44, 0xb0080
	v_lshl_add_u64 v[148:149], v[222:223], 0, s[12:13]
	s_addc_u32 s45, s45, 0
	s_add_i32 s46, s75, s33
	global_load_lds_dwordx4 v[148:149], off
	v_lshl_add_u64 v[148:149], s[44:45], 0, v[130:131]
	s_mov_b32 m0, s46
	s_nop 0
	global_load_lds_dwordx4 v[148:149], off
	v_lshl_add_u64 v[148:149], s[44:45], 0, v[134:135]
	s_add_i32 m0, s46, 0x2000
	s_nop 0
	global_load_lds_dwordx4 v[148:149], off
	s_waitcnt vmcnt(6)
	s_waitcnt lgkmcnt(0)
	s_setprio 1
	s_barrier
	v_mfma_f32_16x16x32_bf16 v[56:59], v[144:147], v[190:193], v[56:59]
	v_mfma_f32_16x16x32_bf16 v[60:63], v[166:169], v[190:193], v[60:63]
	v_mfma_f32_16x16x32_bf16 v[40:43], v[144:147], v[198:201], v[40:43]
	v_mfma_f32_16x16x32_bf16 v[44:47], v[166:169], v[198:201], v[44:47]
	v_mfma_f32_16x16x32_bf16 v[24:27], v[144:147], v[206:209], v[24:27]
	v_mfma_f32_16x16x32_bf16 v[28:31], v[166:169], v[206:209], v[28:31]
	v_lshl_add_u64 v[148:149], v[224:225], 0, s[12:13]
	s_mov_b32 m0, s53
	s_nop 0
	global_load_lds_dwordx4 v[148:149], off
	v_mfma_f32_16x16x32_bf16 v[8:11], v[144:147], v[214:217], v[8:11]
	v_mfma_f32_16x16x32_bf16 v[12:15], v[166:169], v[214:217], v[12:15]
	v_mfma_f32_16x16x32_bf16 v[56:59], v[162:165], v[194:197], v[56:59]
	v_mfma_f32_16x16x32_bf16 v[60:63], v[170:173], v[194:197], v[60:63]
	v_mfma_f32_16x16x32_bf16 v[40:43], v[162:165], v[202:205], v[40:43]
	v_mfma_f32_16x16x32_bf16 v[44:47], v[170:173], v[202:205], v[44:47]
	v_mfma_f32_16x16x32_bf16 v[24:27], v[162:165], v[210:213], v[24:27]
	v_mfma_f32_16x16x32_bf16 v[28:31], v[170:173], v[210:213], v[28:31]
	v_mfma_f32_16x16x32_bf16 v[8:11], v[162:165], v[218:221], v[8:11]
	v_mfma_f32_16x16x32_bf16 v[12:15], v[170:173], v[218:221], v[12:15]
	s_setprio 0
	s_setprio 1
	v_mfma_f32_16x16x32_bf16 v[52:55], v[174:177], v[190:193], v[52:55]
	v_mfma_f32_16x16x32_bf16 v[48:51], v[182:185], v[190:193], v[48:51]
	v_mfma_f32_16x16x32_bf16 v[36:39], v[174:177], v[198:201], v[36:39]
	v_mfma_f32_16x16x32_bf16 v[32:35], v[182:185], v[198:201], v[32:35]
	v_mfma_f32_16x16x32_bf16 v[20:23], v[174:177], v[206:209], v[20:23]
	v_mfma_f32_16x16x32_bf16 v[16:19], v[182:185], v[206:209], v[16:19]
	v_lshl_add_u64 v[148:149], v[226:227], 0, s[12:13]
	s_mov_b32 m0, s60
	s_nop 0
	global_load_lds_dwordx4 v[148:149], off
	v_mfma_f32_16x16x32_bf16 v[4:7], v[174:177], v[214:217], v[4:7]
	v_mfma_f32_16x16x32_bf16 v[0:3], v[182:185], v[214:217], v[0:3]
	v_mfma_f32_16x16x32_bf16 v[52:55], v[178:181], v[194:197], v[52:55]
	v_mfma_f32_16x16x32_bf16 v[48:51], v[186:189], v[194:197], v[48:51]
	v_mfma_f32_16x16x32_bf16 v[36:39], v[178:181], v[202:205], v[36:39]
	v_mfma_f32_16x16x32_bf16 v[32:35], v[186:189], v[202:205], v[32:35]
	v_mfma_f32_16x16x32_bf16 v[20:23], v[178:181], v[210:213], v[20:23]
	v_mfma_f32_16x16x32_bf16 v[16:19], v[186:189], v[210:213], v[16:19]
	v_mfma_f32_16x16x32_bf16 v[4:7], v[178:181], v[218:221], v[4:7]
	v_mfma_f32_16x16x32_bf16 v[0:3], v[186:189], v[218:221], v[0:3]
	s_setprio 0
	s_barrier
	s_add_i32 s73, s73, 2
	s_add_u32 s4, s4, 0x100
	s_addc_u32 s5, s5, 0
	s_add_u32 s43, s43, 0x100
	s_addc_u32 s72, s72, 0
	s_cmp_gt_u32 s73, 41
	s_cbranch_scc0 .LBB0_970
	s_and_b64 vcc, exec, s[14:15]
	s_cbranch_vccz .LBB0_973
	s_barrier
